# non-temporal stores for GEMM/attention outputs whose consumer is a compute-bound phase (P4, P7, P8, P9 outputs)
# baseline (speedup 1.0000x reference)
; __device__ __forceinline__ float bf_lo(unsigned w) { return __uint_as_float(w << 16); }
; __device__ __forceinline__ float bf_hi(unsigned w) { return __uint_as_float(w & 0xffff0000u); }
; __device__ __forceinline__ u32x4 pack8(f32x4 v0, f32x4 v1) { u32x4 w; w.x = cvt_pk_bf16(v0[0], v0[1]); w.y = cvt_pk_bf16(v0[2], v0[3]); w.z = cvt_pk_bf16(v1[0], v1[1]); w.w = cvt_pk_bf16(v1[2], v1[3]); return w; }
;     __device__ __forceinline__ void operator()(const f32x4 (&acc)[2][2][4][2], const Unit& u, int wr, int wc, int fr, int fq) const {
;         const int row0 = u.pm * BM + wr * 64 + fr, col0 = u.pn * BM + wc * 32 + 8 * fq;
;         f32x4 bv[2][2], sv[2][2];
; #pragma unroll
;         for (int bj = 0; bj < 2; ++bj)
; #pragma unroll
;             for (int n = 0; n < 2; ++n) { bv[bj][n] = *(const f32x4*)(bias + col0 + bj * HALF + 4 * n); sv[bj][n] = *(const f32x4*)(scale + col0 + bj * HALF + 4 * n); }
; #pragma unroll
;         for (int ai = 0; ai < 2; ++ai)
; #pragma unroll
;             for (int m = 0; m < 4; ++m) { const size_t off = (size_t)(row0 + ai * HALF + m * 16) * DM + col0;
; #pragma unroll
;                 for (int bj = 0; bj < 2; ++bj) { const u32x4 gw = *(const u32x4*)(SG + off + bj * HALF);
;                     f32x4 v0 = (acc[ai][bj][m][0] + bv[bj][0]) * sv[bj][0], v1 = (acc[ai][bj][m][1] + bv[bj][1]) * sv[bj][1];
;                     v0 = v0 * (f32x4){bf_lo(gw.x), bf_hi(gw.x), bf_lo(gw.y), bf_hi(gw.y)}; v1 = v1 * (f32x4){bf_lo(gw.z), bf_hi(gw.z), bf_lo(gw.w), bf_hi(gw.w)};
;                     *(u32x4*)(Z + off + bj * HALF) = pack8(v0, v1); } }
;     }
.LBB0_577:
	v_lshl_or_b32 v178, s50, 8, v184
	v_readlane_b32 s68, v247, 0
	v_ashrrev_i32_e32 v179, 31, v178
	v_readlane_b32 s69, v247, 1
	v_readlane_b32 s70, v247, 2
	v_readlane_b32 s71, v247, 3
	v_readlane_b32 s72, v247, 4
	v_readlane_b32 s73, v247, 5
	v_lshlrev_b64 v[88:89], 2, v[178:179]
	v_readlane_b32 s74, v247, 6
	v_readlane_b32 s75, v247, 7
	s_mov_b64 s[68:69], s[72:73]
	v_lshl_add_u32 v180, s30, 8, v182
	s_mov_b64 s[70:71], s[74:75]
	v_lshl_add_u64 v[90:91], s[68:69], 0, v[88:89]
	v_ashrrev_i32_e32 v181, 31, v180
	v_lshl_add_u64 v[96:97], s[70:71], 0, v[88:89]
	global_load_dwordx4 v[124:127], v[90:91], off offset:16
	global_load_dwordx4 v[132:135], v[90:91], off
	global_load_dwordx4 v[120:123], v[96:97], off offset:16
	global_load_dwordx4 v[128:131], v[96:97], off
	v_lshlrev_b64 v[88:89], 11, v[180:181]
	v_lshl_add_u64 v[88:89], v[88:89], 0, v[178:179]
	v_lshlrev_b64 v[176:177], 1, v[88:89]
	v_lshl_add_u64 v[192:193], s[14:15], 0, v[176:177]
	global_load_dwordx4 v[92:95], v[90:91], off offset:528
	global_load_dwordx4 v[100:103], v[90:91], off offset:512
	s_nop 0
	global_load_dwordx4 v[88:91], v[96:97], off offset:528
	s_nop 0
	global_load_dwordx4 v[96:99], v[96:97], off offset:512
	v_add_u32_e32 v199, 0x20000, v176
	global_load_dwordx4 v[200:203], v199, s[14:15] offset:256 nt
	v_add_u32_e32 v199, 0x30000, v176
	global_load_dwordx4 v[204:207], v199, s[14:15] nt
	v_add_u32_e32 v199, 0x30000, v176
	global_load_dwordx4 v[208:211], v199, s[14:15] offset:256 nt
	v_add_u32_e32 v199, 0x80000, v176
	global_load_dwordx4 v[212:215], v199, s[14:15] nt
	v_add_u32_e32 v199, 0x80000, v176
	global_load_dwordx4 v[216:219], v199, s[14:15] offset:256 nt
	s_mov_b64 s[4:5], 0x80000
	v_readlane_b32 s76, v247, 8
	v_readlane_b32 s77, v247, 9
	v_readlane_b32 s78, v247, 10
	v_readlane_b32 s79, v247, 11
	v_readlane_b32 s80, v247, 12
	v_readlane_b32 s81, v247, 13
	v_readlane_b32 s82, v247, 14
	v_readlane_b32 s83, v247, 15
	v_readlane_b32 s68, v247, 34
	s_and_b64 vcc, exec, s[0:1]
	s_mov_b64 s[0:1], -1
	v_readlane_b32 s69, v247, 35
	v_readlane_b32 s70, v247, 36
	v_readlane_b32 s71, v247, 37
	v_readlane_b32 s72, v247, 38
	v_readlane_b32 s73, v247, 39
	v_readlane_b32 s74, v247, 40
	v_readlane_b32 s75, v247, 41
	v_readlane_b32 s76, v247, 42
	v_readlane_b32 s77, v247, 43
	v_readlane_b32 s78, v247, 44
	v_readlane_b32 s79, v247, 45
	v_readlane_b32 s80, v247, 46
	v_readlane_b32 s81, v247, 47
	v_readlane_b32 s82, v247, 48
	v_readlane_b32 s83, v247, 49
	s_waitcnt vmcnt(5)
	v_pk_add_f32 v[154:155], v[154:155], v[126:127]
	v_pk_add_f32 v[158:159], v[158:159], v[134:135]
	v_pk_add_f32 v[156:157], v[156:157], v[132:133]
	v_pk_add_f32 v[152:153], v[152:153], v[124:125]
	v_pk_mul_f32 v[158:159], v[130:131], v[158:159]
	v_pk_mul_f32 v[156:157], v[128:129], v[156:157]
	v_pk_mul_f32 v[154:155], v[122:123], v[154:155]
	v_pk_mul_f32 v[152:153], v[120:121], v[152:153]
	v_lshlrev_b32_e32 v194, 16, v226
	v_and_b32_e32 v195, 0xffff0000, v226
	v_lshlrev_b32_e32 v188, 16, v227
	v_and_b32_e32 v189, 0xffff0000, v227
	v_lshlrev_b32_e32 v196, 16, v228
	v_and_b32_e32 v197, 0xffff0000, v228
	v_lshlrev_b32_e32 v190, 16, v229
	v_and_b32_e32 v191, 0xffff0000, v229
	v_pk_mul_f32 v[158:159], v[158:159], v[188:189]
	v_pk_mul_f32 v[156:157], v[156:157], v[194:195]
	v_pk_mul_f32 v[188:189], v[154:155], v[190:191]
	v_pk_mul_f32 v[154:155], v[152:153], v[196:197]
	v_cvt_pk_bf16_f32 v152, v156, v157
	v_cvt_pk_bf16_f32 v153, v158, v159
	v_lshl_add_u64 v[190:191], s[18:19], 0, v[176:177]
	v_cvt_pk_bf16_f32 v154, v154, v155
	v_cvt_pk_bf16_f32 v155, v188, v189
	v_add_u32_e32 v199, 0x90000, v176
	global_load_dwordx4 v[226:229], v199, s[14:15] nt
	v_or_b32_e32 v188, 16, v180
	v_ashrrev_i32_e32 v189, 31, v188
	v_lshlrev_b64 v[188:189], 11, v[188:189]
	v_pk_add_f32 v[148:149], v[148:149], v[100:101]
	v_pk_add_f32 v[142:143], v[142:143], v[94:95]
	v_pk_add_f32 v[140:141], v[140:141], v[92:93]
	v_lshl_add_u64 v[188:189], v[188:189], 0, v[178:179]
	v_pk_add_f32 v[150:151], v[150:151], v[102:103]
	v_pk_mul_f32 v[148:149], v[96:97], v[148:149]
	v_pk_mul_f32 v[142:143], v[90:91], v[142:143]
	v_pk_mul_f32 v[140:141], v[88:89], v[140:141]
	global_store_dwordx4 v[190:191], v[152:155], off nt
	v_lshlrev_b64 v[188:189], 1, v[188:189]
	v_pk_mul_f32 v[150:151], v[98:99], v[150:151]
	v_lshl_add_u64 v[192:193], s[14:15], 0, v[188:189]
	v_pk_add_f32 v[146:147], v[146:147], v[134:135]
	v_pk_add_f32 v[138:139], v[138:139], v[126:127]
	v_pk_add_f32 v[136:137], v[136:137], v[124:125]
	v_pk_add_f32 v[144:145], v[144:145], v[132:133]
	v_pk_mul_f32 v[146:147], v[130:131], v[146:147]
	v_pk_mul_f32 v[138:139], v[122:123], v[138:139]
	v_pk_mul_f32 v[136:137], v[120:121], v[136:137]
	v_pk_mul_f32 v[144:145], v[128:129], v[144:145]
	v_pk_add_f32 v[116:117], v[116:117], v[100:101]
	v_pk_add_f32 v[110:111], v[110:111], v[94:95]
	v_pk_add_f32 v[108:109], v[108:109], v[92:93]
	v_pk_add_f32 v[118:119], v[118:119], v[102:103]
	v_pk_mul_f32 v[116:117], v[96:97], v[116:117]
	v_pk_mul_f32 v[110:111], v[90:91], v[110:111]
	v_pk_mul_f32 v[108:109], v[88:89], v[108:109]
	v_pk_mul_f32 v[118:119], v[98:99], v[118:119]
	v_pk_add_f32 v[114:115], v[114:115], v[134:135]
	v_pk_add_f32 v[106:107], v[106:107], v[126:127]
	v_pk_add_f32 v[104:105], v[104:105], v[124:125]
	v_pk_add_f32 v[112:113], v[112:113], v[132:133]
	v_pk_mul_f32 v[114:115], v[130:131], v[114:115]
	v_pk_mul_f32 v[106:107], v[122:123], v[106:107]
	v_pk_mul_f32 v[104:105], v[120:121], v[104:105]
	v_pk_mul_f32 v[112:113], v[128:129], v[112:113]
	v_pk_add_f32 v[84:85], v[84:85], v[100:101]
	v_pk_add_f32 v[78:79], v[78:79], v[94:95]
	v_pk_add_f32 v[76:77], v[76:77], v[92:93]
; __device__ __forceinline__ float bf_lo(unsigned w) { return __uint_as_float(w << 16); }
; __device__ __forceinline__ float bf_hi(unsigned w) { return __uint_as_float(w & 0xffff0000u); }
; __device__ __forceinline__ u32x4 pack8(f32x4 v0, f32x4 v1) { u32x4 w; w.x = cvt_pk_bf16(v0[0], v0[1]); w.y = cvt_pk_bf16(v0[2], v0[3]); w.z = cvt_pk_bf16(v1[0], v1[1]); w.w = cvt_pk_bf16(v1[2], v1[3]); return w; }
;     __device__ __forceinline__ void operator()(const f32x4 (&acc)[2][2][4][2], const Unit& u, int wr, int wc, int fr, int fq) const {
;         const int row0 = u.pm * BM + wr * 64 + fr, col0 = u.pn * BM + wc * 32 + 8 * fq;
;         f32x4 bv[2][2], sv[2][2];
; #pragma unroll
;         for (int bj = 0; bj < 2; ++bj)
; #pragma unroll
;             for (int n = 0; n < 2; ++n) { bv[bj][n] = *(const f32x4*)(bias + col0 + bj * HALF + 4 * n); sv[bj][n] = *(const f32x4*)(scale + col0 + bj * HALF + 4 * n); }
; #pragma unroll
;         for (int ai = 0; ai < 2; ++ai)
; #pragma unroll
;             for (int m = 0; m < 4; ++m) { const size_t off = (size_t)(row0 + ai * HALF + m * 16) * DM + col0;
; #pragma unroll
;                 for (int bj = 0; bj < 2; ++bj) { const u32x4 gw = *(const u32x4*)(SG + off + bj * HALF);
;                     f32x4 v0 = (acc[ai][bj][m][0] + bv[bj][0]) * sv[bj][0], v1 = (acc[ai][bj][m][1] + bv[bj][1]) * sv[bj][1];
;                     v0 = v0 * (f32x4){bf_lo(gw.x), bf_hi(gw.x), bf_lo(gw.y), bf_hi(gw.y)}; v1 = v1 * (f32x4){bf_lo(gw.z), bf_hi(gw.z), bf_lo(gw.w), bf_hi(gw.w)};
;                     *(u32x4*)(Z + off + bj * HALF) = pack8(v0, v1); } }
;     }
	v_pk_add_f32 v[86:87], v[86:87], v[102:103]
	v_pk_mul_f32 v[84:85], v[96:97], v[84:85]
	v_pk_mul_f32 v[78:79], v[90:91], v[78:79]
	v_pk_mul_f32 v[76:77], v[88:89], v[76:77]
	v_pk_mul_f32 v[86:87], v[98:99], v[86:87]
	v_pk_add_f32 v[82:83], v[82:83], v[134:135]
	v_pk_add_f32 v[74:75], v[74:75], v[126:127]
	v_pk_add_f32 v[72:73], v[72:73], v[124:125]
	v_pk_add_f32 v[80:81], v[80:81], v[132:133]
	v_pk_mul_f32 v[82:83], v[130:131], v[82:83]
	v_pk_mul_f32 v[74:75], v[122:123], v[74:75]
	v_pk_mul_f32 v[72:73], v[120:121], v[72:73]
	v_pk_mul_f32 v[80:81], v[128:129], v[80:81]
	v_pk_add_f32 v[68:69], v[68:69], v[100:101]
	v_pk_add_f32 v[66:67], v[66:67], v[94:95]
	v_pk_add_f32 v[64:65], v[64:65], v[92:93]
	v_pk_add_f32 v[70:71], v[70:71], v[102:103]
	v_pk_mul_f32 v[68:69], v[96:97], v[68:69]
	v_pk_mul_f32 v[66:67], v[90:91], v[66:67]
	v_pk_mul_f32 v[64:65], v[88:89], v[64:65]
	v_pk_mul_f32 v[70:71], v[98:99], v[70:71]
	v_pk_add_f32 v[62:63], v[62:63], v[134:135]
	v_pk_add_f32 v[60:61], v[60:61], v[132:133]
	v_pk_add_f32 v[58:59], v[58:59], v[126:127]
	v_pk_add_f32 v[56:57], v[56:57], v[124:125]
	v_pk_mul_f32 v[62:63], v[130:131], v[62:63]
	v_pk_mul_f32 v[60:61], v[128:129], v[60:61]
	v_pk_mul_f32 v[58:59], v[122:123], v[58:59]
	v_pk_mul_f32 v[56:57], v[120:121], v[56:57]
	v_pk_add_f32 v[52:53], v[52:53], v[100:101]
	v_pk_add_f32 v[46:47], v[46:47], v[94:95]
	v_pk_add_f32 v[44:45], v[44:45], v[92:93]
	v_pk_add_f32 v[54:55], v[54:55], v[102:103]
	v_pk_mul_f32 v[52:53], v[96:97], v[52:53]
	v_pk_mul_f32 v[46:47], v[90:91], v[46:47]
	v_pk_mul_f32 v[44:45], v[88:89], v[44:45]
	v_pk_mul_f32 v[54:55], v[98:99], v[54:55]
	v_lshlrev_b32_e32 v152, 16, v230
	v_and_b32_e32 v153, 0xffff0000, v230
	v_lshlrev_b32_e32 v154, 16, v231
	v_and_b32_e32 v155, 0xffff0000, v231
	v_lshlrev_b32_e32 v156, 16, v232
	v_and_b32_e32 v157, 0xffff0000, v232
	v_lshlrev_b32_e32 v158, 16, v233
	v_and_b32_e32 v159, 0xffff0000, v233
	v_pk_mul_f32 v[148:149], v[148:149], v[152:153]
	v_pk_mul_f32 v[152:153], v[142:143], v[158:159]
	v_pk_mul_f32 v[142:143], v[140:141], v[156:157]
	v_pk_mul_f32 v[150:151], v[150:151], v[154:155]
	v_cvt_pk_bf16_f32 v140, v148, v149
	v_pk_add_f32 v[50:51], v[50:51], v[134:135]
	v_cvt_pk_bf16_f32 v141, v150, v151
	v_cvt_pk_bf16_f32 v142, v142, v143
	v_cvt_pk_bf16_f32 v143, v152, v153
	global_store_dwordx4 v[190:191], v[140:143], off offset:256 nt
	v_add_u32_e32 v199, 0x90000, v176
	global_load_dwordx4 v[230:233], v199, s[14:15] offset:256 nt
	v_pk_add_f32 v[42:43], v[42:43], v[126:127]
	v_pk_add_f32 v[40:41], v[40:41], v[124:125]
	v_pk_add_f32 v[48:49], v[48:49], v[132:133]
	v_pk_mul_f32 v[50:51], v[130:131], v[50:51]
	v_pk_mul_f32 v[42:43], v[122:123], v[42:43]
	v_pk_mul_f32 v[40:41], v[120:121], v[40:41]
	v_pk_mul_f32 v[48:49], v[128:129], v[48:49]
	v_pk_add_f32 v[36:37], v[36:37], v[100:101]
	v_pk_add_f32 v[30:31], v[30:31], v[94:95]
	v_pk_add_f32 v[28:29], v[28:29], v[92:93]
	v_pk_add_f32 v[38:39], v[38:39], v[102:103]
	v_pk_mul_f32 v[36:37], v[96:97], v[36:37]
	v_pk_mul_f32 v[30:31], v[90:91], v[30:31]
	v_pk_mul_f32 v[28:29], v[88:89], v[28:29]
	v_pk_mul_f32 v[38:39], v[98:99], v[38:39]
	v_pk_add_f32 v[34:35], v[34:35], v[134:135]
	v_pk_add_f32 v[26:27], v[26:27], v[126:127]
	v_pk_add_f32 v[24:25], v[24:25], v[124:125]
	v_pk_add_f32 v[32:33], v[32:33], v[132:133]
	v_pk_mul_f32 v[34:35], v[130:131], v[34:35]
	v_pk_mul_f32 v[26:27], v[122:123], v[26:27]
	v_pk_mul_f32 v[24:25], v[120:121], v[24:25]
	v_pk_mul_f32 v[32:33], v[128:129], v[32:33]
	v_pk_add_f32 v[20:21], v[20:21], v[100:101]
	v_pk_add_f32 v[14:15], v[14:15], v[94:95]
	v_pk_add_f32 v[12:13], v[12:13], v[92:93]
	v_pk_add_f32 v[22:23], v[22:23], v[102:103]
	v_pk_mul_f32 v[20:21], v[96:97], v[20:21]
	v_pk_mul_f32 v[14:15], v[90:91], v[14:15]
	v_pk_mul_f32 v[12:13], v[88:89], v[12:13]
	v_pk_mul_f32 v[22:23], v[98:99], v[22:23]
	v_pk_add_f32 v[18:19], v[18:19], v[134:135]
	v_pk_add_f32 v[10:11], v[10:11], v[126:127]
	v_pk_add_f32 v[8:9], v[8:9], v[124:125]
	v_pk_add_f32 v[16:17], v[16:17], v[132:133]
	v_pk_mul_f32 v[18:19], v[130:131], v[18:19]
	v_pk_mul_f32 v[10:11], v[122:123], v[10:11]
	v_pk_mul_f32 v[8:9], v[120:121], v[8:9]
	v_pk_mul_f32 v[16:17], v[128:129], v[16:17]
	v_pk_add_f32 v[4:5], v[4:5], v[100:101]
	v_pk_add_f32 v[2:3], v[2:3], v[94:95]
	v_pk_add_f32 v[0:1], v[0:1], v[92:93]
	v_pk_add_f32 v[6:7], v[6:7], v[102:103]
	v_pk_mul_f32 v[4:5], v[96:97], v[4:5]
	v_pk_mul_f32 v[2:3], v[90:91], v[2:3]
	v_pk_mul_f32 v[0:1], v[88:89], v[0:1]
	v_pk_mul_f32 v[6:7], v[98:99], v[6:7]
	v_lshlrev_b32_e32 v148, 16, v234
	v_and_b32_e32 v149, 0xffff0000, v234
	v_lshlrev_b32_e32 v140, 16, v235
	v_and_b32_e32 v141, 0xffff0000, v235
	v_lshlrev_b32_e32 v150, 16, v236
	v_and_b32_e32 v151, 0xffff0000, v236
	v_lshlrev_b32_e32 v142, 16, v237
	v_and_b32_e32 v143, 0xffff0000, v237
	v_pk_mul_f32 v[140:141], v[146:147], v[140:141]
	v_pk_mul_f32 v[142:143], v[138:139], v[142:143]
	v_pk_mul_f32 v[138:139], v[136:137], v[150:151]
	v_pk_mul_f32 v[144:145], v[144:145], v[148:149]
	v_lshl_add_u64 v[146:147], s[18:19], 0, v[188:189]
	v_cvt_pk_bf16_f32 v136, v144, v145
	v_cvt_pk_bf16_f32 v137, v140, v141
	v_cvt_pk_bf16_f32 v138, v138, v139
	v_cvt_pk_bf16_f32 v139, v142, v143
	v_add_u32_e32 v199, 0xa0000, v176
	global_load_dwordx4 v[234:237], v199, s[14:15] nt
	v_or_b32_e32 v144, 32, v180
	v_ashrrev_i32_e32 v145, 31, v144
	v_lshlrev_b64 v[144:145], 11, v[144:145]
	v_lshl_add_u64 v[144:145], v[144:145], 0, v[178:179]
	global_store_dwordx4 v[146:147], v[136:139], off nt
	v_lshlrev_b64 v[144:145], 1, v[144:145]
	v_lshl_add_u64 v[148:149], s[14:15], 0, v[144:145]
	v_lshlrev_b32_e32 v136, 16, v238
	v_and_b32_e32 v137, 0xffff0000, v238
; __device__ __forceinline__ float bf_lo(unsigned w) { return __uint_as_float(w << 16); }
; __device__ __forceinline__ float bf_hi(unsigned w) { return __uint_as_float(w & 0xffff0000u); }
; __device__ __forceinline__ u32x4 pack8(f32x4 v0, f32x4 v1) { u32x4 w; w.x = cvt_pk_bf16(v0[0], v0[1]); w.y = cvt_pk_bf16(v0[2], v0[3]); w.z = cvt_pk_bf16(v1[0], v1[1]); w.w = cvt_pk_bf16(v1[2], v1[3]); return w; }
;     __device__ __forceinline__ void operator()(const f32x4 (&acc)[2][2][4][2], const Unit& u, int wr, int wc, int fr, int fq) const {
;         const int row0 = u.pm * BM + wr * 64 + fr, col0 = u.pn * BM + wc * 32 + 8 * fq;
;         f32x4 bv[2][2], sv[2][2];
; #pragma unroll
;         for (int bj = 0; bj < 2; ++bj)
; #pragma unroll
;             for (int n = 0; n < 2; ++n) { bv[bj][n] = *(const f32x4*)(bias + col0 + bj * HALF + 4 * n); sv[bj][n] = *(const f32x4*)(scale + col0 + bj * HALF + 4 * n); }
; #pragma unroll
;         for (int ai = 0; ai < 2; ++ai)
; #pragma unroll
;             for (int m = 0; m < 4; ++m) { const size_t off = (size_t)(row0 + ai * HALF + m * 16) * DM + col0;
; #pragma unroll
;                 for (int bj = 0; bj < 2; ++bj) { const u32x4 gw = *(const u32x4*)(SG + off + bj * HALF);
;                     f32x4 v0 = (acc[ai][bj][m][0] + bv[bj][0]) * sv[bj][0], v1 = (acc[ai][bj][m][1] + bv[bj][1]) * sv[bj][1];
;                     v0 = v0 * (f32x4){bf_lo(gw.x), bf_hi(gw.x), bf_lo(gw.y), bf_hi(gw.y)}; v1 = v1 * (f32x4){bf_lo(gw.z), bf_hi(gw.z), bf_lo(gw.w), bf_hi(gw.w)};
;                     *(u32x4*)(Z + off + bj * HALF) = pack8(v0, v1); } }
;     }
	v_lshlrev_b32_e32 v138, 16, v239
	v_and_b32_e32 v139, 0xffff0000, v239
	v_lshlrev_b32_e32 v140, 16, v240
	v_and_b32_e32 v141, 0xffff0000, v240
	v_lshlrev_b32_e32 v142, 16, v241
	v_and_b32_e32 v143, 0xffff0000, v241
	v_pk_mul_f32 v[116:117], v[116:117], v[136:137]
	v_pk_mul_f32 v[136:137], v[110:111], v[142:143]
	v_pk_mul_f32 v[110:111], v[108:109], v[140:141]
	v_pk_mul_f32 v[118:119], v[118:119], v[138:139]
	v_cvt_pk_bf16_f32 v108, v116, v117
	s_nop 0
	v_cvt_pk_bf16_f32 v109, v118, v119
	v_cvt_pk_bf16_f32 v110, v110, v111
	v_cvt_pk_bf16_f32 v111, v136, v137
	global_store_dwordx4 v[146:147], v[108:111], off offset:256 nt
	v_add_u32_e32 v199, 0xa0000, v176
	global_load_dwordx4 v[238:241], v199, s[14:15] offset:256 nt
	v_lshlrev_b32_e32 v116, 16, v242
	v_and_b32_e32 v117, 0xffff0000, v242
	v_lshlrev_b32_e32 v108, 16, v243
	v_and_b32_e32 v109, 0xffff0000, v243
	v_lshlrev_b32_e32 v118, 16, v244
	v_and_b32_e32 v119, 0xffff0000, v244
	v_lshlrev_b32_e32 v110, 16, v245
	v_and_b32_e32 v111, 0xffff0000, v245
	v_pk_mul_f32 v[108:109], v[114:115], v[108:109]
	v_pk_mul_f32 v[110:111], v[106:107], v[110:111]
	v_pk_mul_f32 v[106:107], v[104:105], v[118:119]
	v_pk_mul_f32 v[112:113], v[112:113], v[116:117]
	v_lshl_add_u64 v[114:115], s[18:19], 0, v[144:145]
	v_cvt_pk_bf16_f32 v104, v112, v113
	v_cvt_pk_bf16_f32 v105, v108, v109
	v_cvt_pk_bf16_f32 v106, v106, v107
	v_cvt_pk_bf16_f32 v107, v110, v111
	v_add_u32_e32 v199, 0xb0000, v176
	global_load_dwordx4 v[242:245], v199, s[14:15] nt
	v_or_b32_e32 v112, 48, v180
	v_ashrrev_i32_e32 v113, 31, v112
	v_lshlrev_b64 v[112:113], 11, v[112:113]
	v_lshl_add_u64 v[112:113], v[112:113], 0, v[178:179]
	global_store_dwordx4 v[114:115], v[104:107], off nt
	v_lshlrev_b64 v[112:113], 1, v[112:113]
	v_lshl_add_u64 v[116:117], s[14:15], 0, v[112:113]
	s_waitcnt vmcnt(14)
	v_lshlrev_b32_e32 v104, 16, v200
	v_and_b32_e32 v105, 0xffff0000, v200
	v_lshlrev_b32_e32 v106, 16, v201
	v_and_b32_e32 v107, 0xffff0000, v201
	v_lshlrev_b32_e32 v108, 16, v202
	v_and_b32_e32 v109, 0xffff0000, v202
	v_lshlrev_b32_e32 v110, 16, v203
	v_and_b32_e32 v111, 0xffff0000, v203
	v_pk_mul_f32 v[84:85], v[84:85], v[104:105]
	v_pk_mul_f32 v[104:105], v[78:79], v[110:111]
	v_pk_mul_f32 v[78:79], v[76:77], v[108:109]
	v_pk_mul_f32 v[86:87], v[86:87], v[106:107]
	v_cvt_pk_bf16_f32 v76, v84, v85
	s_nop 0
	v_cvt_pk_bf16_f32 v77, v86, v87
	v_cvt_pk_bf16_f32 v78, v78, v79
	v_cvt_pk_bf16_f32 v79, v104, v105
	global_store_dwordx4 v[114:115], v[76:79], off offset:256 nt
	v_add_u32_e32 v199, 0xb0000, v176
	global_load_dwordx4 v[200:203], v199, s[14:15] offset:256 nt
	s_waitcnt vmcnt(15)
	v_lshlrev_b32_e32 v84, 16, v204
	v_and_b32_e32 v85, 0xffff0000, v204
	v_lshlrev_b32_e32 v76, 16, v205
	v_and_b32_e32 v77, 0xffff0000, v205
	v_lshlrev_b32_e32 v86, 16, v206
	v_and_b32_e32 v87, 0xffff0000, v206
	v_lshlrev_b32_e32 v78, 16, v207
	v_and_b32_e32 v79, 0xffff0000, v207
	v_pk_mul_f32 v[76:77], v[82:83], v[76:77]
	v_pk_mul_f32 v[78:79], v[74:75], v[78:79]
	v_pk_mul_f32 v[74:75], v[72:73], v[86:87]
	v_pk_mul_f32 v[80:81], v[80:81], v[84:85]
	v_lshl_add_u64 v[82:83], s[18:19], 0, v[112:113]
	v_cvt_pk_bf16_f32 v72, v80, v81
	v_cvt_pk_bf16_f32 v73, v76, v77
	v_cvt_pk_bf16_f32 v74, v74, v75
	v_cvt_pk_bf16_f32 v75, v78, v79
	v_lshl_add_u64 v[80:81], v[176:177], 0, s[4:5]
	global_store_dwordx4 v[82:83], v[72:75], off nt
	v_lshl_add_u64 v[84:85], s[14:15], 0, v[80:81]
	s_mov_b64 s[4:5], 0x90000
	s_waitcnt vmcnt(15)
	v_lshlrev_b32_e32 v72, 16, v208
	v_and_b32_e32 v73, 0xffff0000, v208
	v_lshlrev_b32_e32 v74, 16, v209
	v_and_b32_e32 v75, 0xffff0000, v209
	v_lshlrev_b32_e32 v76, 16, v210
	v_and_b32_e32 v77, 0xffff0000, v210
	v_lshlrev_b32_e32 v78, 16, v211
	v_and_b32_e32 v79, 0xffff0000, v211
	v_pk_mul_f32 v[68:69], v[68:69], v[72:73]
	v_pk_mul_f32 v[72:73], v[66:67], v[78:79]
	v_pk_mul_f32 v[66:67], v[64:65], v[76:77]
	v_pk_mul_f32 v[70:71], v[70:71], v[74:75]
	v_cvt_pk_bf16_f32 v64, v68, v69
	s_nop 0
	v_cvt_pk_bf16_f32 v65, v70, v71
	v_cvt_pk_bf16_f32 v66, v66, v67
	v_cvt_pk_bf16_f32 v67, v72, v73
	global_store_dwordx4 v[82:83], v[64:67], off offset:256 nt
	s_waitcnt vmcnt(15)
	v_lshlrev_b32_e32 v68, 16, v212
	v_and_b32_e32 v69, 0xffff0000, v212
	v_lshlrev_b32_e32 v64, 16, v213
	v_and_b32_e32 v65, 0xffff0000, v213
	v_lshlrev_b32_e32 v70, 16, v214
	v_and_b32_e32 v71, 0xffff0000, v214
	v_lshlrev_b32_e32 v66, 16, v215
	v_and_b32_e32 v67, 0xffff0000, v215
	v_pk_mul_f32 v[62:63], v[62:63], v[64:65]
	v_pk_mul_f32 v[60:61], v[60:61], v[68:69]
	v_pk_mul_f32 v[64:65], v[58:59], v[66:67]
	v_pk_mul_f32 v[58:59], v[56:57], v[70:71]
	v_cvt_pk_bf16_f32 v56, v60, v61
	v_cvt_pk_bf16_f32 v57, v62, v63
	v_lshl_add_u64 v[66:67], s[18:19], 0, v[80:81]
	v_cvt_pk_bf16_f32 v58, v58, v59
	v_cvt_pk_bf16_f32 v59, v64, v65
	v_lshl_add_u64 v[64:65], v[176:177], 0, s[4:5]
	global_store_dwordx4 v[66:67], v[56:59], off nt
	v_lshl_add_u64 v[68:69], s[14:15], 0, v[64:65]
	s_mov_b64 s[4:5], 0xa0000
	s_waitcnt vmcnt(15)
; __device__ __forceinline__ float bf_lo(unsigned w) { return __uint_as_float(w << 16); }
; __device__ __forceinline__ float bf_hi(unsigned w) { return __uint_as_float(w & 0xffff0000u); }
; __device__ __forceinline__ u32x4 pack8(f32x4 v0, f32x4 v1) { u32x4 w; w.x = cvt_pk_bf16(v0[0], v0[1]); w.y = cvt_pk_bf16(v0[2], v0[3]); w.z = cvt_pk_bf16(v1[0], v1[1]); w.w = cvt_pk_bf16(v1[2], v1[3]); return w; }
;     __device__ __forceinline__ void operator()(const f32x4 (&acc)[2][2][4][2], const Unit& u, int wr, int wc, int fr, int fq) const {
;         const int row0 = u.pm * BM + wr * 64 + fr, col0 = u.pn * BM + wc * 32 + 8 * fq;
;         f32x4 bv[2][2], sv[2][2];
; #pragma unroll
;         for (int bj = 0; bj < 2; ++bj)
; #pragma unroll
;             for (int n = 0; n < 2; ++n) { bv[bj][n] = *(const f32x4*)(bias + col0 + bj * HALF + 4 * n); sv[bj][n] = *(const f32x4*)(scale + col0 + bj * HALF + 4 * n); }
; #pragma unroll
;         for (int ai = 0; ai < 2; ++ai)
; #pragma unroll
;             for (int m = 0; m < 4; ++m) { const size_t off = (size_t)(row0 + ai * HALF + m * 16) * DM + col0;
; #pragma unroll
;                 for (int bj = 0; bj < 2; ++bj) { const u32x4 gw = *(const u32x4*)(SG + off + bj * HALF);
;                     f32x4 v0 = (acc[ai][bj][m][0] + bv[bj][0]) * sv[bj][0], v1 = (acc[ai][bj][m][1] + bv[bj][1]) * sv[bj][1];
;                     v0 = v0 * (f32x4){bf_lo(gw.x), bf_hi(gw.x), bf_lo(gw.y), bf_hi(gw.y)}; v1 = v1 * (f32x4){bf_lo(gw.z), bf_hi(gw.z), bf_lo(gw.w), bf_hi(gw.w)};
;                     *(u32x4*)(Z + off + bj * HALF) = pack8(v0, v1); } }
;     }
	v_lshlrev_b32_e32 v56, 16, v216
	v_and_b32_e32 v57, 0xffff0000, v216
	v_lshlrev_b32_e32 v58, 16, v217
	v_and_b32_e32 v59, 0xffff0000, v217
	v_lshlrev_b32_e32 v60, 16, v218
	v_and_b32_e32 v61, 0xffff0000, v218
	v_lshlrev_b32_e32 v62, 16, v219
	v_and_b32_e32 v63, 0xffff0000, v219
	v_pk_mul_f32 v[52:53], v[52:53], v[56:57]
	v_pk_mul_f32 v[56:57], v[46:47], v[62:63]
	v_pk_mul_f32 v[46:47], v[44:45], v[60:61]
	v_pk_mul_f32 v[54:55], v[54:55], v[58:59]
	v_cvt_pk_bf16_f32 v44, v52, v53
	s_nop 0
	v_cvt_pk_bf16_f32 v45, v54, v55
	v_cvt_pk_bf16_f32 v46, v46, v47
	v_cvt_pk_bf16_f32 v47, v56, v57
	global_store_dwordx4 v[66:67], v[44:47], off offset:256 nt
	s_waitcnt vmcnt(15)
	v_lshlrev_b32_e32 v52, 16, v226
	v_and_b32_e32 v53, 0xffff0000, v226
	v_lshlrev_b32_e32 v44, 16, v227
	v_and_b32_e32 v45, 0xffff0000, v227
	v_lshlrev_b32_e32 v54, 16, v228
	v_and_b32_e32 v55, 0xffff0000, v228
	v_lshlrev_b32_e32 v46, 16, v229
	v_and_b32_e32 v47, 0xffff0000, v229
	v_pk_mul_f32 v[44:45], v[50:51], v[44:45]
	v_pk_mul_f32 v[46:47], v[42:43], v[46:47]
	v_pk_mul_f32 v[42:43], v[40:41], v[54:55]
	v_pk_mul_f32 v[48:49], v[48:49], v[52:53]
	v_lshl_add_u64 v[50:51], s[18:19], 0, v[64:65]
	v_cvt_pk_bf16_f32 v40, v48, v49
	v_cvt_pk_bf16_f32 v41, v44, v45
	v_cvt_pk_bf16_f32 v42, v42, v43
	v_cvt_pk_bf16_f32 v43, v46, v47
	v_lshl_add_u64 v[48:49], v[176:177], 0, s[4:5]
	global_store_dwordx4 v[50:51], v[40:43], off nt
	v_lshl_add_u64 v[52:53], s[14:15], 0, v[48:49]
	s_mov_b64 s[4:5], 0xb0000
	s_waitcnt vmcnt(13)
	v_lshlrev_b32_e32 v40, 16, v230
	v_and_b32_e32 v41, 0xffff0000, v230
	v_lshlrev_b32_e32 v42, 16, v231
	v_and_b32_e32 v43, 0xffff0000, v231
	v_lshlrev_b32_e32 v44, 16, v232
	v_and_b32_e32 v45, 0xffff0000, v232
	v_lshlrev_b32_e32 v46, 16, v233
	v_and_b32_e32 v47, 0xffff0000, v233
	v_pk_mul_f32 v[36:37], v[36:37], v[40:41]
	v_pk_mul_f32 v[40:41], v[30:31], v[46:47]
	v_pk_mul_f32 v[30:31], v[28:29], v[44:45]
	v_pk_mul_f32 v[38:39], v[38:39], v[42:43]
	v_cvt_pk_bf16_f32 v28, v36, v37
	s_nop 0
	v_cvt_pk_bf16_f32 v29, v38, v39
	v_cvt_pk_bf16_f32 v30, v30, v31
	v_cvt_pk_bf16_f32 v31, v40, v41
	global_store_dwordx4 v[50:51], v[28:31], off offset:256 nt
	s_waitcnt vmcnt(13)
	v_lshlrev_b32_e32 v36, 16, v234
	v_and_b32_e32 v37, 0xffff0000, v234
	v_lshlrev_b32_e32 v28, 16, v235
	v_and_b32_e32 v29, 0xffff0000, v235
	v_lshlrev_b32_e32 v38, 16, v236
	v_and_b32_e32 v39, 0xffff0000, v236
	v_lshlrev_b32_e32 v30, 16, v237
	v_and_b32_e32 v31, 0xffff0000, v237
	v_pk_mul_f32 v[28:29], v[34:35], v[28:29]
	v_pk_mul_f32 v[30:31], v[26:27], v[30:31]
	v_pk_mul_f32 v[26:27], v[24:25], v[38:39]
	v_pk_mul_f32 v[32:33], v[32:33], v[36:37]
	v_lshl_add_u64 v[34:35], s[18:19], 0, v[48:49]
	v_cvt_pk_bf16_f32 v24, v32, v33
	v_cvt_pk_bf16_f32 v25, v28, v29
	v_cvt_pk_bf16_f32 v26, v26, v27
	v_cvt_pk_bf16_f32 v27, v30, v31
	v_lshl_add_u64 v[32:33], v[176:177], 0, s[4:5]
	global_store_dwordx4 v[34:35], v[24:27], off nt
	v_lshl_add_u64 v[36:37], s[14:15], 0, v[32:33]
	s_waitcnt vmcnt(11)
	v_lshlrev_b32_e32 v24, 16, v238
	v_and_b32_e32 v25, 0xffff0000, v238
	v_lshlrev_b32_e32 v26, 16, v239
	v_and_b32_e32 v27, 0xffff0000, v239
	v_lshlrev_b32_e32 v28, 16, v240
	v_and_b32_e32 v29, 0xffff0000, v240
	v_lshlrev_b32_e32 v30, 16, v241
	v_and_b32_e32 v31, 0xffff0000, v241
	v_pk_mul_f32 v[20:21], v[20:21], v[24:25]
	v_pk_mul_f32 v[24:25], v[14:15], v[30:31]
	v_pk_mul_f32 v[14:15], v[12:13], v[28:29]
	v_pk_mul_f32 v[22:23], v[22:23], v[26:27]
	v_cvt_pk_bf16_f32 v12, v20, v21
	s_nop 0
	v_cvt_pk_bf16_f32 v13, v22, v23
	v_cvt_pk_bf16_f32 v14, v14, v15
	v_cvt_pk_bf16_f32 v15, v24, v25
	global_store_dwordx4 v[34:35], v[12:15], off offset:256 nt
	s_waitcnt vmcnt(11)
	v_lshlrev_b32_e32 v20, 16, v242
	v_and_b32_e32 v21, 0xffff0000, v242
	v_lshlrev_b32_e32 v12, 16, v243
	v_and_b32_e32 v13, 0xffff0000, v243
	v_lshlrev_b32_e32 v22, 16, v244
	v_and_b32_e32 v23, 0xffff0000, v244
	v_lshlrev_b32_e32 v14, 16, v245
	v_and_b32_e32 v15, 0xffff0000, v245
	v_pk_mul_f32 v[12:13], v[18:19], v[12:13]
	v_pk_mul_f32 v[14:15], v[10:11], v[14:15]
	v_pk_mul_f32 v[10:11], v[8:9], v[22:23]
	v_pk_mul_f32 v[16:17], v[16:17], v[20:21]
	s_nop 0
	v_cvt_pk_bf16_f32 v8, v16, v17
	v_cvt_pk_bf16_f32 v9, v12, v13
	v_cvt_pk_bf16_f32 v10, v10, v11
	v_cvt_pk_bf16_f32 v11, v14, v15
	v_lshl_add_u64 v[16:17], s[18:19], 0, v[32:33]
	global_store_dwordx4 v[16:17], v[8:11], off nt
	s_waitcnt vmcnt(9)
	s_nop 0
	v_lshlrev_b32_e32 v8, 16, v200
	v_and_b32_e32 v9, 0xffff0000, v200
	v_lshlrev_b32_e32 v10, 16, v201
	v_and_b32_e32 v11, 0xffff0000, v201
	v_lshlrev_b32_e32 v12, 16, v202
	v_and_b32_e32 v13, 0xffff0000, v202
	v_lshlrev_b32_e32 v14, 16, v203
	v_and_b32_e32 v15, 0xffff0000, v203
	v_pk_mul_f32 v[4:5], v[4:5], v[8:9]
	v_pk_mul_f32 v[8:9], v[2:3], v[14:15]
	v_pk_mul_f32 v[2:3], v[0:1], v[12:13]
	v_pk_mul_f32 v[6:7], v[6:7], v[10:11]
	v_cvt_pk_bf16_f32 v0, v4, v5
	s_nop 0
	v_cvt_pk_bf16_f32 v1, v6, v7
	v_cvt_pk_bf16_f32 v2, v2, v3
	v_cvt_pk_bf16_f32 v3, v8, v9
	global_store_dwordx4 v[16:17], v[0:3], off offset:256 nt
	s_cbranch_vccnz .LBB0_568
	s_andn2_b64 vcc, exec, s[10:11]
	s_cbranch_vccnz .LBB0_567
	s_barrier
	s_branch .LBB0_567

; __device__ __forceinline__ u32x4 pack8(f32x4 v0, f32x4 v1) { u32x4 w; w.x = cvt_pk_bf16(v0[0], v0[1]); w.y = cvt_pk_bf16(v0[2], v0[3]); w.z = cvt_pk_bf16(v1[0], v1[1]); w.w = cvt_pk_bf16(v1[2], v1[3]); return w; }
;     __device__ __forceinline__ void operator()(const f32x4 (&acc)[2][2][4][2], const Unit& u, int wr, int wc, int fr, int fq) const {
;     ...
;             if (wc < 2) {
;                 const bool lat = u.pm < ML / BM;
; #pragma unroll
;                 for (int ai = 0; ai < 2; ++ai)
; #pragma unroll
;                     for (int m = 0; m < 4; ++m) { const int row = row0 + ai * HALF + m * 16;
;                         f32x4 v0 = acc[ai][0][m][0], v1 = acc[ai][0][m][1];
;                         if (lat) {
;                             const int t = row & (SEQ - 1), pos = wc == 0 ? (t >> 6) : (t & 63);
;                             const f32x2* tp = tab + pos * 16 + 8 * (fq & 1);
;                             f32x4 p0, p1;
; #pragma unroll
;                             for (int j = 0; j < 4; ++j) { p0[j] = __shfl_xor(v0[j], 32); p1[j] = __shfl_xor(v1[j], 32); }
;                             const bool first = fq < 2;
; #pragma unroll
;                             for (int j = 0; j < 4; ++j) { const f32x2 c0 = tp[j], c1 = tp[4 + j];
;                                 v0[j] = first ? (v0[j] * c0.x - p0[j] * c0.y) : (p0[j] * c0.y + v0[j] * c0.x);
;                                 v1[j] = first ? (v1[j] * c1.x - p1[j] * c1.y) : (p1[j] * c1.y + v1[j] * c1.x); }
;                         }
;                         *(u32x4*)(KR + (size_t)row * 64 + wc * 32 + 8 * fq) = pack8(v0, v1); }
;             }
.LBB0_850:
	v_ashrrev_i32_e32 v151, 31, v150
	v_cvt_pk_bf16_f32 v152, v152, v153
	v_cvt_pk_bf16_f32 v153, v156, v157
	v_lshlrev_b64 v[156:157], 7, v[150:151]
	v_cvt_pk_bf16_f32 v154, v154, v155
	v_cvt_pk_bf16_f32 v155, v158, v159
	v_lshl_add_u64 v[156:157], v[140:141], 0, v[156:157]
	v_cndmask_b32_e64 v136, 0, 1, s[30:31]
	global_store_dwordx4 v[156:157], v[152:155], off nt
	v_cmp_ne_u32_e64 s[8:9], 1, v136
	s_andn2_b64 vcc, exec, s[30:31]
	v_mov_b32_e32 v152, v108
	v_mov_b32_e32 v153, v109
	v_mov_b32_e32 v156, v110
	v_mov_b32_e32 v157, v111
	v_mov_b32_e32 v154, v104
	v_mov_b32_e32 v155, v105
	v_mov_b32_e32 v158, v106
	v_mov_b32_e32 v159, v107
	s_cbranch_vccnz .LBB0_852
	v_mov_b32_e32 v136, s34
	v_cndmask_b32_e64 v136, v166, v136, s[0:1]
	v_lshlrev_b32_e32 v136, 7, v136
	v_lshl_add_u64 v[160:161], v[138:139], 0, v[136:137]
	global_load_dwordx4 v[152:155], v[160:161], off
	global_load_dwordx4 v[156:159], v[160:161], off offset:32
	global_load_dwordx4 v[174:177], v[160:161], off offset:16
	global_load_dwordx4 v[178:181], v[160:161], off offset:48
	v_and_b32_e32 v160, 64, v172
	v_xor_b32_e32 v136, 32, v172
	v_add_u32_e32 v160, 64, v160
	v_cmp_lt_i32_e32 vcc, v136, v160
	s_waitcnt vmcnt(0)
	v_mov_b32_e32 v189, v154
	v_cndmask_b32_e32 v136, v172, v136, vcc
	v_lshlrev_b32_e32 v136, 2, v136
	ds_bpermute_b32 v160, v136, v108
	ds_bpermute_b32 v182, v136, v104
	ds_bpermute_b32 v161, v136, v109
	ds_bpermute_b32 v183, v136, v105
	ds_bpermute_b32 v184, v136, v110
	ds_bpermute_b32 v186, v136, v106
	ds_bpermute_b32 v185, v136, v111
	ds_bpermute_b32 v187, v136, v107
	v_mov_b32_e32 v154, v153
	v_mov_b32_e32 v191, v158
	v_mov_b32_e32 v158, v157
	v_mov_b32_e32 v157, v176
	v_mov_b32_e32 v176, v175
	v_mov_b32_e32 v175, v180
	v_mov_b32_e32 v180, v179
	v_mov_b32_e32 v188, v152
	s_waitcnt lgkmcnt(5)
	v_pk_mul_f32 v[152:153], v[154:155], v[160:161]
	s_waitcnt lgkmcnt(4)
	v_pk_mul_f32 v[154:155], v[158:159], v[182:183]
	s_waitcnt lgkmcnt(1)
	v_pk_mul_f32 v[158:159], v[176:177], v[184:185]
	s_waitcnt lgkmcnt(0)
	v_pk_mul_f32 v[160:161], v[180:181], v[186:187]
	v_mov_b32_e32 v190, v156
	v_mov_b32_e32 v156, v174
	v_mov_b32_e32 v174, v178
	v_cndmask_b32_e64 v153, v153, -v153, s[10:11]
	v_cndmask_b32_e64 v152, v152, -v152, s[10:11]
	v_cndmask_b32_e64 v155, v155, -v155, s[10:11]
	v_cndmask_b32_e64 v154, v154, -v154, s[10:11]
	v_cndmask_b32_e64 v159, v159, -v159, s[10:11]
	v_cndmask_b32_e64 v158, v158, -v158, s[10:11]
	v_cndmask_b32_e64 v161, v161, -v161, s[10:11]
	v_cndmask_b32_e64 v160, v160, -v160, s[10:11]
	v_pk_fma_f32 v[152:153], v[108:109], v[188:189], v[152:153]
	v_pk_fma_f32 v[154:155], v[104:105], v[190:191], v[154:155]
	v_pk_fma_f32 v[156:157], v[110:111], v[156:157], v[158:159]
	v_pk_fma_f32 v[158:159], v[106:107], v[174:175], v[160:161]
.LBB0_852:
	v_or_b32_e32 v160, 16, v150
	v_ashrrev_i32_e32 v161, 31, v160
	v_cvt_pk_bf16_f32 v152, v152, v153
	v_cvt_pk_bf16_f32 v153, v156, v157
	v_lshlrev_b64 v[156:157], 7, v[160:161]
	v_cvt_pk_bf16_f32 v154, v154, v155
	v_cvt_pk_bf16_f32 v155, v158, v159
	v_lshl_add_u64 v[156:157], v[140:141], 0, v[156:157]
	global_store_dwordx4 v[156:157], v[152:155], off nt
	s_and_b64 vcc, exec, s[8:9]
	v_mov_b32_e32 v156, v94
	v_mov_b32_e32 v152, v92
	v_mov_b32_e32 v153, v93
	v_mov_b32_e32 v157, v95
	v_mov_b32_e32 v154, v88
	v_mov_b32_e32 v155, v89
	v_mov_b32_e32 v158, v90
	v_mov_b32_e32 v159, v91
	s_cbranch_vccnz .LBB0_854
	v_mov_b32_e32 v136, s34
	v_cndmask_b32_e64 v136, v167, v136, s[0:1]
	v_lshlrev_b32_e32 v136, 7, v136
	v_lshl_add_u64 v[160:161], v[138:139], 0, v[136:137]
	global_load_dwordx4 v[152:155], v[160:161], off
	global_load_dwordx4 v[156:159], v[160:161], off offset:32
	global_load_dwordx4 v[174:177], v[160:161], off offset:16
	global_load_dwordx4 v[178:181], v[160:161], off offset:48
	v_and_b32_e32 v160, 64, v172
	v_xor_b32_e32 v136, 32, v172
	v_add_u32_e32 v160, 64, v160
	v_cmp_lt_i32_e32 vcc, v136, v160
	s_waitcnt vmcnt(0)
	v_mov_b32_e32 v189, v154
	v_cndmask_b32_e32 v136, v172, v136, vcc
	v_lshlrev_b32_e32 v136, 2, v136
	ds_bpermute_b32 v160, v136, v92
	ds_bpermute_b32 v182, v136, v88
	ds_bpermute_b32 v161, v136, v93
	ds_bpermute_b32 v183, v136, v89
	ds_bpermute_b32 v184, v136, v94
	ds_bpermute_b32 v186, v136, v90
	ds_bpermute_b32 v185, v136, v95
	ds_bpermute_b32 v187, v136, v91
	v_mov_b32_e32 v154, v153
	v_mov_b32_e32 v191, v158
	v_mov_b32_e32 v158, v157
	v_mov_b32_e32 v157, v176
	v_mov_b32_e32 v176, v175
	v_mov_b32_e32 v175, v180
	v_mov_b32_e32 v180, v179
	v_mov_b32_e32 v188, v152
	s_waitcnt lgkmcnt(5)
	v_pk_mul_f32 v[152:153], v[154:155], v[160:161]
	s_waitcnt lgkmcnt(4)
	v_pk_mul_f32 v[154:155], v[158:159], v[182:183]
	s_waitcnt lgkmcnt(1)
	v_pk_mul_f32 v[158:159], v[176:177], v[184:185]
	s_waitcnt lgkmcnt(0)
	v_pk_mul_f32 v[160:161], v[180:181], v[186:187]
	v_mov_b32_e32 v190, v156
	v_mov_b32_e32 v156, v174
	v_mov_b32_e32 v174, v178
	v_cndmask_b32_e64 v153, v153, -v153, s[10:11]
	v_cndmask_b32_e64 v152, v152, -v152, s[10:11]
	v_cndmask_b32_e64 v155, v155, -v155, s[10:11]
	v_cndmask_b32_e64 v154, v154, -v154, s[10:11]
	v_cndmask_b32_e64 v159, v159, -v159, s[10:11]
	v_cndmask_b32_e64 v158, v158, -v158, s[10:11]
	v_cndmask_b32_e64 v161, v161, -v161, s[10:11]
	v_cndmask_b32_e64 v160, v160, -v160, s[10:11]
	v_pk_fma_f32 v[152:153], v[92:93], v[188:189], v[152:153]
	v_pk_fma_f32 v[154:155], v[88:89], v[190:191], v[154:155]
	v_pk_fma_f32 v[156:157], v[94:95], v[156:157], v[158:159]
	v_pk_fma_f32 v[158:159], v[90:91], v[174:175], v[160:161]
; __device__ __forceinline__ u32x4 pack8(f32x4 v0, f32x4 v1) { u32x4 w; w.x = cvt_pk_bf16(v0[0], v0[1]); w.y = cvt_pk_bf16(v0[2], v0[3]); w.z = cvt_pk_bf16(v1[0], v1[1]); w.w = cvt_pk_bf16(v1[2], v1[3]); return w; }
;     __device__ __forceinline__ void operator()(const f32x4 (&acc)[2][2][4][2], const Unit& u, int wr, int wc, int fr, int fq) const {
;     ...
;             if (wc < 2) {
;                 const bool lat = u.pm < ML / BM;
; #pragma unroll
;                 for (int ai = 0; ai < 2; ++ai)
; #pragma unroll
;                     for (int m = 0; m < 4; ++m) { const int row = row0 + ai * HALF + m * 16;
;                         f32x4 v0 = acc[ai][0][m][0], v1 = acc[ai][0][m][1];
;                         if (lat) {
;                             const int t = row & (SEQ - 1), pos = wc == 0 ? (t >> 6) : (t & 63);
;                             const f32x2* tp = tab + pos * 16 + 8 * (fq & 1);
;                             f32x4 p0, p1;
; #pragma unroll
;                             for (int j = 0; j < 4; ++j) { p0[j] = __shfl_xor(v0[j], 32); p1[j] = __shfl_xor(v1[j], 32); }
;                             const bool first = fq < 2;
; #pragma unroll
;                             for (int j = 0; j < 4; ++j) { const f32x2 c0 = tp[j], c1 = tp[4 + j];
;                                 v0[j] = first ? (v0[j] * c0.x - p0[j] * c0.y) : (p0[j] * c0.y + v0[j] * c0.x);
;                                 v1[j] = first ? (v1[j] * c1.x - p1[j] * c1.y) : (p1[j] * c1.y + v1[j] * c1.x); }
;                         }
;                         *(u32x4*)(KR + (size_t)row * 64 + wc * 32 + 8 * fq) = pack8(v0, v1); }
;             }
.LBB0_854:
	v_or_b32_e32 v160, 32, v150
	v_ashrrev_i32_e32 v161, 31, v160
	v_cvt_pk_bf16_f32 v152, v152, v153
	v_cvt_pk_bf16_f32 v153, v156, v157
	v_lshlrev_b64 v[156:157], 7, v[160:161]
	v_cvt_pk_bf16_f32 v154, v154, v155
	v_cvt_pk_bf16_f32 v155, v158, v159
	v_lshl_add_u64 v[156:157], v[140:141], 0, v[156:157]
	global_store_dwordx4 v[156:157], v[152:155], off nt
	s_and_b64 vcc, exec, s[8:9]
	v_mov_b32_e32 v156, v78
	v_mov_b32_e32 v152, v76
	v_mov_b32_e32 v153, v77
	v_mov_b32_e32 v157, v79
	v_mov_b32_e32 v154, v72
	v_mov_b32_e32 v155, v73
	v_mov_b32_e32 v158, v74
	v_mov_b32_e32 v159, v75
	s_cbranch_vccnz .LBB0_856
	v_mov_b32_e32 v136, s34
	v_cndmask_b32_e64 v136, v168, v136, s[0:1]
	v_lshlrev_b32_e32 v136, 7, v136
	v_lshl_add_u64 v[160:161], v[138:139], 0, v[136:137]
	global_load_dwordx4 v[152:155], v[160:161], off
	global_load_dwordx4 v[156:159], v[160:161], off offset:32
	global_load_dwordx4 v[174:177], v[160:161], off offset:16
	global_load_dwordx4 v[178:181], v[160:161], off offset:48
	v_and_b32_e32 v160, 64, v172
	v_xor_b32_e32 v136, 32, v172
	v_add_u32_e32 v160, 64, v160
	v_cmp_lt_i32_e32 vcc, v136, v160
	s_waitcnt vmcnt(0)
	v_mov_b32_e32 v189, v154
	v_cndmask_b32_e32 v136, v172, v136, vcc
	v_lshlrev_b32_e32 v136, 2, v136
	ds_bpermute_b32 v160, v136, v76
	ds_bpermute_b32 v182, v136, v72
	ds_bpermute_b32 v161, v136, v77
	ds_bpermute_b32 v183, v136, v73
	ds_bpermute_b32 v184, v136, v78
	ds_bpermute_b32 v186, v136, v74
	ds_bpermute_b32 v185, v136, v79
	ds_bpermute_b32 v187, v136, v75
	v_mov_b32_e32 v154, v153
	v_mov_b32_e32 v191, v158
	v_mov_b32_e32 v158, v157
	v_mov_b32_e32 v157, v176
	v_mov_b32_e32 v176, v175
	v_mov_b32_e32 v175, v180
	v_mov_b32_e32 v180, v179
	v_mov_b32_e32 v188, v152
	s_waitcnt lgkmcnt(5)
	v_pk_mul_f32 v[152:153], v[154:155], v[160:161]
	s_waitcnt lgkmcnt(4)
	v_pk_mul_f32 v[154:155], v[158:159], v[182:183]
	s_waitcnt lgkmcnt(1)
	v_pk_mul_f32 v[158:159], v[176:177], v[184:185]
	s_waitcnt lgkmcnt(0)
	v_pk_mul_f32 v[160:161], v[180:181], v[186:187]
	v_mov_b32_e32 v190, v156
	v_mov_b32_e32 v156, v174
	v_mov_b32_e32 v174, v178
	v_cndmask_b32_e64 v153, v153, -v153, s[10:11]
	v_cndmask_b32_e64 v152, v152, -v152, s[10:11]
	v_cndmask_b32_e64 v155, v155, -v155, s[10:11]
	v_cndmask_b32_e64 v154, v154, -v154, s[10:11]
	v_cndmask_b32_e64 v159, v159, -v159, s[10:11]
	v_cndmask_b32_e64 v158, v158, -v158, s[10:11]
	v_cndmask_b32_e64 v161, v161, -v161, s[10:11]
	v_cndmask_b32_e64 v160, v160, -v160, s[10:11]
	v_pk_fma_f32 v[152:153], v[76:77], v[188:189], v[152:153]
	v_pk_fma_f32 v[154:155], v[72:73], v[190:191], v[154:155]
	v_pk_fma_f32 v[156:157], v[78:79], v[156:157], v[158:159]
	v_pk_fma_f32 v[158:159], v[74:75], v[174:175], v[160:161]
.LBB0_856:
	v_or_b32_e32 v160, 48, v150
	v_ashrrev_i32_e32 v161, 31, v160
	v_cvt_pk_bf16_f32 v152, v152, v153
	v_cvt_pk_bf16_f32 v153, v156, v157
	v_lshlrev_b64 v[156:157], 7, v[160:161]
	v_lshl_add_u64 v[156:157], v[140:141], 0, v[156:157]
	v_cvt_pk_bf16_f32 v154, v154, v155
	v_cvt_pk_bf16_f32 v155, v158, v159
	global_store_dwordx4 v[156:157], v[152:155], off nt
	s_and_b64 vcc, exec, s[8:9]
	v_mov_b32_e32 v158, v62
	v_add_u32_e32 v152, 0x80, v150
	v_bfe_u32 v173, v152, 6, 5
	v_mov_b32_e32 v154, v60
	v_mov_b32_e32 v155, v61
	v_mov_b32_e32 v159, v63
	v_mov_b32_e32 v156, v56
	v_mov_b32_e32 v157, v57
	v_mov_b32_e32 v160, v58
	v_mov_b32_e32 v161, v59
	s_cbranch_vccnz .LBB0_858
	v_cndmask_b32_e64 v136, v162, v173, s[0:1]
	v_lshlrev_b32_e32 v136, 7, v136
	v_lshl_add_u64 v[178:179], v[138:139], 0, v[136:137]
	global_load_dwordx4 v[154:157], v[178:179], off
	global_load_dwordx4 v[158:161], v[178:179], off offset:32
	global_load_dwordx4 v[174:177], v[178:179], off offset:16
	s_nop 0
	global_load_dwordx4 v[178:181], v[178:179], off offset:48
	v_and_b32_e32 v153, 64, v172
	v_xor_b32_e32 v136, 32, v172
	v_add_u32_e32 v153, 64, v153
	v_cmp_lt_i32_e32 vcc, v136, v153
	s_waitcnt vmcnt(0)
	v_mov_b32_e32 v191, v156
	v_cndmask_b32_e32 v136, v172, v136, vcc
	v_lshlrev_b32_e32 v136, 2, v136
	ds_bpermute_b32 v182, v136, v60
	ds_bpermute_b32 v184, v136, v56
	ds_bpermute_b32 v183, v136, v61
	ds_bpermute_b32 v185, v136, v57
	ds_bpermute_b32 v186, v136, v62
	ds_bpermute_b32 v188, v136, v58
	ds_bpermute_b32 v187, v136, v63
	ds_bpermute_b32 v189, v136, v59
	v_mov_b32_e32 v156, v155
	v_mov_b32_e32 v193, v160
	v_mov_b32_e32 v160, v159
	v_mov_b32_e32 v159, v176
	v_mov_b32_e32 v176, v175
	v_mov_b32_e32 v175, v180
	v_mov_b32_e32 v180, v179
	v_mov_b32_e32 v190, v154
	s_waitcnt lgkmcnt(5)
	v_pk_mul_f32 v[154:155], v[156:157], v[182:183]
	s_waitcnt lgkmcnt(4)
	v_pk_mul_f32 v[156:157], v[160:161], v[184:185]
	s_waitcnt lgkmcnt(1)
	v_pk_mul_f32 v[160:161], v[176:177], v[186:187]
	s_waitcnt lgkmcnt(0)
	v_pk_mul_f32 v[176:177], v[180:181], v[188:189]
	v_mov_b32_e32 v192, v158
	v_mov_b32_e32 v158, v174
	v_mov_b32_e32 v174, v178
	v_cndmask_b32_e64 v155, v155, -v155, s[10:11]
	v_cndmask_b32_e64 v154, v154, -v154, s[10:11]
	v_cndmask_b32_e64 v157, v157, -v157, s[10:11]
	v_cndmask_b32_e64 v156, v156, -v156, s[10:11]
	v_cndmask_b32_e64 v161, v161, -v161, s[10:11]
	v_cndmask_b32_e64 v160, v160, -v160, s[10:11]
	v_cndmask_b32_e64 v177, v177, -v177, s[10:11]
	v_cndmask_b32_e64 v176, v176, -v176, s[10:11]
	v_pk_fma_f32 v[154:155], v[60:61], v[190:191], v[154:155]
	v_pk_fma_f32 v[156:157], v[56:57], v[192:193], v[156:157]
	v_pk_fma_f32 v[158:159], v[62:63], v[158:159], v[160:161]
	v_pk_fma_f32 v[160:161], v[58:59], v[174:175], v[176:177]
; __device__ __forceinline__ u32x4 pack8(f32x4 v0, f32x4 v1) { u32x4 w; w.x = cvt_pk_bf16(v0[0], v0[1]); w.y = cvt_pk_bf16(v0[2], v0[3]); w.z = cvt_pk_bf16(v1[0], v1[1]); w.w = cvt_pk_bf16(v1[2], v1[3]); return w; }
;     __device__ __forceinline__ void operator()(const f32x4 (&acc)[2][2][4][2], const Unit& u, int wr, int wc, int fr, int fq) const {
;     ...
;             if (wc < 2) {
;                 const bool lat = u.pm < ML / BM;
; #pragma unroll
;                 for (int ai = 0; ai < 2; ++ai)
; #pragma unroll
;                     for (int m = 0; m < 4; ++m) { const int row = row0 + ai * HALF + m * 16;
;                         f32x4 v0 = acc[ai][0][m][0], v1 = acc[ai][0][m][1];
;                         if (lat) {
;                             const int t = row & (SEQ - 1), pos = wc == 0 ? (t >> 6) : (t & 63);
;                             const f32x2* tp = tab + pos * 16 + 8 * (fq & 1);
;                             f32x4 p0, p1;
; #pragma unroll
;                             for (int j = 0; j < 4; ++j) { p0[j] = __shfl_xor(v0[j], 32); p1[j] = __shfl_xor(v1[j], 32); }
;                             const bool first = fq < 2;
; #pragma unroll
;                             for (int j = 0; j < 4; ++j) { const f32x2 c0 = tp[j], c1 = tp[4 + j];
;                                 v0[j] = first ? (v0[j] * c0.x - p0[j] * c0.y) : (p0[j] * c0.y + v0[j] * c0.x);
;                                 v1[j] = first ? (v1[j] * c1.x - p1[j] * c1.y) : (p1[j] * c1.y + v1[j] * c1.x); }
;                         }
;                         *(u32x4*)(KR + (size_t)row * 64 + wc * 32 + 8 * fq) = pack8(v0, v1); }
;             }
.LBB0_858:
	v_ashrrev_i32_e32 v153, 31, v152
	v_lshlrev_b64 v[152:153], 7, v[152:153]
	v_cvt_pk_bf16_f32 v154, v154, v155
	v_cvt_pk_bf16_f32 v155, v158, v159
	v_cvt_pk_bf16_f32 v156, v156, v157
	v_cvt_pk_bf16_f32 v157, v160, v161
	v_lshl_add_u64 v[152:153], v[140:141], 0, v[152:153]
	global_store_dwordx4 v[152:153], v[154:157], off nt
	s_and_b64 vcc, exec, s[8:9]
	v_mov_b32_e32 v152, v44
	v_mov_b32_e32 v153, v45
	v_mov_b32_e32 v156, v46
	v_mov_b32_e32 v157, v47
	v_mov_b32_e32 v154, v40
	v_mov_b32_e32 v155, v41
	v_mov_b32_e32 v158, v42
	v_mov_b32_e32 v159, v43
	s_cbranch_vccnz .LBB0_860
	v_cndmask_b32_e64 v136, v166, v173, s[0:1]
	v_lshlrev_b32_e32 v136, 7, v136
	v_lshl_add_u64 v[160:161], v[138:139], 0, v[136:137]
	global_load_dwordx4 v[152:155], v[160:161], off
	global_load_dwordx4 v[156:159], v[160:161], off offset:32
	global_load_dwordx4 v[174:177], v[160:161], off offset:16
	global_load_dwordx4 v[178:181], v[160:161], off offset:48
	v_and_b32_e32 v160, 64, v172
	v_xor_b32_e32 v136, 32, v172
	v_add_u32_e32 v160, 64, v160
	v_cmp_lt_i32_e32 vcc, v136, v160
	s_waitcnt vmcnt(0)
	v_mov_b32_e32 v189, v154
	v_cndmask_b32_e32 v136, v172, v136, vcc
	v_lshlrev_b32_e32 v136, 2, v136
	ds_bpermute_b32 v160, v136, v44
	ds_bpermute_b32 v182, v136, v40
	ds_bpermute_b32 v161, v136, v45
	ds_bpermute_b32 v183, v136, v41
	ds_bpermute_b32 v184, v136, v46
	ds_bpermute_b32 v186, v136, v42
	ds_bpermute_b32 v185, v136, v47
	ds_bpermute_b32 v187, v136, v43
	v_mov_b32_e32 v154, v153
	v_mov_b32_e32 v191, v158
	v_mov_b32_e32 v158, v157
	v_mov_b32_e32 v157, v176
	v_mov_b32_e32 v176, v175
	v_mov_b32_e32 v175, v180
	v_mov_b32_e32 v180, v179
	v_mov_b32_e32 v188, v152
	s_waitcnt lgkmcnt(5)
	v_pk_mul_f32 v[152:153], v[154:155], v[160:161]
	s_waitcnt lgkmcnt(4)
	v_pk_mul_f32 v[154:155], v[158:159], v[182:183]
	s_waitcnt lgkmcnt(1)
	v_pk_mul_f32 v[158:159], v[176:177], v[184:185]
	s_waitcnt lgkmcnt(0)
	v_pk_mul_f32 v[160:161], v[180:181], v[186:187]
	v_mov_b32_e32 v190, v156
	v_mov_b32_e32 v156, v174
	v_mov_b32_e32 v174, v178
	v_cndmask_b32_e64 v153, v153, -v153, s[10:11]
	v_cndmask_b32_e64 v152, v152, -v152, s[10:11]
	v_cndmask_b32_e64 v155, v155, -v155, s[10:11]
	v_cndmask_b32_e64 v154, v154, -v154, s[10:11]
	v_cndmask_b32_e64 v159, v159, -v159, s[10:11]
	v_cndmask_b32_e64 v158, v158, -v158, s[10:11]
	v_cndmask_b32_e64 v161, v161, -v161, s[10:11]
	v_cndmask_b32_e64 v160, v160, -v160, s[10:11]
	v_pk_fma_f32 v[152:153], v[44:45], v[188:189], v[152:153]
	v_pk_fma_f32 v[154:155], v[40:41], v[190:191], v[154:155]
	v_pk_fma_f32 v[156:157], v[46:47], v[156:157], v[158:159]
	v_pk_fma_f32 v[158:159], v[42:43], v[174:175], v[160:161]
.LBB0_860:
	v_cvt_pk_bf16_f32 v174, v152, v153
	v_lshlrev_b64 v[152:153], 7, v[150:151]
	v_lshl_add_u64 v[152:153], v[140:141], 0, v[152:153]
	v_cvt_pk_bf16_f32 v175, v156, v157
	v_cvt_pk_bf16_f32 v176, v154, v155
	v_add_co_u32_e32 v154, vcc, 0x4000, v152
	v_cvt_pk_bf16_f32 v177, v158, v159
	v_mov_b32_e32 v158, v30
	s_nop 0
	v_addc_co_u32_e32 v155, vcc, 0, v153, vcc
	global_store_dwordx4 v[154:155], v[174:177], off offset:2048 nt
	s_and_b64 vcc, exec, s[8:9]
	v_mov_b32_e32 v154, v28
	v_mov_b32_e32 v155, v29
	v_mov_b32_e32 v159, v31
	v_mov_b32_e32 v156, v24
	v_mov_b32_e32 v157, v25
	v_mov_b32_e32 v160, v26
	v_mov_b32_e32 v161, v27
	s_cbranch_vccnz .LBB0_862
	v_cndmask_b32_e64 v136, v167, v173, s[0:1]
	v_lshlrev_b32_e32 v136, 7, v136
	v_lshl_add_u64 v[178:179], v[138:139], 0, v[136:137]
	global_load_dwordx4 v[154:157], v[178:179], off
	global_load_dwordx4 v[158:161], v[178:179], off offset:32
	global_load_dwordx4 v[174:177], v[178:179], off offset:16
	s_nop 0
	global_load_dwordx4 v[178:181], v[178:179], off offset:48
	v_and_b32_e32 v182, 64, v172
	v_xor_b32_e32 v136, 32, v172
	v_add_u32_e32 v182, 64, v182
	v_cmp_lt_i32_e32 vcc, v136, v182
	s_waitcnt vmcnt(0)
	v_mov_b32_e32 v191, v156
	v_cndmask_b32_e32 v136, v172, v136, vcc
	v_lshlrev_b32_e32 v136, 2, v136
	ds_bpermute_b32 v182, v136, v28
	ds_bpermute_b32 v184, v136, v24
	ds_bpermute_b32 v183, v136, v29
	ds_bpermute_b32 v185, v136, v25
	ds_bpermute_b32 v186, v136, v30
	ds_bpermute_b32 v188, v136, v26
	ds_bpermute_b32 v187, v136, v31
	ds_bpermute_b32 v189, v136, v27
	v_mov_b32_e32 v156, v155
	v_mov_b32_e32 v193, v160
	v_mov_b32_e32 v160, v159
	v_mov_b32_e32 v159, v176
	v_mov_b32_e32 v176, v175
	v_mov_b32_e32 v175, v180
	v_mov_b32_e32 v180, v179
	v_mov_b32_e32 v190, v154
	s_waitcnt lgkmcnt(5)
	v_pk_mul_f32 v[154:155], v[156:157], v[182:183]
	s_waitcnt lgkmcnt(4)
	v_pk_mul_f32 v[156:157], v[160:161], v[184:185]
	s_waitcnt lgkmcnt(1)
	v_pk_mul_f32 v[160:161], v[176:177], v[186:187]
	s_waitcnt lgkmcnt(0)
	v_pk_mul_f32 v[176:177], v[180:181], v[188:189]
	v_mov_b32_e32 v192, v158
	v_mov_b32_e32 v158, v174
	v_mov_b32_e32 v174, v178
	v_cndmask_b32_e64 v155, v155, -v155, s[10:11]
	v_cndmask_b32_e64 v154, v154, -v154, s[10:11]
	v_cndmask_b32_e64 v157, v157, -v157, s[10:11]
	v_cndmask_b32_e64 v156, v156, -v156, s[10:11]
	v_cndmask_b32_e64 v161, v161, -v161, s[10:11]
	v_cndmask_b32_e64 v160, v160, -v160, s[10:11]
	v_cndmask_b32_e64 v177, v177, -v177, s[10:11]
	v_cndmask_b32_e64 v176, v176, -v176, s[10:11]
	v_pk_fma_f32 v[154:155], v[28:29], v[190:191], v[154:155]
	v_pk_fma_f32 v[156:157], v[24:25], v[192:193], v[156:157]
	v_pk_fma_f32 v[158:159], v[30:31], v[158:159], v[160:161]
	v_pk_fma_f32 v[160:161], v[26:27], v[174:175], v[176:177]
; __device__ __forceinline__ u32x4 pack8(f32x4 v0, f32x4 v1) { u32x4 w; w.x = cvt_pk_bf16(v0[0], v0[1]); w.y = cvt_pk_bf16(v0[2], v0[3]); w.z = cvt_pk_bf16(v1[0], v1[1]); w.w = cvt_pk_bf16(v1[2], v1[3]); return w; }
;     __device__ __forceinline__ void operator()(const f32x4 (&acc)[2][2][4][2], const Unit& u, int wr, int wc, int fr, int fq) const {
;     ...
;             if (wc < 2) {
;                 const bool lat = u.pm < ML / BM;
; #pragma unroll
;                 for (int ai = 0; ai < 2; ++ai)
; #pragma unroll
;                     for (int m = 0; m < 4; ++m) { const int row = row0 + ai * HALF + m * 16;
;                         f32x4 v0 = acc[ai][0][m][0], v1 = acc[ai][0][m][1];
;                         if (lat) {
;                             const int t = row & (SEQ - 1), pos = wc == 0 ? (t >> 6) : (t & 63);
;                             const f32x2* tp = tab + pos * 16 + 8 * (fq & 1);
;                             f32x4 p0, p1;
; #pragma unroll
;                             for (int j = 0; j < 4; ++j) { p0[j] = __shfl_xor(v0[j], 32); p1[j] = __shfl_xor(v1[j], 32); }
;                             const bool first = fq < 2;
; #pragma unroll
;                             for (int j = 0; j < 4; ++j) { const f32x2 c0 = tp[j], c1 = tp[4 + j];
;                                 v0[j] = first ? (v0[j] * c0.x - p0[j] * c0.y) : (p0[j] * c0.y + v0[j] * c0.x);
;                                 v1[j] = first ? (v1[j] * c1.x - p1[j] * c1.y) : (p1[j] * c1.y + v1[j] * c1.x); }
;                         }
;                         *(u32x4*)(KR + (size_t)row * 64 + wc * 32 + 8 * fq) = pack8(v0, v1); }
;             }
.LBB0_862:
	v_add_co_u32_e32 v152, vcc, 0x5000, v152
	v_cvt_pk_bf16_f32 v154, v154, v155
	v_cvt_pk_bf16_f32 v155, v158, v159
	v_cvt_pk_bf16_f32 v156, v156, v157
	v_cvt_pk_bf16_f32 v157, v160, v161
	s_nop 1
	v_addc_co_u32_e32 v153, vcc, 0, v153, vcc
	global_store_dwordx4 v[152:153], v[154:157], off nt
	s_and_b64 vcc, exec, s[8:9]
	v_mov_b32_e32 v152, v8
	v_mov_b32_e32 v154, v12
	v_mov_b32_e32 v155, v13
	v_mov_b32_e32 v156, v14
	v_mov_b32_e32 v157, v15
	v_mov_b32_e32 v153, v9
	v_mov_b32_e32 v158, v10
	v_mov_b32_e32 v159, v11
	s_cbranch_vccnz .LBB0_864
	v_cndmask_b32_e64 v136, v168, v173, s[0:1]
	v_lshlrev_b32_e32 v136, 7, v136
	v_lshl_add_u64 v[160:161], v[138:139], 0, v[136:137]
	global_load_dwordx4 v[152:155], v[160:161], off
	global_load_dwordx4 v[156:159], v[160:161], off offset:32
	global_load_dwordx4 v[174:177], v[160:161], off offset:16
	global_load_dwordx4 v[178:181], v[160:161], off offset:48
	v_and_b32_e32 v160, 64, v172
	v_xor_b32_e32 v136, 32, v172
	v_add_u32_e32 v160, 64, v160
	v_cmp_lt_i32_e32 vcc, v136, v160
	s_waitcnt vmcnt(0)
	v_mov_b32_e32 v189, v154
	v_cndmask_b32_e32 v136, v172, v136, vcc
	v_lshlrev_b32_e32 v136, 2, v136
	ds_bpermute_b32 v160, v136, v12
	ds_bpermute_b32 v182, v136, v8
	ds_bpermute_b32 v161, v136, v13
	ds_bpermute_b32 v183, v136, v9
	ds_bpermute_b32 v184, v136, v14
	ds_bpermute_b32 v186, v136, v10
	ds_bpermute_b32 v185, v136, v15
	ds_bpermute_b32 v187, v136, v11
	v_mov_b32_e32 v154, v153
	v_mov_b32_e32 v153, v158
	v_mov_b32_e32 v158, v157
	v_mov_b32_e32 v157, v176
	v_mov_b32_e32 v176, v175
	v_mov_b32_e32 v175, v180
	v_mov_b32_e32 v180, v179
	s_waitcnt lgkmcnt(5)
	v_pk_mul_f32 v[154:155], v[154:155], v[160:161]
	s_waitcnt lgkmcnt(4)
	v_pk_mul_f32 v[158:159], v[158:159], v[182:183]
	s_waitcnt lgkmcnt(1)
	v_pk_mul_f32 v[160:161], v[176:177], v[184:185]
	s_waitcnt lgkmcnt(0)
	v_pk_mul_f32 v[176:177], v[180:181], v[186:187]
	v_mov_b32_e32 v188, v152
	v_mov_b32_e32 v152, v156
	v_mov_b32_e32 v156, v174
	v_mov_b32_e32 v174, v178
	v_cndmask_b32_e64 v155, v155, -v155, s[10:11]
	v_cndmask_b32_e64 v154, v154, -v154, s[10:11]
	v_cndmask_b32_e64 v159, v159, -v159, s[10:11]
	v_cndmask_b32_e64 v158, v158, -v158, s[10:11]
	v_cndmask_b32_e64 v161, v161, -v161, s[10:11]
	v_cndmask_b32_e64 v160, v160, -v160, s[10:11]
	v_cndmask_b32_e64 v177, v177, -v177, s[10:11]
	v_cndmask_b32_e64 v176, v176, -v176, s[10:11]
	v_pk_fma_f32 v[154:155], v[12:13], v[188:189], v[154:155]
	v_pk_fma_f32 v[152:153], v[8:9], v[152:153], v[158:159]
	v_pk_fma_f32 v[156:157], v[14:15], v[156:157], v[160:161]
	v_pk_fma_f32 v[158:159], v[10:11], v[174:175], v[176:177]
.LBB0_864:
	v_cvt_pk_bf16_f32 v154, v154, v155
	v_cvt_pk_bf16_f32 v155, v156, v157
	v_cvt_pk_bf16_f32 v156, v152, v153
	v_lshlrev_b64 v[152:153], 7, v[150:151]
	v_lshl_add_u64 v[152:153], v[140:141], 0, v[152:153]
	v_add_co_u32_e32 v152, vcc, 0x5000, v152
	v_cvt_pk_bf16_f32 v157, v158, v159
	s_nop 1
	v_addc_co_u32_e32 v153, vcc, 0, v153, vcc
	global_store_dwordx4 v[152:153], v[154:157], off offset:2048 nt

; __device__ __forceinline__ u32x4 pack8(f32x4 v0, f32x4 v1) { u32x4 w; w.x = cvt_pk_bf16(v0[0], v0[1]); w.y = cvt_pk_bf16(v0[2], v0[3]); w.z = cvt_pk_bf16(v1[0], v1[1]); w.w = cvt_pk_bf16(v1[2], v1[3]); return w; }
; __device__ __forceinline__ f32x4 silu4(f32x4 v) { return (f32x4){silu_f(v[0]), silu_f(v[1]), silu_f(v[2]), silu_f(v[3])}; }
;     __device__ __forceinline__ void operator()(const f32x4 (&acc)[2][2][4][2], const Unit& u, int wr, int wc, int fr, int fq) const {
;     ...
;         } else if (pn < 12) {
;             if (u.pm < ML / BM) {
;                 const int col0 = (pn - 4) * BM + wc * 32 + 8 * fq;
; #pragma unroll
;                 for (int ai = 0; ai < 2; ++ai)
; #pragma unroll
;                     for (int m = 0; m < 4; ++m) { bf16_t* rowp = SG + (size_t)(row0 + ai * HALF + m * 16) * DM + col0;
; #pragma unroll
;                         for (int bj = 0; bj < 2; ++bj) *(u32x4*)(rowp + bj * HALF) = pack8(silu4(acc[ai][bj][m][0]), silu4(acc[ai][bj][m][1])); }
;             }
.LBB0_866:
	s_andn2_b64 vcc, exec, s[8:9]
	s_cbranch_vccnz .LBB0_869
	s_cmp_gt_i32 s54, 63
	s_cbranch_scc1 .LBB0_869
	v_mul_f32_e32 v156, 0xbfb8aa3b, v126
	v_exp_f32_e32 v156, v156
	v_mul_f32_e32 v157, 0xbfb8aa3b, v127
	v_exp_f32_e32 v157, v157
	v_ashrrev_i32_e32 v151, 31, v150
	v_add_f32_e32 v156, 1.0, v156
	v_rcp_f32_e32 v156, v156
	v_lshlrev_b64 v[152:153], 12, v[150:151]
	v_mul_f32_e32 v151, 0xbfb8aa3b, v124
	v_mul_f32_e32 v159, 0xbfb8aa3b, v121
	v_mul_f32_e32 v158, v126, v156
	v_add_f32_e32 v156, 1.0, v157
	v_mul_f32_e32 v157, 0xbfb8aa3b, v120
	v_exp_f32_e32 v151, v151
	v_rcp_f32_e32 v156, v156
	v_exp_f32_e32 v157, v157
	v_exp_f32_e32 v159, v159
	v_lshl_add_u32 v136, s52, 8, v165
	v_lshlrev_b64 v[154:155], 1, v[136:137]
	v_add_f32_e32 v136, 1.0, v151
	v_mul_f32_e32 v151, 0xbfb8aa3b, v125
	v_mul_f32_e32 v160, v127, v156
	v_add_f32_e32 v156, 1.0, v157
	v_add_f32_e32 v157, 1.0, v159
	v_mul_f32_e32 v159, 0xbfb8aa3b, v122
	v_exp_f32_e32 v151, v151
	v_exp_f32_e32 v159, v159
	v_mul_f32_e32 v161, 0xbfb8aa3b, v123
	v_exp_f32_e32 v161, v161
	v_add_f32_e32 v151, 1.0, v151
	v_add_f32_e32 v159, 1.0, v159
	v_rcp_f32_e32 v136, v136
	v_rcp_f32_e32 v151, v151
	v_rcp_f32_e32 v156, v156
	v_rcp_f32_e32 v159, v159
	v_add_f32_e32 v161, 1.0, v161
	v_rcp_f32_e32 v157, v157
	v_rcp_f32_e32 v161, v161
	v_lshl_add_u64 v[152:153], s[14:15], 0, v[152:153]
	v_lshl_add_u64 v[152:153], v[152:153], 0, v[154:155]
	v_mul_f32_e32 v136, v124, v136
	v_mul_f32_e32 v151, v125, v151
	v_mul_f32_e32 v173, v120, v156
	v_mul_f32_e32 v159, v122, v159
	v_cvt_pk_bf16_f32 v156, v136, v151
	v_mul_f32_e32 v174, v121, v157
	v_mul_f32_e32 v161, v123, v161
	v_cvt_pk_bf16_f32 v157, v158, v160
	v_cvt_pk_bf16_f32 v158, v173, v174
	v_cvt_pk_bf16_f32 v159, v159, v161
	global_store_dwordx4 v[152:153], v[156:159], off nt
	v_mul_f32_e32 v136, 0xbfb8aa3b, v116
	v_mul_f32_e32 v151, 0xbfb8aa3b, v117
	v_mul_f32_e32 v156, 0xbfb8aa3b, v118
	v_exp_f32_e32 v156, v156
	v_mul_f32_e32 v157, 0xbfb8aa3b, v119
	v_exp_f32_e32 v157, v157
	v_mul_f32_e32 v159, 0xbfb8aa3b, v113
	v_add_f32_e32 v156, 1.0, v156
	v_rcp_f32_e32 v156, v156
	v_exp_f32_e32 v159, v159
	v_exp_f32_e32 v136, v136
	v_exp_f32_e32 v151, v151
	v_mul_f32_e32 v158, v118, v156
	v_add_f32_e32 v156, 1.0, v157
	v_mul_f32_e32 v157, 0xbfb8aa3b, v112
	v_rcp_f32_e32 v156, v156
	v_exp_f32_e32 v157, v157
	v_mul_f32_e32 v161, 0xbfb8aa3b, v115
	v_exp_f32_e32 v161, v161
	v_mul_f32_e32 v160, v119, v156
	v_add_f32_e32 v156, 1.0, v157
	v_add_f32_e32 v157, 1.0, v159
	v_mul_f32_e32 v159, 0xbfb8aa3b, v114
	v_exp_f32_e32 v159, v159
	v_add_f32_e32 v136, 1.0, v136
	v_add_f32_e32 v151, 1.0, v151
	v_rcp_f32_e32 v136, v136
	v_add_f32_e32 v159, 1.0, v159
	v_rcp_f32_e32 v151, v151
	v_rcp_f32_e32 v156, v156
	v_rcp_f32_e32 v159, v159
	v_add_f32_e32 v161, 1.0, v161
	v_rcp_f32_e32 v157, v157
	v_rcp_f32_e32 v161, v161
	v_mul_f32_e32 v136, v116, v136
	v_mul_f32_e32 v151, v117, v151
	v_mul_f32_e32 v173, v112, v156
	v_mul_f32_e32 v159, v114, v159
	v_cvt_pk_bf16_f32 v156, v136, v151
	v_mul_f32_e32 v174, v113, v157
	v_mul_f32_e32 v161, v115, v161
	v_cvt_pk_bf16_f32 v157, v158, v160
	v_cvt_pk_bf16_f32 v158, v173, v174
	v_cvt_pk_bf16_f32 v159, v159, v161
	global_store_dwordx4 v[152:153], v[156:159], off offset:256 nt
	v_mul_f32_e32 v136, 0xbfb8aa3b, v108
	v_mul_f32_e32 v151, 0xbfb8aa3b, v109
	v_or_b32_e32 v156, 16, v150
	v_ashrrev_i32_e32 v157, 31, v156
	v_lshlrev_b64 v[156:157], 12, v[156:157]
	v_lshl_add_u64 v[156:157], s[14:15], 0, v[156:157]
	v_lshl_add_u64 v[160:161], v[156:157], 0, v[154:155]
	v_mul_f32_e32 v156, 0xbfb8aa3b, v110
	v_exp_f32_e32 v156, v156
	v_mul_f32_e32 v157, 0xbfb8aa3b, v111
	v_exp_f32_e32 v157, v157
	v_mul_f32_e32 v159, 0xbfb8aa3b, v105
	v_add_f32_e32 v156, 1.0, v156
	v_rcp_f32_e32 v156, v156
	v_exp_f32_e32 v159, v159
	v_exp_f32_e32 v136, v136
	v_exp_f32_e32 v151, v151
	v_mul_f32_e32 v158, v110, v156
	v_add_f32_e32 v156, 1.0, v157
	v_mul_f32_e32 v157, 0xbfb8aa3b, v104
	v_rcp_f32_e32 v156, v156
	v_exp_f32_e32 v157, v157
	v_mul_f32_e32 v174, 0xbfb8aa3b, v107
	v_exp_f32_e32 v174, v174
	v_mul_f32_e32 v173, v111, v156
	v_add_f32_e32 v156, 1.0, v157
	v_add_f32_e32 v157, 1.0, v159
	v_mul_f32_e32 v159, 0xbfb8aa3b, v106
	v_exp_f32_e32 v159, v159
	v_add_f32_e32 v136, 1.0, v136
	v_add_f32_e32 v151, 1.0, v151
	v_rcp_f32_e32 v136, v136
	v_add_f32_e32 v159, 1.0, v159
	v_rcp_f32_e32 v151, v151
	v_rcp_f32_e32 v156, v156
	v_rcp_f32_e32 v159, v159
	v_add_f32_e32 v174, 1.0, v174
	v_rcp_f32_e32 v157, v157
	v_rcp_f32_e32 v174, v174
	v_mul_f32_e32 v136, v108, v136
	v_mul_f32_e32 v151, v109, v151
	v_mul_f32_e32 v175, v104, v156
	v_mul_f32_e32 v159, v106, v159
	v_cvt_pk_bf16_f32 v156, v136, v151
	v_mul_f32_e32 v176, v105, v157
	v_mul_f32_e32 v174, v107, v174
	v_cvt_pk_bf16_f32 v157, v158, v173
	v_cvt_pk_bf16_f32 v158, v175, v176
	v_cvt_pk_bf16_f32 v159, v159, v174
	global_store_dwordx4 v[160:161], v[156:159], off nt
	v_mul_f32_e32 v136, 0xbfb8aa3b, v100
	v_mul_f32_e32 v151, 0xbfb8aa3b, v101
	v_mul_f32_e32 v156, 0xbfb8aa3b, v102
	v_exp_f32_e32 v156, v156
	v_mul_f32_e32 v157, 0xbfb8aa3b, v103
	v_exp_f32_e32 v157, v157
	v_mul_f32_e32 v159, 0xbfb8aa3b, v97
	v_add_f32_e32 v156, 1.0, v156
	v_rcp_f32_e32 v156, v156
	v_exp_f32_e32 v159, v159
	v_exp_f32_e32 v136, v136
	v_exp_f32_e32 v151, v151
	v_mul_f32_e32 v158, v102, v156
	v_add_f32_e32 v156, 1.0, v157
	v_mul_f32_e32 v157, 0xbfb8aa3b, v96
	v_rcp_f32_e32 v156, v156
	v_exp_f32_e32 v157, v157
	v_mul_f32_e32 v174, 0xbfb8aa3b, v99
	v_exp_f32_e32 v174, v174
	v_mul_f32_e32 v173, v103, v156
	v_add_f32_e32 v156, 1.0, v157
	v_add_f32_e32 v157, 1.0, v159
	v_mul_f32_e32 v159, 0xbfb8aa3b, v98
	v_exp_f32_e32 v159, v159
	v_add_f32_e32 v136, 1.0, v136
; __device__ __forceinline__ u32x4 pack8(f32x4 v0, f32x4 v1) { u32x4 w; w.x = cvt_pk_bf16(v0[0], v0[1]); w.y = cvt_pk_bf16(v0[2], v0[3]); w.z = cvt_pk_bf16(v1[0], v1[1]); w.w = cvt_pk_bf16(v1[2], v1[3]); return w; }
; __device__ __forceinline__ f32x4 silu4(f32x4 v) { return (f32x4){silu_f(v[0]), silu_f(v[1]), silu_f(v[2]), silu_f(v[3])}; }
; __device__ __forceinline__ float silu_f(float v) { return v * __builtin_amdgcn_rcpf(1.f + __builtin_amdgcn_exp2f(-1.4426950408889634f * v)); }
;     __device__ __forceinline__ void operator()(const f32x4 (&acc)[2][2][4][2], const Unit& u, int wr, int wc, int fr, int fq) const {
;     ...
;         } else if (pn < 12) {
;             if (u.pm < ML / BM) {
;                 const int col0 = (pn - 4) * BM + wc * 32 + 8 * fq;
; #pragma unroll
;                 for (int ai = 0; ai < 2; ++ai)
; #pragma unroll
;                     for (int m = 0; m < 4; ++m) { bf16_t* rowp = SG + (size_t)(row0 + ai * HALF + m * 16) * DM + col0;
; #pragma unroll
;                         for (int bj = 0; bj < 2; ++bj) *(u32x4*)(rowp + bj * HALF) = pack8(silu4(acc[ai][bj][m][0]), silu4(acc[ai][bj][m][1])); }
;             }
	v_add_f32_e32 v151, 1.0, v151
	v_rcp_f32_e32 v136, v136
	v_add_f32_e32 v159, 1.0, v159
	v_rcp_f32_e32 v151, v151
	v_rcp_f32_e32 v156, v156
	v_rcp_f32_e32 v159, v159
	v_add_f32_e32 v174, 1.0, v174
	v_rcp_f32_e32 v157, v157
	v_rcp_f32_e32 v174, v174
	v_mul_f32_e32 v136, v100, v136
	v_mul_f32_e32 v151, v101, v151
	v_mul_f32_e32 v175, v96, v156
	v_mul_f32_e32 v159, v98, v159
	v_cvt_pk_bf16_f32 v156, v136, v151
	v_mul_f32_e32 v176, v97, v157
	v_mul_f32_e32 v174, v99, v174
	v_cvt_pk_bf16_f32 v157, v158, v173
	v_cvt_pk_bf16_f32 v158, v175, v176
	v_cvt_pk_bf16_f32 v159, v159, v174
	global_store_dwordx4 v[160:161], v[156:159], off offset:256 nt
	v_mul_f32_e32 v136, 0xbfb8aa3b, v92
	v_mul_f32_e32 v151, 0xbfb8aa3b, v93
	v_or_b32_e32 v156, 32, v150
	v_ashrrev_i32_e32 v157, 31, v156
	v_lshlrev_b64 v[156:157], 12, v[156:157]
	v_lshl_add_u64 v[156:157], s[14:15], 0, v[156:157]
	v_lshl_add_u64 v[160:161], v[156:157], 0, v[154:155]
	v_mul_f32_e32 v156, 0xbfb8aa3b, v94
	v_exp_f32_e32 v156, v156
	v_mul_f32_e32 v157, 0xbfb8aa3b, v95
	v_exp_f32_e32 v157, v157
	v_mul_f32_e32 v159, 0xbfb8aa3b, v89
	v_add_f32_e32 v156, 1.0, v156
	v_rcp_f32_e32 v156, v156
	v_exp_f32_e32 v159, v159
	v_exp_f32_e32 v136, v136
	v_exp_f32_e32 v151, v151
	v_mul_f32_e32 v158, v94, v156
	v_add_f32_e32 v156, 1.0, v157
	v_mul_f32_e32 v157, 0xbfb8aa3b, v88
	v_rcp_f32_e32 v156, v156
	v_exp_f32_e32 v157, v157
	v_mul_f32_e32 v174, 0xbfb8aa3b, v91
	v_exp_f32_e32 v174, v174
	v_mul_f32_e32 v173, v95, v156
	v_add_f32_e32 v156, 1.0, v157
	v_add_f32_e32 v157, 1.0, v159
	v_mul_f32_e32 v159, 0xbfb8aa3b, v90
	v_exp_f32_e32 v159, v159
	v_add_f32_e32 v136, 1.0, v136
	v_add_f32_e32 v151, 1.0, v151
	v_rcp_f32_e32 v136, v136
	v_add_f32_e32 v159, 1.0, v159
	v_rcp_f32_e32 v151, v151
	v_rcp_f32_e32 v156, v156
	v_rcp_f32_e32 v159, v159
	v_add_f32_e32 v174, 1.0, v174
	v_rcp_f32_e32 v157, v157
	v_rcp_f32_e32 v174, v174
	v_mul_f32_e32 v136, v92, v136
	v_mul_f32_e32 v151, v93, v151
	v_mul_f32_e32 v175, v88, v156
	v_mul_f32_e32 v159, v90, v159
	v_cvt_pk_bf16_f32 v156, v136, v151
	v_mul_f32_e32 v176, v89, v157
	v_mul_f32_e32 v174, v91, v174
	v_cvt_pk_bf16_f32 v157, v158, v173
	v_cvt_pk_bf16_f32 v158, v175, v176
	v_cvt_pk_bf16_f32 v159, v159, v174
	global_store_dwordx4 v[160:161], v[156:159], off nt
	v_mul_f32_e32 v136, 0xbfb8aa3b, v84
	v_mul_f32_e32 v151, 0xbfb8aa3b, v85
	v_mul_f32_e32 v156, 0xbfb8aa3b, v86
	v_exp_f32_e32 v156, v156
	v_mul_f32_e32 v157, 0xbfb8aa3b, v87
	v_exp_f32_e32 v157, v157
	v_mul_f32_e32 v159, 0xbfb8aa3b, v81
	v_add_f32_e32 v156, 1.0, v156
	v_rcp_f32_e32 v156, v156
	v_exp_f32_e32 v159, v159
	v_exp_f32_e32 v136, v136
	v_exp_f32_e32 v151, v151
	v_mul_f32_e32 v158, v86, v156
	v_add_f32_e32 v156, 1.0, v157
	v_mul_f32_e32 v157, 0xbfb8aa3b, v80
	v_rcp_f32_e32 v156, v156
	v_exp_f32_e32 v157, v157
	v_mul_f32_e32 v174, 0xbfb8aa3b, v83
	v_exp_f32_e32 v174, v174
	v_mul_f32_e32 v173, v87, v156
	v_add_f32_e32 v156, 1.0, v157
	v_add_f32_e32 v157, 1.0, v159
	v_mul_f32_e32 v159, 0xbfb8aa3b, v82
	v_exp_f32_e32 v159, v159
	v_add_f32_e32 v136, 1.0, v136
	v_add_f32_e32 v151, 1.0, v151
	v_rcp_f32_e32 v136, v136
	v_add_f32_e32 v159, 1.0, v159
	v_rcp_f32_e32 v151, v151
	v_rcp_f32_e32 v156, v156
	v_rcp_f32_e32 v159, v159
	v_add_f32_e32 v174, 1.0, v174
	v_rcp_f32_e32 v157, v157
	v_rcp_f32_e32 v174, v174
	v_mul_f32_e32 v136, v84, v136
	v_mul_f32_e32 v151, v85, v151
	v_mul_f32_e32 v175, v80, v156
	v_mul_f32_e32 v159, v82, v159
	v_cvt_pk_bf16_f32 v156, v136, v151
	v_mul_f32_e32 v176, v81, v157
	v_mul_f32_e32 v174, v83, v174
	v_cvt_pk_bf16_f32 v157, v158, v173
	v_cvt_pk_bf16_f32 v158, v175, v176
	v_cvt_pk_bf16_f32 v159, v159, v174
	global_store_dwordx4 v[160:161], v[156:159], off offset:256 nt
	v_mul_f32_e32 v136, 0xbfb8aa3b, v76
	v_mul_f32_e32 v151, 0xbfb8aa3b, v77
	v_or_b32_e32 v156, 48, v150
	v_ashrrev_i32_e32 v157, 31, v156
	v_lshlrev_b64 v[156:157], 12, v[156:157]
	v_lshl_add_u64 v[156:157], s[14:15], 0, v[156:157]
	v_lshl_add_u64 v[158:159], v[156:157], 0, v[154:155]
	v_mul_f32_e32 v154, 0xbfb8aa3b, v78
	v_exp_f32_e32 v154, v154
	v_mul_f32_e32 v155, 0xbfb8aa3b, v79
	v_exp_f32_e32 v155, v155
	v_mul_f32_e32 v157, 0xbfb8aa3b, v73
	v_add_f32_e32 v154, 1.0, v154
	v_rcp_f32_e32 v154, v154
	v_exp_f32_e32 v157, v157
	v_exp_f32_e32 v136, v136
	v_exp_f32_e32 v151, v151
	v_mul_f32_e32 v156, v78, v154
	v_add_f32_e32 v154, 1.0, v155
	v_mul_f32_e32 v155, 0xbfb8aa3b, v72
	v_rcp_f32_e32 v154, v154
	v_exp_f32_e32 v155, v155
	v_mul_f32_e32 v161, 0xbfb8aa3b, v75
	v_exp_f32_e32 v161, v161
	v_mul_f32_e32 v160, v79, v154
	v_add_f32_e32 v154, 1.0, v155
	v_add_f32_e32 v155, 1.0, v157
	v_mul_f32_e32 v157, 0xbfb8aa3b, v74
	v_exp_f32_e32 v157, v157
	v_add_f32_e32 v136, 1.0, v136
	v_add_f32_e32 v151, 1.0, v151
	v_rcp_f32_e32 v136, v136
	v_add_f32_e32 v157, 1.0, v157
	v_rcp_f32_e32 v151, v151
	v_rcp_f32_e32 v154, v154
	v_rcp_f32_e32 v157, v157
	v_add_f32_e32 v161, 1.0, v161
	v_rcp_f32_e32 v155, v155
	v_rcp_f32_e32 v161, v161
	v_mul_f32_e32 v136, v76, v136
	v_mul_f32_e32 v151, v77, v151
	v_mul_f32_e32 v173, v72, v154
	v_mul_f32_e32 v157, v74, v157
	v_cvt_pk_bf16_f32 v154, v136, v151
	v_mul_f32_e32 v174, v73, v155
	v_mul_f32_e32 v161, v75, v161
	v_cvt_pk_bf16_f32 v155, v156, v160
	v_cvt_pk_bf16_f32 v156, v173, v174
	v_cvt_pk_bf16_f32 v157, v157, v161
	global_store_dwordx4 v[158:159], v[154:157], off nt
	v_mul_f32_e32 v136, 0xbfb8aa3b, v68
	v_mul_f32_e32 v151, 0xbfb8aa3b, v69
	v_mul_f32_e32 v154, 0xbfb8aa3b, v70
	v_exp_f32_e32 v154, v154
	v_mul_f32_e32 v155, 0xbfb8aa3b, v71
	v_exp_f32_e32 v155, v155
	v_mul_f32_e32 v157, 0xbfb8aa3b, v65
	v_add_f32_e32 v154, 1.0, v154
	v_rcp_f32_e32 v154, v154
	v_exp_f32_e32 v157, v157
	v_exp_f32_e32 v136, v136
; __device__ __forceinline__ u32x4 pack8(f32x4 v0, f32x4 v1) { u32x4 w; w.x = cvt_pk_bf16(v0[0], v0[1]); w.y = cvt_pk_bf16(v0[2], v0[3]); w.z = cvt_pk_bf16(v1[0], v1[1]); w.w = cvt_pk_bf16(v1[2], v1[3]); return w; }
; __device__ __forceinline__ f32x4 silu4(f32x4 v) { return (f32x4){silu_f(v[0]), silu_f(v[1]), silu_f(v[2]), silu_f(v[3])}; }
; __device__ __forceinline__ float silu_f(float v) { return v * __builtin_amdgcn_rcpf(1.f + __builtin_amdgcn_exp2f(-1.4426950408889634f * v)); }
;     __device__ __forceinline__ void operator()(const f32x4 (&acc)[2][2][4][2], const Unit& u, int wr, int wc, int fr, int fq) const {
;     ...
;         } else if (pn < 12) {
;             if (u.pm < ML / BM) {
;                 const int col0 = (pn - 4) * BM + wc * 32 + 8 * fq;
; #pragma unroll
;                 for (int ai = 0; ai < 2; ++ai)
; #pragma unroll
;                     for (int m = 0; m < 4; ++m) { bf16_t* rowp = SG + (size_t)(row0 + ai * HALF + m * 16) * DM + col0;
; #pragma unroll
;                         for (int bj = 0; bj < 2; ++bj) *(u32x4*)(rowp + bj * HALF) = pack8(silu4(acc[ai][bj][m][0]), silu4(acc[ai][bj][m][1])); }
;             }
	v_exp_f32_e32 v151, v151
	v_mul_f32_e32 v156, v70, v154
	v_add_f32_e32 v154, 1.0, v155
	v_mul_f32_e32 v155, 0xbfb8aa3b, v64
	v_rcp_f32_e32 v154, v154
	v_exp_f32_e32 v155, v155
	v_mul_f32_e32 v161, 0xbfb8aa3b, v67
	v_exp_f32_e32 v161, v161
	v_mul_f32_e32 v160, v71, v154
	v_add_f32_e32 v154, 1.0, v155
	v_add_f32_e32 v155, 1.0, v157
	v_mul_f32_e32 v157, 0xbfb8aa3b, v66
	v_exp_f32_e32 v157, v157
	v_add_f32_e32 v136, 1.0, v136
	v_add_f32_e32 v151, 1.0, v151
	v_rcp_f32_e32 v136, v136
	v_add_f32_e32 v157, 1.0, v157
	v_rcp_f32_e32 v151, v151
	v_rcp_f32_e32 v154, v154
	v_rcp_f32_e32 v157, v157
	v_add_f32_e32 v161, 1.0, v161
	v_rcp_f32_e32 v155, v155
	v_rcp_f32_e32 v161, v161
	v_mul_f32_e32 v136, v68, v136
	v_mul_f32_e32 v151, v69, v151
	v_mul_f32_e32 v173, v64, v154
	v_mul_f32_e32 v157, v66, v157
	v_cvt_pk_bf16_f32 v154, v136, v151
	v_mul_f32_e32 v174, v65, v155
	v_mul_f32_e32 v161, v67, v161
	v_cvt_pk_bf16_f32 v155, v156, v160
	v_cvt_pk_bf16_f32 v156, v173, v174
	v_cvt_pk_bf16_f32 v157, v157, v161
	global_store_dwordx4 v[158:159], v[154:157], off offset:256 nt
	v_mul_f32_e32 v136, 0xbfb8aa3b, v60
	v_mul_f32_e32 v151, 0xbfb8aa3b, v61
	v_mul_f32_e32 v154, 0xbfb8aa3b, v62
	v_exp_f32_e32 v154, v154
	v_mul_f32_e32 v155, 0xbfb8aa3b, v63
	v_exp_f32_e32 v155, v155
	v_mul_f32_e32 v157, 0xbfb8aa3b, v57
	v_add_f32_e32 v154, 1.0, v154
	v_rcp_f32_e32 v154, v154
	v_exp_f32_e32 v157, v157
	v_mul_f32_e32 v161, 0xbfb8aa3b, v59
	v_exp_f32_e32 v136, v136
	v_mul_f32_e32 v156, v62, v154
	v_add_f32_e32 v154, 1.0, v155
	v_mul_f32_e32 v155, 0xbfb8aa3b, v56
	v_rcp_f32_e32 v154, v154
	v_exp_f32_e32 v155, v155
	v_exp_f32_e32 v151, v151
	v_exp_f32_e32 v161, v161
	v_mul_f32_e32 v160, v63, v154
	v_add_f32_e32 v154, 1.0, v155
	v_add_f32_e32 v155, 1.0, v157
	v_mul_f32_e32 v157, 0xbfb8aa3b, v58
	v_exp_f32_e32 v157, v157
	v_add_f32_e32 v136, 1.0, v136
	v_add_f32_e32 v151, 1.0, v151
	v_add_f32_e32 v161, 1.0, v161
	v_add_f32_e32 v157, 1.0, v157
	v_rcp_f32_e32 v136, v136
	v_rcp_f32_e32 v151, v151
	v_rcp_f32_e32 v154, v154
	v_rcp_f32_e32 v155, v155
	v_rcp_f32_e32 v157, v157
	v_rcp_f32_e32 v161, v161
	s_mov_b64 s[8:9], 0x80000
	v_lshl_add_u64 v[158:159], v[152:153], 0, s[8:9]
	s_mov_b32 s8, 0x80000
	v_mul_f32_e32 v136, v60, v136
	v_mul_f32_e32 v151, v61, v151
	v_mul_f32_e32 v173, v56, v154
	v_mul_f32_e32 v174, v57, v155
	v_mul_f32_e32 v157, v58, v157
	v_mul_f32_e32 v161, v59, v161
	v_cvt_pk_bf16_f32 v154, v136, v151
	v_cvt_pk_bf16_f32 v155, v156, v160
	v_add_co_u32_e32 v160, vcc, s8, v152
	v_cvt_pk_bf16_f32 v156, v173, v174
	v_cvt_pk_bf16_f32 v157, v157, v161
	v_mul_f32_e32 v136, 0xbfb8aa3b, v52
	s_nop 0
	v_addc_co_u32_e32 v161, vcc, 0, v153, vcc
	global_store_dwordx4 v[160:161], v[154:157], off nt
	v_mul_f32_e32 v151, 0xbfb8aa3b, v53
	v_exp_f32_e32 v136, v136
	v_mul_f32_e32 v154, 0xbfb8aa3b, v54
	v_exp_f32_e32 v154, v154
	v_mul_f32_e32 v155, 0xbfb8aa3b, v55
	v_exp_f32_e32 v155, v155
	v_mul_f32_e32 v157, 0xbfb8aa3b, v49
	v_add_f32_e32 v154, 1.0, v154
	v_rcp_f32_e32 v154, v154
	v_exp_f32_e32 v157, v157
	v_exp_f32_e32 v151, v151
	v_mul_f32_e32 v161, 0xbfb8aa3b, v51
	v_mul_f32_e32 v156, v54, v154
	v_add_f32_e32 v154, 1.0, v155
	v_mul_f32_e32 v155, 0xbfb8aa3b, v48
	v_rcp_f32_e32 v154, v154
	v_exp_f32_e32 v155, v155
	v_exp_f32_e32 v161, v161
	v_add_f32_e32 v136, 1.0, v136
	v_mul_f32_e32 v160, v55, v154
	v_add_f32_e32 v154, 1.0, v155
	v_add_f32_e32 v155, 1.0, v157
	v_mul_f32_e32 v157, 0xbfb8aa3b, v50
	v_exp_f32_e32 v157, v157
	v_add_f32_e32 v151, 1.0, v151
	v_rcp_f32_e32 v136, v136
	v_rcp_f32_e32 v151, v151
	v_add_f32_e32 v157, 1.0, v157
	v_rcp_f32_e32 v154, v154
	v_rcp_f32_e32 v157, v157
	v_add_f32_e32 v161, 1.0, v161
	v_rcp_f32_e32 v155, v155
	v_rcp_f32_e32 v161, v161
	v_mul_f32_e32 v136, v52, v136
	v_mul_f32_e32 v151, v53, v151
	v_mul_f32_e32 v173, v48, v154
	v_mul_f32_e32 v157, v50, v157
	v_cvt_pk_bf16_f32 v154, v136, v151
	v_mul_f32_e32 v174, v49, v155
	v_mul_f32_e32 v161, v51, v161
	v_cvt_pk_bf16_f32 v155, v156, v160
	v_cvt_pk_bf16_f32 v156, v173, v174
	v_cvt_pk_bf16_f32 v157, v157, v161
	global_store_dwordx4 v[158:159], v[154:157], off offset:256 nt
	v_mul_f32_e32 v136, 0xbfb8aa3b, v44
	v_mul_f32_e32 v151, 0xbfb8aa3b, v45
	v_mul_f32_e32 v154, 0xbfb8aa3b, v46
	v_exp_f32_e32 v154, v154
	v_mul_f32_e32 v155, 0xbfb8aa3b, v47
	v_exp_f32_e32 v155, v155
	v_mul_f32_e32 v157, 0xbfb8aa3b, v41
	v_add_f32_e32 v154, 1.0, v154
	v_rcp_f32_e32 v154, v154
	v_exp_f32_e32 v157, v157
	v_mul_f32_e32 v161, 0xbfb8aa3b, v43
	v_exp_f32_e32 v136, v136
	v_mul_f32_e32 v156, v46, v154
	v_add_f32_e32 v154, 1.0, v155
	v_mul_f32_e32 v155, 0xbfb8aa3b, v40
	v_rcp_f32_e32 v154, v154
	v_exp_f32_e32 v155, v155
	v_exp_f32_e32 v151, v151
	v_exp_f32_e32 v161, v161
	v_mul_f32_e32 v160, v47, v154
	v_add_f32_e32 v154, 1.0, v155
	v_add_f32_e32 v155, 1.0, v157
	v_mul_f32_e32 v157, 0xbfb8aa3b, v42
	v_exp_f32_e32 v157, v157
	v_add_f32_e32 v136, 1.0, v136
	v_add_f32_e32 v151, 1.0, v151
	v_add_f32_e32 v161, 1.0, v161
	v_add_f32_e32 v157, 1.0, v157
	v_rcp_f32_e32 v136, v136
	v_rcp_f32_e32 v151, v151
	v_rcp_f32_e32 v154, v154
	v_rcp_f32_e32 v155, v155
	v_rcp_f32_e32 v157, v157
	v_rcp_f32_e32 v161, v161
	s_mov_b64 s[8:9], 0x90000
	v_lshl_add_u64 v[158:159], v[152:153], 0, s[8:9]
	s_mov_b32 s8, 0x90000
	v_mul_f32_e32 v136, v44, v136
	v_mul_f32_e32 v151, v45, v151
	v_mul_f32_e32 v173, v40, v154
	v_mul_f32_e32 v174, v41, v155
	v_mul_f32_e32 v157, v42, v157
	v_mul_f32_e32 v161, v43, v161
	v_cvt_pk_bf16_f32 v154, v136, v151
	v_cvt_pk_bf16_f32 v155, v156, v160
	v_add_co_u32_e32 v160, vcc, s8, v152
	v_cvt_pk_bf16_f32 v156, v173, v174
	v_cvt_pk_bf16_f32 v157, v157, v161
	v_mul_f32_e32 v136, 0xbfb8aa3b, v36
	s_nop 0
	v_addc_co_u32_e32 v161, vcc, 0, v153, vcc
; __device__ __forceinline__ u32x4 pack8(f32x4 v0, f32x4 v1) { u32x4 w; w.x = cvt_pk_bf16(v0[0], v0[1]); w.y = cvt_pk_bf16(v0[2], v0[3]); w.z = cvt_pk_bf16(v1[0], v1[1]); w.w = cvt_pk_bf16(v1[2], v1[3]); return w; }
; __device__ __forceinline__ f32x4 silu4(f32x4 v) { return (f32x4){silu_f(v[0]), silu_f(v[1]), silu_f(v[2]), silu_f(v[3])}; }
; __device__ __forceinline__ float silu_f(float v) { return v * __builtin_amdgcn_rcpf(1.f + __builtin_amdgcn_exp2f(-1.4426950408889634f * v)); }
;     __device__ __forceinline__ void operator()(const f32x4 (&acc)[2][2][4][2], const Unit& u, int wr, int wc, int fr, int fq) const {
;     ...
;         } else if (pn < 12) {
;             if (u.pm < ML / BM) {
;                 const int col0 = (pn - 4) * BM + wc * 32 + 8 * fq;
; #pragma unroll
;                 for (int ai = 0; ai < 2; ++ai)
; #pragma unroll
;                     for (int m = 0; m < 4; ++m) { bf16_t* rowp = SG + (size_t)(row0 + ai * HALF + m * 16) * DM + col0;
; #pragma unroll
;                         for (int bj = 0; bj < 2; ++bj) *(u32x4*)(rowp + bj * HALF) = pack8(silu4(acc[ai][bj][m][0]), silu4(acc[ai][bj][m][1])); }
;             }
	global_store_dwordx4 v[160:161], v[154:157], off nt
	v_mul_f32_e32 v151, 0xbfb8aa3b, v37
	v_exp_f32_e32 v136, v136
	v_mul_f32_e32 v154, 0xbfb8aa3b, v38
	v_exp_f32_e32 v154, v154
	v_mul_f32_e32 v155, 0xbfb8aa3b, v39
	v_exp_f32_e32 v155, v155
	v_mul_f32_e32 v157, 0xbfb8aa3b, v33
	v_add_f32_e32 v154, 1.0, v154
	v_rcp_f32_e32 v154, v154
	v_exp_f32_e32 v157, v157
	v_exp_f32_e32 v151, v151
	v_mul_f32_e32 v161, 0xbfb8aa3b, v35
	v_mul_f32_e32 v156, v38, v154
	v_add_f32_e32 v154, 1.0, v155
	v_mul_f32_e32 v155, 0xbfb8aa3b, v32
	v_rcp_f32_e32 v154, v154
	v_exp_f32_e32 v155, v155
	v_exp_f32_e32 v161, v161
	v_add_f32_e32 v136, 1.0, v136
	v_mul_f32_e32 v160, v39, v154
	v_add_f32_e32 v154, 1.0, v155
	v_add_f32_e32 v155, 1.0, v157
	v_mul_f32_e32 v157, 0xbfb8aa3b, v34
	v_exp_f32_e32 v157, v157
	v_add_f32_e32 v151, 1.0, v151
	v_rcp_f32_e32 v136, v136
	v_rcp_f32_e32 v151, v151
	v_add_f32_e32 v157, 1.0, v157
	v_rcp_f32_e32 v154, v154
	v_rcp_f32_e32 v157, v157
	v_add_f32_e32 v161, 1.0, v161
	v_rcp_f32_e32 v155, v155
	v_rcp_f32_e32 v161, v161
	v_mul_f32_e32 v136, v36, v136
	v_mul_f32_e32 v151, v37, v151
	v_mul_f32_e32 v173, v32, v154
	v_mul_f32_e32 v157, v34, v157
	v_cvt_pk_bf16_f32 v154, v136, v151
	v_mul_f32_e32 v174, v33, v155
	v_mul_f32_e32 v161, v35, v161
	v_cvt_pk_bf16_f32 v155, v156, v160
	v_cvt_pk_bf16_f32 v156, v173, v174
	v_cvt_pk_bf16_f32 v157, v157, v161
	global_store_dwordx4 v[158:159], v[154:157], off offset:256 nt
	v_mul_f32_e32 v136, 0xbfb8aa3b, v28
	v_mul_f32_e32 v151, 0xbfb8aa3b, v29
	v_mul_f32_e32 v154, 0xbfb8aa3b, v30
	v_exp_f32_e32 v154, v154
	v_mul_f32_e32 v155, 0xbfb8aa3b, v31
	v_exp_f32_e32 v155, v155
	v_mul_f32_e32 v157, 0xbfb8aa3b, v25
	v_add_f32_e32 v154, 1.0, v154
	v_rcp_f32_e32 v154, v154
	v_exp_f32_e32 v157, v157
	v_mul_f32_e32 v161, 0xbfb8aa3b, v27
	v_exp_f32_e32 v136, v136
	v_mul_f32_e32 v156, v30, v154
	v_add_f32_e32 v154, 1.0, v155
	v_mul_f32_e32 v155, 0xbfb8aa3b, v24
	v_rcp_f32_e32 v154, v154
	v_exp_f32_e32 v155, v155
	v_exp_f32_e32 v151, v151
	v_exp_f32_e32 v161, v161
	v_mul_f32_e32 v160, v31, v154
	v_add_f32_e32 v154, 1.0, v155
	v_add_f32_e32 v155, 1.0, v157
	v_mul_f32_e32 v157, 0xbfb8aa3b, v26
	v_exp_f32_e32 v157, v157
	v_add_f32_e32 v136, 1.0, v136
	v_add_f32_e32 v151, 1.0, v151
	v_add_f32_e32 v161, 1.0, v161
	v_add_f32_e32 v157, 1.0, v157
	v_rcp_f32_e32 v136, v136
	v_rcp_f32_e32 v151, v151
	v_rcp_f32_e32 v154, v154
	v_rcp_f32_e32 v155, v155
	v_rcp_f32_e32 v157, v157
	v_rcp_f32_e32 v161, v161
	s_mov_b64 s[8:9], 0xa0000
	v_lshl_add_u64 v[158:159], v[152:153], 0, s[8:9]
	s_mov_b32 s8, 0xa0000
	v_mul_f32_e32 v136, v28, v136
	v_mul_f32_e32 v151, v29, v151
	v_mul_f32_e32 v173, v24, v154
	v_mul_f32_e32 v174, v25, v155
	v_mul_f32_e32 v157, v26, v157
	v_mul_f32_e32 v161, v27, v161
	v_cvt_pk_bf16_f32 v154, v136, v151
	v_cvt_pk_bf16_f32 v155, v156, v160
	v_add_co_u32_e32 v160, vcc, s8, v152
	v_cvt_pk_bf16_f32 v156, v173, v174
	v_cvt_pk_bf16_f32 v157, v157, v161
	v_mul_f32_e32 v136, 0xbfb8aa3b, v20
	s_nop 0
	v_addc_co_u32_e32 v161, vcc, 0, v153, vcc
	global_store_dwordx4 v[160:161], v[154:157], off nt
	v_mul_f32_e32 v151, 0xbfb8aa3b, v21
	v_exp_f32_e32 v136, v136
	v_mul_f32_e32 v154, 0xbfb8aa3b, v22
	v_exp_f32_e32 v154, v154
	v_mul_f32_e32 v155, 0xbfb8aa3b, v23
	v_exp_f32_e32 v155, v155
	v_mul_f32_e32 v157, 0xbfb8aa3b, v17
	v_add_f32_e32 v154, 1.0, v154
	v_rcp_f32_e32 v154, v154
	v_exp_f32_e32 v157, v157
	v_exp_f32_e32 v151, v151
	v_mul_f32_e32 v161, 0xbfb8aa3b, v19
	v_mul_f32_e32 v156, v22, v154
	v_add_f32_e32 v154, 1.0, v155
	v_mul_f32_e32 v155, 0xbfb8aa3b, v16
	v_rcp_f32_e32 v154, v154
	v_exp_f32_e32 v155, v155
	v_exp_f32_e32 v161, v161
	v_add_f32_e32 v136, 1.0, v136
	v_mul_f32_e32 v160, v23, v154
	v_add_f32_e32 v154, 1.0, v155
; __device__ __forceinline__ u32x4 pack8(f32x4 v0, f32x4 v1) { u32x4 w; w.x = cvt_pk_bf16(v0[0], v0[1]); w.y = cvt_pk_bf16(v0[2], v0[3]); w.z = cvt_pk_bf16(v1[0], v1[1]); w.w = cvt_pk_bf16(v1[2], v1[3]); return w; }
; __device__ __forceinline__ f32x4 silu4(f32x4 v) { return (f32x4){silu_f(v[0]), silu_f(v[1]), silu_f(v[2]), silu_f(v[3])}; }
; __device__ __forceinline__ float silu_f(float v) { return v * __builtin_amdgcn_rcpf(1.f + __builtin_amdgcn_exp2f(-1.4426950408889634f * v)); }
;     __device__ __forceinline__ void operator()(const f32x4 (&acc)[2][2][4][2], const Unit& u, int wr, int wc, int fr, int fq) const {
;     ...
;         } else if (pn < 12) {
;             if (u.pm < ML / BM) {
;                 const int col0 = (pn - 4) * BM + wc * 32 + 8 * fq;
; #pragma unroll
;                 for (int ai = 0; ai < 2; ++ai)
; #pragma unroll
;                     for (int m = 0; m < 4; ++m) { bf16_t* rowp = SG + (size_t)(row0 + ai * HALF + m * 16) * DM + col0;
; #pragma unroll
;                         for (int bj = 0; bj < 2; ++bj) *(u32x4*)(rowp + bj * HALF) = pack8(silu4(acc[ai][bj][m][0]), silu4(acc[ai][bj][m][1])); }
;             }
	v_add_f32_e32 v155, 1.0, v157
	v_mul_f32_e32 v157, 0xbfb8aa3b, v18
	v_exp_f32_e32 v157, v157
	v_add_f32_e32 v151, 1.0, v151
	v_rcp_f32_e32 v136, v136
	v_rcp_f32_e32 v151, v151
	v_add_f32_e32 v157, 1.0, v157
	v_rcp_f32_e32 v154, v154
	v_rcp_f32_e32 v157, v157
	v_add_f32_e32 v161, 1.0, v161
	v_rcp_f32_e32 v155, v155
	v_rcp_f32_e32 v161, v161
	v_mul_f32_e32 v136, v20, v136
	v_mul_f32_e32 v151, v21, v151
	v_mul_f32_e32 v173, v16, v154
	v_mul_f32_e32 v157, v18, v157
	v_cvt_pk_bf16_f32 v154, v136, v151
	v_mul_f32_e32 v174, v17, v155
	v_mul_f32_e32 v161, v19, v161
	v_cvt_pk_bf16_f32 v155, v156, v160
	v_cvt_pk_bf16_f32 v156, v173, v174
	v_cvt_pk_bf16_f32 v157, v157, v161
	global_store_dwordx4 v[158:159], v[154:157], off offset:256 nt
	v_mul_f32_e32 v136, 0xbfb8aa3b, v12
	v_mul_f32_e32 v151, 0xbfb8aa3b, v13
	v_mul_f32_e32 v154, 0xbfb8aa3b, v14
	v_exp_f32_e32 v154, v154
	v_mul_f32_e32 v155, 0xbfb8aa3b, v15
	v_exp_f32_e32 v155, v155
	v_mul_f32_e32 v157, 0xbfb8aa3b, v9
	v_add_f32_e32 v154, 1.0, v154
	v_rcp_f32_e32 v154, v154
	v_exp_f32_e32 v157, v157
	v_mul_f32_e32 v161, 0xbfb8aa3b, v11
	v_exp_f32_e32 v136, v136
	v_mul_f32_e32 v156, v14, v154
	v_add_f32_e32 v154, 1.0, v155
	v_mul_f32_e32 v155, 0xbfb8aa3b, v8
	v_rcp_f32_e32 v154, v154
	v_exp_f32_e32 v155, v155
	v_exp_f32_e32 v151, v151
	v_exp_f32_e32 v161, v161
	v_mul_f32_e32 v160, v15, v154
	v_add_f32_e32 v154, 1.0, v155
	v_add_f32_e32 v155, 1.0, v157
	v_mul_f32_e32 v157, 0xbfb8aa3b, v10
	v_exp_f32_e32 v157, v157
	v_add_f32_e32 v136, 1.0, v136
	v_add_f32_e32 v151, 1.0, v151
	v_add_f32_e32 v161, 1.0, v161
	v_add_f32_e32 v157, 1.0, v157
	v_rcp_f32_e32 v157, v157
	s_mov_b64 s[8:9], 0xb0000
	v_rcp_f32_e32 v136, v136
	v_rcp_f32_e32 v151, v151
	v_rcp_f32_e32 v154, v154
	v_rcp_f32_e32 v155, v155
	v_rcp_f32_e32 v161, v161
	v_lshl_add_u64 v[158:159], v[152:153], 0, s[8:9]
	s_mov_b32 s8, 0xb0000
	v_add_co_u32_e32 v152, vcc, s8, v152
	v_mul_f32_e32 v157, v10, v157
	s_nop 0
	v_addc_co_u32_e32 v153, vcc, 0, v153, vcc
	v_mul_f32_e32 v136, v12, v136
	v_mul_f32_e32 v151, v13, v151
	v_mul_f32_e32 v173, v8, v154
	v_mul_f32_e32 v174, v9, v155
	v_mul_f32_e32 v161, v11, v161
	v_cvt_pk_bf16_f32 v154, v136, v151
	v_cvt_pk_bf16_f32 v155, v156, v160
	v_cvt_pk_bf16_f32 v156, v173, v174
	v_cvt_pk_bf16_f32 v157, v157, v161
	global_store_dwordx4 v[152:153], v[154:157], off nt
	v_mul_f32_e32 v152, 0xbfb8aa3b, v6
	v_exp_f32_e32 v152, v152
	v_mul_f32_e32 v153, 0xbfb8aa3b, v7
	v_exp_f32_e32 v153, v153
	v_mul_f32_e32 v155, 0xbfb8aa3b, v1
	v_add_f32_e32 v152, 1.0, v152
	v_rcp_f32_e32 v152, v152
	v_exp_f32_e32 v155, v155
	v_mul_f32_e32 v136, 0xbfb8aa3b, v4
	v_mul_f32_e32 v151, 0xbfb8aa3b, v5
	v_mul_f32_e32 v154, v6, v152
	v_add_f32_e32 v152, 1.0, v153
	v_mul_f32_e32 v153, 0xbfb8aa3b, v0
	v_rcp_f32_e32 v152, v152
	v_exp_f32_e32 v153, v153
	v_mul_f32_e32 v157, 0xbfb8aa3b, v3
	v_exp_f32_e32 v136, v136
	v_mul_f32_e32 v156, v7, v152
	v_add_f32_e32 v152, 1.0, v153
	v_add_f32_e32 v153, 1.0, v155
	v_mul_f32_e32 v155, 0xbfb8aa3b, v2
	v_exp_f32_e32 v155, v155
	v_exp_f32_e32 v151, v151
	v_exp_f32_e32 v157, v157
	v_add_f32_e32 v136, 1.0, v136
	v_add_f32_e32 v155, 1.0, v155
	v_add_f32_e32 v151, 1.0, v151
	v_rcp_f32_e32 v155, v155
	v_add_f32_e32 v157, 1.0, v157
	v_rcp_f32_e32 v136, v136
	v_rcp_f32_e32 v151, v151
	v_rcp_f32_e32 v152, v152
	v_rcp_f32_e32 v153, v153
	v_rcp_f32_e32 v157, v157
	v_mul_f32_e32 v155, v2, v155
	v_mul_f32_e32 v136, v4, v136
	v_mul_f32_e32 v151, v5, v151
	v_mul_f32_e32 v160, v0, v152
	v_mul_f32_e32 v161, v1, v153
	v_mul_f32_e32 v157, v3, v157
	v_cvt_pk_bf16_f32 v152, v136, v151
	v_cvt_pk_bf16_f32 v153, v154, v156
	v_cvt_pk_bf16_f32 v154, v160, v161
	v_cvt_pk_bf16_f32 v155, v155, v157
	global_store_dwordx4 v[158:159], v[152:155], off offset:256 nt

; __device__ __forceinline__ u32x4 pack8(f32x4 v0, f32x4 v1) { u32x4 w; w.x = cvt_pk_bf16(v0[0], v0[1]); w.y = cvt_pk_bf16(v0[2], v0[3]); w.z = cvt_pk_bf16(v1[0], v1[1]); w.w = cvt_pk_bf16(v1[2], v1[3]); return w; }
;     __device__ __forceinline__ void operator()(const f32x4 (&acc)[2][2][4][2], const Unit& u, int wr, int wc, int fr, int fq) const {
;     ...
;         if (pn < 4) {
;             bf16_t* base = pn < 2 ? CQ : CKV; float* ss = ssq + (pn < 2 ? 0 : MT);
;             const int col0 = (pn & 1) * BM + wc * 32 + 8 * fq;
; #pragma unroll
;             for (int ai = 0; ai < 2; ++ai)
; #pragma unroll
;                 for (int m = 0; m < 4; ++m) { const int row = row0 + ai * HALF + m * 16; bf16_t* rowp = base + (size_t)row * 512 + col0; float s = 0.f;
; #pragma unroll
;                     for (int bj = 0; bj < 2; ++bj) { const f32x4 v0 = acc[ai][bj][m][0], v1 = acc[ai][bj][m][1];
;                         s += (v0[0] * v0[0] + v0[1] * v0[1]) + (v0[2] * v0[2] + v0[3] * v0[3]) + (v1[0] * v1[0] + v1[1] * v1[1]) + (v1[2] * v1[2] + v1[3] * v1[3]);
;                         *(u32x4*)(rowp + bj * HALF) = pack8(v0, v1); }
;                     s += __shfl_xor(s, 16); s += __shfl_xor(s, 32);
;                     if (fq == 0) atomicAdd(ss + row, s); }
.LBB0_870:
	s_cmp_lt_i32 s52, 2
	s_cselect_b32 s8, 0, 0x12000
	s_cselect_b32 s31, s67, s64
	s_cselect_b32 s30, s66, s62
	s_add_u32 s8, s22, s8
	s_addc_u32 s9, s23, 0
	s_lshl_b32 s34, s52, 8
	s_and_b32 s34, s34, 0x100
	v_or_b32_e32 v136, s34, v164
	v_lshlrev_b32_e32 v136, 1, v136
	v_lshl_add_u64 v[152:153], s[30:31], 0, v[136:137]
	v_mul_f32_e32 v136, v125, v125
	v_mul_f32_e32 v156, v127, v127
	v_fmac_f32_e32 v136, v124, v124
	v_fmac_f32_e32 v156, v126, v126
	v_add_f32_e32 v136, v136, v156
	v_mul_f32_e32 v156, v121, v121
	v_fmac_f32_e32 v156, v120, v120
	v_cvt_pk_bf16_f32 v124, v124, v125
	v_cvt_pk_bf16_f32 v125, v126, v127
	v_cvt_pk_bf16_f32 v126, v120, v121
	v_mul_f32_e32 v120, v117, v117
	v_mul_f32_e32 v121, v119, v119
	v_fmac_f32_e32 v120, v116, v116
	v_fmac_f32_e32 v121, v118, v118
	v_add_f32_e32 v120, v120, v121
	v_mul_f32_e32 v121, v113, v113
	v_fmac_f32_e32 v121, v112, v112
	v_add_f32_e32 v136, v136, v156
	v_mul_f32_e32 v156, v123, v123
	v_add_f32_e32 v120, v120, v121
	v_mul_f32_e32 v121, v115, v115
	v_fmac_f32_e32 v156, v122, v122
	v_fmac_f32_e32 v121, v114, v114
	v_add_f32_e32 v136, v156, v136
	v_add_f32_e32 v120, v121, v120
	v_and_b32_e32 v127, 64, v172
	v_add_f32_e32 v121, v136, v120
	v_xor_b32_e32 v120, 16, v172
	v_add_u32_e32 v136, 64, v127
	v_cmp_lt_i32_e32 vcc, v120, v136
	v_ashrrev_i32_e32 v151, 31, v150
	v_lshlrev_b64 v[154:155], 10, v[150:151]
	v_cndmask_b32_e32 v120, v172, v120, vcc
	v_lshlrev_b32_e32 v120, 2, v120
	ds_bpermute_b32 v156, v120, v121
	v_lshl_add_u64 v[154:155], v[152:153], 0, v[154:155]
	v_cvt_pk_bf16_f32 v127, v122, v123
	global_store_dwordx4 v[154:155], v[124:127], off nt
	v_cvt_pk_bf16_f32 v122, v116, v117
	v_xor_b32_e32 v116, 32, v172
	v_cmp_lt_i32_e32 vcc, v116, v136
	s_waitcnt lgkmcnt(0)
	v_add_f32_e32 v117, v121, v156
	v_cvt_pk_bf16_f32 v123, v118, v119
	v_cvt_pk_bf16_f32 v124, v112, v113
	v_lshl_add_u64 v[112:113], v[150:151], 2, s[8:9]
	v_cndmask_b32_e32 v116, v172, v116, vcc
	v_lshlrev_b32_e32 v116, 2, v116
	ds_bpermute_b32 v118, v116, v117
	v_cvt_pk_bf16_f32 v125, v114, v115
	global_store_dwordx4 v[154:155], v[122:125], off offset:256 nt
	s_and_saveexec_b64 s[8:9], s[4:5]
	s_cbranch_execz .LBB0_872
	s_waitcnt lgkmcnt(0)
	v_add_f32_e32 v114, v117, v118
	global_atomic_add_f32 v[112:113], v114, off
.LBB0_872:
	s_or_b64 exec, exec, s[8:9]
	v_mul_f32_e32 v117, v109, v109
	s_waitcnt lgkmcnt(0)
	v_mul_f32_e32 v118, v111, v111
	v_fmac_f32_e32 v117, v108, v108
	v_fmac_f32_e32 v118, v110, v110
	v_cvt_pk_bf16_f32 v108, v108, v109
	v_cvt_pk_bf16_f32 v109, v110, v111
	v_mul_f32_e32 v110, v101, v101
	v_mul_f32_e32 v111, v103, v103
	v_fmac_f32_e32 v110, v100, v100
	v_fmac_f32_e32 v111, v102, v102
	v_add_f32_e32 v117, v117, v118
	v_mul_f32_e32 v118, v105, v105
	v_add_f32_e32 v110, v110, v111
	v_mul_f32_e32 v111, v97, v97
	v_fmac_f32_e32 v118, v104, v104
	v_fmac_f32_e32 v111, v96, v96
	v_add_f32_e32 v117, v117, v118
	v_mul_f32_e32 v118, v107, v107
	v_add_f32_e32 v110, v110, v111
	v_mul_f32_e32 v111, v99, v99
	v_fmac_f32_e32 v118, v106, v106
	v_fmac_f32_e32 v111, v98, v98
	v_add_f32_e32 v117, v118, v117
	v_add_f32_e32 v110, v111, v110
	v_add_f32_e32 v117, v117, v110
	ds_bpermute_b32 v118, v120, v117
	v_or_b32_e32 v114, 16, v150
	v_ashrrev_i32_e32 v115, 31, v114
	v_lshlrev_b64 v[114:115], 10, v[114:115]
	v_lshl_add_u64 v[114:115], v[152:153], 0, v[114:115]
	v_cvt_pk_bf16_f32 v110, v104, v105
	v_cvt_pk_bf16_f32 v111, v106, v107
	global_store_dwordx4 v[114:115], v[108:111], off nt
	v_cvt_pk_bf16_f32 v104, v100, v101
	s_waitcnt lgkmcnt(0)
	v_add_f32_e32 v100, v117, v118
	ds_bpermute_b32 v101, v116, v100
	v_cvt_pk_bf16_f32 v105, v102, v103
	v_cvt_pk_bf16_f32 v106, v96, v97
	v_cvt_pk_bf16_f32 v107, v98, v99
	global_store_dwordx4 v[114:115], v[104:107], off offset:256 nt
	s_and_saveexec_b64 s[8:9], s[4:5]
	s_cbranch_execz .LBB0_874
	s_waitcnt lgkmcnt(0)
	v_add_f32_e32 v96, v100, v101
	global_atomic_add_f32 v[112:113], v96, off offset:64
.LBB0_874:
	s_or_b64 exec, exec, s[8:9]
	v_mul_f32_e32 v98, v93, v93
	v_mul_f32_e32 v99, v95, v95
	v_fmac_f32_e32 v98, v92, v92
	v_fmac_f32_e32 v99, v94, v94
	v_cvt_pk_bf16_f32 v92, v92, v93
	v_cvt_pk_bf16_f32 v93, v94, v95
	v_mul_f32_e32 v94, v85, v85
	v_mul_f32_e32 v95, v87, v87
	v_fmac_f32_e32 v94, v84, v84
	v_fmac_f32_e32 v95, v86, v86
	v_add_f32_e32 v98, v98, v99
	v_mul_f32_e32 v99, v89, v89
	v_add_f32_e32 v94, v94, v95
	v_mul_f32_e32 v95, v81, v81
	v_fmac_f32_e32 v99, v88, v88
	v_fmac_f32_e32 v95, v80, v80
	v_add_f32_e32 v98, v98, v99
	v_mul_f32_e32 v99, v91, v91
	v_add_f32_e32 v94, v94, v95
	v_mul_f32_e32 v95, v83, v83
	v_fmac_f32_e32 v99, v90, v90
	v_fmac_f32_e32 v95, v82, v82
	v_add_f32_e32 v98, v99, v98
	v_add_f32_e32 v94, v95, v94
	v_add_f32_e32 v98, v98, v94
	ds_bpermute_b32 v99, v120, v98
	v_or_b32_e32 v96, 32, v150
	v_ashrrev_i32_e32 v97, 31, v96
	v_lshlrev_b64 v[96:97], 10, v[96:97]
	v_lshl_add_u64 v[96:97], v[152:153], 0, v[96:97]
	v_cvt_pk_bf16_f32 v94, v88, v89
	v_cvt_pk_bf16_f32 v95, v90, v91
	global_store_dwordx4 v[96:97], v[92:95], off nt
	v_cvt_pk_bf16_f32 v88, v84, v85
	s_waitcnt lgkmcnt(0)
	v_add_f32_e32 v84, v98, v99
	ds_bpermute_b32 v85, v116, v84
	v_cvt_pk_bf16_f32 v89, v86, v87
	v_cvt_pk_bf16_f32 v90, v80, v81
	v_cvt_pk_bf16_f32 v91, v82, v83
	global_store_dwordx4 v[96:97], v[88:91], off offset:256 nt
	s_and_saveexec_b64 s[8:9], s[4:5]
	s_cbranch_execz .LBB0_876
	s_waitcnt lgkmcnt(0)
	v_add_f32_e32 v80, v84, v85
	global_atomic_add_f32 v[112:113], v80, off offset:128
; __device__ __forceinline__ u32x4 pack8(f32x4 v0, f32x4 v1) { u32x4 w; w.x = cvt_pk_bf16(v0[0], v0[1]); w.y = cvt_pk_bf16(v0[2], v0[3]); w.z = cvt_pk_bf16(v1[0], v1[1]); w.w = cvt_pk_bf16(v1[2], v1[3]); return w; }
;     __device__ __forceinline__ void operator()(const f32x4 (&acc)[2][2][4][2], const Unit& u, int wr, int wc, int fr, int fq) const {
;     ...
;         if (pn < 4) {
;             bf16_t* base = pn < 2 ? CQ : CKV; float* ss = ssq + (pn < 2 ? 0 : MT);
;             const int col0 = (pn & 1) * BM + wc * 32 + 8 * fq;
; #pragma unroll
;             for (int ai = 0; ai < 2; ++ai)
; #pragma unroll
;                 for (int m = 0; m < 4; ++m) { const int row = row0 + ai * HALF + m * 16; bf16_t* rowp = base + (size_t)row * 512 + col0; float s = 0.f;
; #pragma unroll
;                     for (int bj = 0; bj < 2; ++bj) { const f32x4 v0 = acc[ai][bj][m][0], v1 = acc[ai][bj][m][1];
;                         s += (v0[0] * v0[0] + v0[1] * v0[1]) + (v0[2] * v0[2] + v0[3] * v0[3]) + (v1[0] * v1[0] + v1[1] * v1[1]) + (v1[2] * v1[2] + v1[3] * v1[3]);
;                         *(u32x4*)(rowp + bj * HALF) = pack8(v0, v1); }
;                     s += __shfl_xor(s, 16); s += __shfl_xor(s, 32);
;                     if (fq == 0) atomicAdd(ss + row, s); }
.LBB0_876:
	s_or_b64 exec, exec, s[8:9]
	v_mul_f32_e32 v82, v77, v77
	v_mul_f32_e32 v83, v79, v79
	v_fmac_f32_e32 v82, v76, v76
	v_fmac_f32_e32 v83, v78, v78
	v_cvt_pk_bf16_f32 v76, v76, v77
	v_cvt_pk_bf16_f32 v77, v78, v79
	v_mul_f32_e32 v78, v69, v69
	v_mul_f32_e32 v79, v71, v71
	v_fmac_f32_e32 v78, v68, v68
	v_fmac_f32_e32 v79, v70, v70
	v_add_f32_e32 v82, v82, v83
	v_mul_f32_e32 v83, v73, v73
	v_add_f32_e32 v78, v78, v79
	v_mul_f32_e32 v79, v65, v65
	v_fmac_f32_e32 v83, v72, v72
	v_fmac_f32_e32 v79, v64, v64
	v_add_f32_e32 v82, v82, v83
	v_mul_f32_e32 v83, v75, v75
	v_add_f32_e32 v78, v78, v79
	v_mul_f32_e32 v79, v67, v67
	v_fmac_f32_e32 v83, v74, v74
	v_fmac_f32_e32 v79, v66, v66
	v_add_f32_e32 v82, v83, v82
	v_add_f32_e32 v78, v79, v78
	v_add_f32_e32 v82, v82, v78
	ds_bpermute_b32 v83, v120, v82
	v_or_b32_e32 v80, 48, v150
	v_ashrrev_i32_e32 v81, 31, v80
	v_lshlrev_b64 v[80:81], 10, v[80:81]
	v_lshl_add_u64 v[80:81], v[152:153], 0, v[80:81]
	v_cvt_pk_bf16_f32 v78, v72, v73
	v_cvt_pk_bf16_f32 v79, v74, v75
	global_store_dwordx4 v[80:81], v[76:79], off nt
	v_cvt_pk_bf16_f32 v72, v68, v69
	s_waitcnt lgkmcnt(0)
	v_add_f32_e32 v68, v82, v83
	ds_bpermute_b32 v69, v116, v68
	v_cvt_pk_bf16_f32 v73, v70, v71
	v_cvt_pk_bf16_f32 v74, v64, v65
	v_cvt_pk_bf16_f32 v75, v66, v67
	global_store_dwordx4 v[80:81], v[72:75], off offset:256 nt
	s_and_saveexec_b64 s[8:9], s[4:5]
	s_cbranch_execz .LBB0_878
	s_waitcnt lgkmcnt(0)
	v_add_f32_e32 v64, v68, v69
	global_atomic_add_f32 v[112:113], v64, off offset:192
.LBB0_878:
	s_or_b64 exec, exec, s[8:9]
	v_mul_f32_e32 v68, v61, v61
	s_waitcnt lgkmcnt(0)
	v_mul_f32_e32 v69, v63, v63
	v_fmac_f32_e32 v68, v60, v60
	v_fmac_f32_e32 v69, v62, v62
	v_add_f32_e32 v68, v68, v69
	v_mul_f32_e32 v69, v57, v57
	v_fmac_f32_e32 v69, v56, v56
	v_cvt_pk_bf16_f32 v60, v60, v61
	v_cvt_pk_bf16_f32 v61, v62, v63
	v_cvt_pk_bf16_f32 v62, v56, v57
	v_mul_f32_e32 v56, v53, v53
	v_mul_f32_e32 v57, v55, v55
	v_fmac_f32_e32 v56, v52, v52
	v_fmac_f32_e32 v57, v54, v54
	v_add_f32_e32 v56, v56, v57
	v_mul_f32_e32 v57, v49, v49
	v_fmac_f32_e32 v57, v48, v48
	v_add_f32_e32 v68, v68, v69
	v_mul_f32_e32 v69, v59, v59
	v_add_f32_e32 v56, v56, v57
	v_mul_f32_e32 v57, v51, v51
	v_fmac_f32_e32 v69, v58, v58
	v_fmac_f32_e32 v57, v50, v50
	v_add_f32_e32 v68, v69, v68
	v_add_f32_e32 v56, v57, v56
	v_cvt_pk_bf16_f32 v63, v58, v59
	v_add_f32_e32 v58, v68, v56
	v_lshlrev_b64 v[64:65], 10, v[150:151]
	ds_bpermute_b32 v59, v120, v58
	v_lshl_add_u64 v[64:65], v[152:153], 0, v[64:65]
	s_mov_b64 s[8:9], 0x20000
	v_lshl_add_u64 v[66:67], v[64:65], 0, s[8:9]
	s_mov_b32 s8, 0x20000
	v_add_co_u32_e32 v56, vcc, s8, v64
	s_nop 1
	v_addc_co_u32_e32 v57, vcc, 0, v65, vcc
	global_store_dwordx4 v[56:57], v[60:63], off nt
	v_cvt_pk_bf16_f32 v56, v52, v53
	s_waitcnt lgkmcnt(0)
	v_add_f32_e32 v52, v58, v59
	ds_bpermute_b32 v53, v116, v52
	v_cvt_pk_bf16_f32 v57, v54, v55
	v_cvt_pk_bf16_f32 v58, v48, v49
	v_cvt_pk_bf16_f32 v59, v50, v51
	global_store_dwordx4 v[66:67], v[56:59], off offset:256 nt
	s_and_saveexec_b64 s[8:9], s[4:5]
	s_cbranch_execz .LBB0_880
	s_waitcnt lgkmcnt(0)
	v_add_f32_e32 v48, v52, v53
	global_atomic_add_f32 v[112:113], v48, off offset:512
; __device__ __forceinline__ u32x4 pack8(f32x4 v0, f32x4 v1) { u32x4 w; w.x = cvt_pk_bf16(v0[0], v0[1]); w.y = cvt_pk_bf16(v0[2], v0[3]); w.z = cvt_pk_bf16(v1[0], v1[1]); w.w = cvt_pk_bf16(v1[2], v1[3]); return w; }
;     __device__ __forceinline__ void operator()(const f32x4 (&acc)[2][2][4][2], const Unit& u, int wr, int wc, int fr, int fq) const {
;     ...
;         if (pn < 4) {
;             bf16_t* base = pn < 2 ? CQ : CKV; float* ss = ssq + (pn < 2 ? 0 : MT);
;             const int col0 = (pn & 1) * BM + wc * 32 + 8 * fq;
; #pragma unroll
;             for (int ai = 0; ai < 2; ++ai)
; #pragma unroll
;                 for (int m = 0; m < 4; ++m) { const int row = row0 + ai * HALF + m * 16; bf16_t* rowp = base + (size_t)row * 512 + col0; float s = 0.f;
; #pragma unroll
;                     for (int bj = 0; bj < 2; ++bj) { const f32x4 v0 = acc[ai][bj][m][0], v1 = acc[ai][bj][m][1];
;                         s += (v0[0] * v0[0] + v0[1] * v0[1]) + (v0[2] * v0[2] + v0[3] * v0[3]) + (v1[0] * v1[0] + v1[1] * v1[1]) + (v1[2] * v1[2] + v1[3] * v1[3]);
;                         *(u32x4*)(rowp + bj * HALF) = pack8(v0, v1); }
;                     s += __shfl_xor(s, 16); s += __shfl_xor(s, 32);
;                     if (fq == 0) atomicAdd(ss + row, s); }
.LBB0_880:
	s_or_b64 exec, exec, s[8:9]
	v_mul_f32_e32 v50, v45, v45
	v_mul_f32_e32 v51, v47, v47
	v_fmac_f32_e32 v50, v44, v44
	v_fmac_f32_e32 v51, v46, v46
	v_add_f32_e32 v50, v50, v51
	v_mul_f32_e32 v51, v41, v41
	v_fmac_f32_e32 v51, v40, v40
	v_cvt_pk_bf16_f32 v44, v44, v45
	v_cvt_pk_bf16_f32 v45, v46, v47
	v_cvt_pk_bf16_f32 v46, v40, v41
	v_mul_f32_e32 v40, v37, v37
	v_mul_f32_e32 v41, v39, v39
	v_fmac_f32_e32 v40, v36, v36
	v_fmac_f32_e32 v41, v38, v38
	v_add_f32_e32 v40, v40, v41
	v_mul_f32_e32 v41, v33, v33
	v_fmac_f32_e32 v41, v32, v32
	v_add_f32_e32 v50, v50, v51
	v_mul_f32_e32 v51, v43, v43
	v_add_f32_e32 v40, v40, v41
	v_mul_f32_e32 v41, v35, v35
	v_fmac_f32_e32 v51, v42, v42
	v_fmac_f32_e32 v41, v34, v34
	v_add_f32_e32 v50, v51, v50
	v_add_f32_e32 v40, v41, v40
	v_cvt_pk_bf16_f32 v47, v42, v43
	v_add_f32_e32 v42, v50, v40
	ds_bpermute_b32 v43, v120, v42
	s_mov_b64 s[8:9], 0x24000
	v_lshl_add_u64 v[48:49], v[64:65], 0, s[8:9]
	s_mov_b32 s8, 0x24000
	v_add_co_u32_e32 v40, vcc, s8, v64
	s_nop 1
	v_addc_co_u32_e32 v41, vcc, 0, v65, vcc
	global_store_dwordx4 v[40:41], v[44:47], off nt
	v_cvt_pk_bf16_f32 v40, v36, v37
	s_waitcnt lgkmcnt(0)
	v_add_f32_e32 v36, v42, v43
	ds_bpermute_b32 v37, v116, v36
	v_cvt_pk_bf16_f32 v41, v38, v39
	v_cvt_pk_bf16_f32 v42, v32, v33
	v_cvt_pk_bf16_f32 v43, v34, v35
	global_store_dwordx4 v[48:49], v[40:43], off offset:256 nt
	s_and_saveexec_b64 s[8:9], s[4:5]
	s_cbranch_execz .LBB0_882
	s_waitcnt lgkmcnt(0)
	v_add_f32_e32 v32, v36, v37
	global_atomic_add_f32 v[112:113], v32, off offset:576
.LBB0_882:
	s_or_b64 exec, exec, s[8:9]
	v_mul_f32_e32 v36, v29, v29
	s_waitcnt lgkmcnt(0)
	v_mul_f32_e32 v37, v31, v31
	v_fmac_f32_e32 v36, v28, v28
	v_fmac_f32_e32 v37, v30, v30
	v_add_f32_e32 v36, v36, v37
	v_mul_f32_e32 v37, v25, v25
	v_fmac_f32_e32 v37, v24, v24
	v_cvt_pk_bf16_f32 v28, v28, v29
	v_cvt_pk_bf16_f32 v29, v30, v31
	v_cvt_pk_bf16_f32 v30, v24, v25
	v_mul_f32_e32 v24, v21, v21
	v_mul_f32_e32 v25, v23, v23
	v_fmac_f32_e32 v24, v20, v20
	v_fmac_f32_e32 v25, v22, v22
	v_add_f32_e32 v24, v24, v25
	v_mul_f32_e32 v25, v17, v17
	v_fmac_f32_e32 v25, v16, v16
	v_add_f32_e32 v36, v36, v37
	v_mul_f32_e32 v37, v27, v27
	v_add_f32_e32 v24, v24, v25
	v_mul_f32_e32 v25, v19, v19
	v_fmac_f32_e32 v37, v26, v26
	v_fmac_f32_e32 v25, v18, v18
	v_add_f32_e32 v36, v37, v36
	v_add_f32_e32 v24, v25, v24
	v_cvt_pk_bf16_f32 v31, v26, v27
	v_add_f32_e32 v26, v36, v24
	ds_bpermute_b32 v27, v120, v26
	v_lshlrev_b64 v[32:33], 10, v[150:151]
	v_lshl_add_u64 v[32:33], v[152:153], 0, v[32:33]
	v_add_co_u32_e32 v24, vcc, s73, v32
	s_mov_b64 s[8:9], 0x28000
	s_nop 0
	v_addc_co_u32_e32 v25, vcc, 0, v33, vcc
	global_store_dwordx4 v[24:25], v[28:31], off nt
	v_cvt_pk_bf16_f32 v24, v20, v21
	s_waitcnt lgkmcnt(0)
	v_add_f32_e32 v20, v26, v27
	ds_bpermute_b32 v21, v116, v20
	v_lshl_add_u64 v[34:35], v[32:33], 0, s[8:9]
	v_cvt_pk_bf16_f32 v25, v22, v23
	v_cvt_pk_bf16_f32 v26, v16, v17
	v_cvt_pk_bf16_f32 v27, v18, v19
	global_store_dwordx4 v[34:35], v[24:27], off offset:256 nt
	s_and_saveexec_b64 s[8:9], s[4:5]
	s_cbranch_execz .LBB0_884
	s_waitcnt lgkmcnt(0)
	v_add_f32_e32 v16, v20, v21
	global_atomic_add_f32 v[112:113], v16, off offset:640
.LBB0_884:
	s_or_b64 exec, exec, s[8:9]
	v_mul_f32_e32 v18, v13, v13
	v_mul_f32_e32 v19, v15, v15
	v_fmac_f32_e32 v18, v12, v12
	v_fmac_f32_e32 v19, v14, v14
	v_add_f32_e32 v18, v18, v19
	v_mul_f32_e32 v19, v9, v9
	v_fmac_f32_e32 v19, v8, v8
	v_cvt_pk_bf16_f32 v12, v12, v13
	v_cvt_pk_bf16_f32 v13, v14, v15
	v_cvt_pk_bf16_f32 v14, v8, v9
	v_mul_f32_e32 v8, v5, v5
	v_mul_f32_e32 v9, v7, v7
	v_fmac_f32_e32 v8, v4, v4
	v_fmac_f32_e32 v9, v6, v6
	v_add_f32_e32 v8, v8, v9
	v_mul_f32_e32 v9, v1, v1
	v_fmac_f32_e32 v9, v0, v0
	v_add_f32_e32 v18, v18, v19
	v_mul_f32_e32 v19, v11, v11
	v_add_f32_e32 v8, v8, v9
	v_mul_f32_e32 v9, v3, v3
	v_fmac_f32_e32 v19, v10, v10
	v_fmac_f32_e32 v9, v2, v2
	v_add_f32_e32 v18, v19, v18
	v_add_f32_e32 v8, v9, v8
	v_cvt_pk_bf16_f32 v15, v10, v11
	v_add_f32_e32 v10, v18, v8
	ds_bpermute_b32 v11, v120, v10
	v_add_co_u32_e32 v8, vcc, s74, v32
	v_lshl_add_u64 v[16:17], v[32:33], 0, s[40:41]
	s_nop 0
	v_addc_co_u32_e32 v9, vcc, 0, v33, vcc
	global_store_dwordx4 v[8:9], v[12:15], off nt
	v_cvt_pk_bf16_f32 v8, v4, v5
	s_waitcnt lgkmcnt(0)
	v_add_f32_e32 v4, v10, v11
	ds_bpermute_b32 v5, v116, v4
	v_cvt_pk_bf16_f32 v9, v6, v7
	v_cvt_pk_bf16_f32 v10, v0, v1
	v_cvt_pk_bf16_f32 v11, v2, v3
	global_store_dwordx4 v[16:17], v[8:11], off offset:256 nt
	s_and_saveexec_b64 s[8:9], s[4:5]
	s_cbranch_execz .LBB0_886
	s_waitcnt lgkmcnt(0)
	v_add_f32_e32 v0, v4, v5
	global_atomic_add_f32 v[112:113], v0, off offset:704

; __device__ __forceinline__ u32x4 pack8(f32x4 v0, f32x4 v1) { u32x4 w; w.x = cvt_pk_bf16(v0[0], v0[1]); w.y = cvt_pk_bf16(v0[2], v0[3]); w.z = cvt_pk_bf16(v1[0], v1[1]); w.w = cvt_pk_bf16(v1[2], v1[3]); return w; }
;     __device__ __forceinline__ void operator()(const f32x4 (&acc)[2][2][4][2], const Unit& u, int wr, int wc, int fr, int fq) const {
;         const int row0 = u.pm * BM + wr * 64 + fr; const bool first = fq < 2;
; #pragma unroll
;         for (int ai = 0; ai < 2; ++ai)
; #pragma unroll
;             for (int m = 0; m < 4; ++m) { const int row = row0 + ai * HALF + m * 16; const float rs = __builtin_amdgcn_rsqf(ssq[row] * (1.f / 512.f) + EPS) * QSCALE; const int t = row & (SEQ - 1);
; #pragma unroll
;                 for (int bj = 0; bj < 2; ++bj) { const int gcol = u.pn * 8 + bj * 4 + wc, hg = gcol % 6;
;                     f32x4 v0 = acc[ai][bj][m][0] * rs, v1 = acc[ai][bj][m][1] * rs;
;                     if (hg >= 4) { const int pos = hg == 4 ? (t >> 6) : (t & 63); const f32x2* tp = tab + pos * 16 + 8 * (fq & 1);
;                         f32x4 p0, p1;
; #pragma unroll
;                         for (int j = 0; j < 4; ++j) { p0[j] = __shfl_xor(v0[j], 32); p1[j] = __shfl_xor(v1[j], 32); }
; #pragma unroll
;                         for (int j = 0; j < 4; ++j) { const f32x2 c0 = tp[j], c1 = tp[4 + j];
;                             v0[j] = first ? (v0[j] * c0.x - p0[j] * c0.y) : (p0[j] * c0.y + v0[j] * c0.x);
;                             v1[j] = first ? (v1[j] * c1.x - p1[j] * c1.y) : (p1[j] * c1.y + v1[j] * c1.x); } }
;                     *(u32x4*)(Q + (size_t)row * 3072 + gcol * 32 + 8 * fq) = pack8(v0, v1); } }
;     }
.LBB0_957:
	v_cvt_pk_bf16_f32 v124, v124, v125
	v_cvt_pk_bf16_f32 v125, v126, v127
	v_cvt_pk_bf16_f32 v126, v120, v121
	v_mov_b64_e32 v[120:121], s[16:17]
	s_lshl_b32 s44, s4, 5
	s_or_b32 s4, s4, 4
	v_mad_i64_i32 v[120:121], s[30:31], v148, s71, v[120:121]
	s_mul_hi_i32 s5, s4, 0x2aaaaaab
	s_lshr_b32 s30, s5, 31
	s_ashr_i32 s45, s44, 31
	s_add_i32 s5, s5, s30
	v_cvt_pk_bf16_f32 v127, v122, v123
	v_lshl_add_u64 v[122:123], s[44:45], 1, v[120:121]
	s_mul_i32 s5, s5, 6
	v_lshl_add_u64 v[122:123], v[122:123], 0, v[136:137]
	s_sub_i32 s35, s4, s5
	v_mov_b32_e32 v153, v152
	global_store_dwordx4 v[122:123], v[124:127], off nt
	v_mov_b32_e32 v122, v152
	v_mov_b32_e32 v123, v152
	s_cmp_gt_i32 s35, 3
	v_pk_mul_f32 v[118:119], v[118:119], v[122:123]
	v_pk_mul_f32 v[116:117], v[116:117], v[152:153]
	v_pk_mul_f32 v[114:115], v[114:115], v[122:123]
	s_cselect_b64 s[30:31], -1, 0
	s_cmp_lt_i32 s35, 4
	v_pk_mul_f32 v[112:113], v[112:113], v[152:153]
	s_cbranch_scc1 .LBB0_959
	s_cmp_eq_u32 s35, 4
	v_mov_b32_e32 v122, s37
	s_cselect_b64 vcc, -1, 0
	v_cndmask_b32_e32 v122, v160, v122, vcc
	v_lshlrev_b32_e32 v122, 7, v122
	v_mov_b32_e32 v123, v137
	v_lshl_add_u64 v[126:127], v[138:139], 0, v[122:123]
	global_load_dwordx4 v[122:125], v[126:127], off
	global_load_dwordx4 v[172:175], v[126:127], off offset:32
	global_load_dwordx4 v[176:179], v[126:127], off offset:16
	global_load_dwordx4 v[180:183], v[126:127], off offset:48
	v_and_b32_e32 v127, 64, v170
	v_xor_b32_e32 v126, 32, v170
	v_add_u32_e32 v127, 64, v127
	v_cmp_lt_i32_e32 vcc, v126, v127
	s_waitcnt vmcnt(3)
	v_mov_b32_e32 v189, v124
	v_cndmask_b32_e32 v126, v170, v126, vcc
	v_lshlrev_b32_e32 v149, 2, v126
	ds_bpermute_b32 v126, v149, v116
	ds_bpermute_b32 v152, v149, v112
	ds_bpermute_b32 v127, v149, v117
	ds_bpermute_b32 v153, v149, v113
	ds_bpermute_b32 v184, v149, v118
	ds_bpermute_b32 v186, v149, v114
	ds_bpermute_b32 v185, v149, v119
	ds_bpermute_b32 v187, v149, v115
	v_mov_b32_e32 v124, v123
	s_waitcnt vmcnt(2)
	v_mov_b32_e32 v123, v174
	v_mov_b32_e32 v174, v173
	s_waitcnt vmcnt(1)
	v_mov_b32_e32 v173, v178
	v_mov_b32_e32 v178, v177
	s_waitcnt vmcnt(0)
	v_mov_b32_e32 v177, v182
	v_mov_b32_e32 v182, v181
	s_waitcnt lgkmcnt(5)
	v_pk_mul_f32 v[124:125], v[124:125], v[126:127]
	s_waitcnt lgkmcnt(4)
	v_pk_mul_f32 v[126:127], v[174:175], v[152:153]
	s_waitcnt lgkmcnt(1)
	v_pk_mul_f32 v[152:153], v[178:179], v[184:185]
	s_waitcnt lgkmcnt(0)
	v_pk_mul_f32 v[174:175], v[182:183], v[186:187]
	v_mov_b32_e32 v188, v122
	v_mov_b32_e32 v122, v172
	v_mov_b32_e32 v172, v176
	v_mov_b32_e32 v176, v180
	v_cndmask_b32_e64 v125, v125, -v125, s[0:1]
	v_cndmask_b32_e64 v124, v124, -v124, s[0:1]
	v_cndmask_b32_e64 v127, v127, -v127, s[0:1]
	v_cndmask_b32_e64 v126, v126, -v126, s[0:1]
	v_cndmask_b32_e64 v153, v153, -v153, s[0:1]
	v_cndmask_b32_e64 v152, v152, -v152, s[0:1]
	v_cndmask_b32_e64 v175, v175, -v175, s[0:1]
	v_cndmask_b32_e64 v174, v174, -v174, s[0:1]
	v_pk_fma_f32 v[116:117], v[116:117], v[188:189], v[124:125]
	v_pk_fma_f32 v[112:113], v[112:113], v[122:123], v[126:127]
	v_pk_fma_f32 v[118:119], v[118:119], v[172:173], v[152:153]
	v_pk_fma_f32 v[114:115], v[114:115], v[176:177], v[174:175]
.LBB0_959:
	s_lshl_b32 s46, s4, 5
	s_ashr_i32 s47, s46, 31
	v_cvt_pk_bf16_f32 v116, v116, v117
	v_cvt_pk_bf16_f32 v117, v118, v119
	v_cvt_pk_bf16_f32 v118, v112, v113
	v_lshl_add_u64 v[112:113], s[46:47], 1, v[120:121]
	v_lshl_add_u64 v[112:113], v[112:113], 0, v[136:137]
	v_cvt_pk_bf16_f32 v119, v114, v115
	global_store_dwordx4 v[112:113], v[116:119], off nt
	v_or_b32_e32 v112, 16, v148
	v_ashrrev_i32_e32 v113, 31, v112
	v_lshl_add_u64 v[114:115], v[112:113], 2, s[22:23]
	global_load_dword v113, v[114:115], off
	v_cndmask_b32_e64 v114, 0, 1, s[6:7]
	v_cmp_ne_u32_e64 s[4:5], 1, v114
	s_andn2_b64 vcc, exec, s[6:7]
	s_waitcnt vmcnt(0)
	v_fmamk_f32 v113, v113, 0x3b000000, v169
	v_rsq_f32_e32 v113, v113
	s_nop 0
	v_mul_f32_e32 v114, 0x3dd53b94, v113
	v_pk_mul_f32 v[110:111], v[110:111], v[114:115] op_sel_hi:[1,0]
	v_pk_mul_f32 v[108:109], v[108:109], v[114:115] op_sel_hi:[1,0]
	v_pk_mul_f32 v[106:107], v[106:107], v[114:115] op_sel_hi:[1,0]
	v_pk_mul_f32 v[104:105], v[104:105], v[114:115] op_sel_hi:[1,0]
	s_cbranch_vccnz .LBB0_961
	s_cmp_eq_u32 s34, 4
	v_mov_b32_e32 v113, s37
	s_cselect_b64 vcc, -1, 0
	v_cndmask_b32_e32 v113, v163, v113, vcc
	v_lshlrev_b32_e32 v116, 7, v113
	v_mov_b32_e32 v117, v137
	v_lshl_add_u64 v[152:153], v[138:139], 0, v[116:117]
	global_load_dwordx4 v[116:119], v[152:153], off
	global_load_dwordx4 v[120:123], v[152:153], off offset:32
	global_load_dwordx4 v[124:127], v[152:153], off offset:16
	global_load_dwordx4 v[172:175], v[152:153], off offset:48
	v_and_b32_e32 v115, 64, v170
	v_xor_b32_e32 v113, 32, v170
	v_add_u32_e32 v115, 64, v115
	v_cmp_lt_i32_e32 vcc, v113, v115
	s_waitcnt vmcnt(3)
	v_mov_b32_e32 v183, v118
	v_cndmask_b32_e32 v113, v170, v113, vcc
	v_lshlrev_b32_e32 v113, 2, v113
	ds_bpermute_b32 v152, v113, v108
	ds_bpermute_b32 v176, v113, v104
	ds_bpermute_b32 v153, v113, v109
	ds_bpermute_b32 v177, v113, v105
	ds_bpermute_b32 v178, v113, v110
	ds_bpermute_b32 v180, v113, v106
	ds_bpermute_b32 v179, v113, v111
	ds_bpermute_b32 v181, v113, v107
	v_mov_b32_e32 v118, v117
	s_waitcnt vmcnt(2)
	v_mov_b32_e32 v117, v122
	v_mov_b32_e32 v122, v121
	s_waitcnt vmcnt(1)
	v_mov_b32_e32 v121, v126
	v_mov_b32_e32 v126, v125
	s_waitcnt vmcnt(0)
	v_mov_b32_e32 v125, v174
	v_mov_b32_e32 v174, v173
	s_waitcnt lgkmcnt(5)
	v_pk_mul_f32 v[118:119], v[118:119], v[152:153]
	s_waitcnt lgkmcnt(4)
	v_pk_mul_f32 v[122:123], v[122:123], v[176:177]
	s_waitcnt lgkmcnt(1)
	v_pk_mul_f32 v[126:127], v[126:127], v[178:179]
	s_waitcnt lgkmcnt(0)
	v_pk_mul_f32 v[152:153], v[174:175], v[180:181]
	v_mov_b32_e32 v182, v116
	v_mov_b32_e32 v116, v120
	v_mov_b32_e32 v120, v124
	v_mov_b32_e32 v124, v172
	v_cndmask_b32_e64 v119, v119, -v119, s[0:1]
	v_cndmask_b32_e64 v118, v118, -v118, s[0:1]
	v_cndmask_b32_e64 v123, v123, -v123, s[0:1]
	v_cndmask_b32_e64 v122, v122, -v122, s[0:1]
	v_cndmask_b32_e64 v127, v127, -v127, s[0:1]
	v_cndmask_b32_e64 v126, v126, -v126, s[0:1]
	v_cndmask_b32_e64 v153, v153, -v153, s[0:1]
	v_cndmask_b32_e64 v152, v152, -v152, s[0:1]
	v_pk_fma_f32 v[108:109], v[108:109], v[182:183], v[118:119]
	v_pk_fma_f32 v[104:105], v[104:105], v[116:117], v[122:123]
	v_pk_fma_f32 v[110:111], v[110:111], v[120:121], v[126:127]
	v_pk_fma_f32 v[106:107], v[106:107], v[124:125], v[152:153]
; __device__ __forceinline__ u32x4 pack8(f32x4 v0, f32x4 v1) { u32x4 w; w.x = cvt_pk_bf16(v0[0], v0[1]); w.y = cvt_pk_bf16(v0[2], v0[3]); w.z = cvt_pk_bf16(v1[0], v1[1]); w.w = cvt_pk_bf16(v1[2], v1[3]); return w; }
;     __device__ __forceinline__ void operator()(const f32x4 (&acc)[2][2][4][2], const Unit& u, int wr, int wc, int fr, int fq) const {
;         const int row0 = u.pm * BM + wr * 64 + fr; const bool first = fq < 2;
; #pragma unroll
;         for (int ai = 0; ai < 2; ++ai)
; #pragma unroll
;             for (int m = 0; m < 4; ++m) { const int row = row0 + ai * HALF + m * 16; const float rs = __builtin_amdgcn_rsqf(ssq[row] * (1.f / 512.f) + EPS) * QSCALE; const int t = row & (SEQ - 1);
; #pragma unroll
;                 for (int bj = 0; bj < 2; ++bj) { const int gcol = u.pn * 8 + bj * 4 + wc, hg = gcol % 6;
;                     f32x4 v0 = acc[ai][bj][m][0] * rs, v1 = acc[ai][bj][m][1] * rs;
;                     if (hg >= 4) { const int pos = hg == 4 ? (t >> 6) : (t & 63); const f32x2* tp = tab + pos * 16 + 8 * (fq & 1);
;                         f32x4 p0, p1;
; #pragma unroll
;                         for (int j = 0; j < 4; ++j) { p0[j] = __shfl_xor(v0[j], 32); p1[j] = __shfl_xor(v1[j], 32); }
; #pragma unroll
;                         for (int j = 0; j < 4; ++j) { const f32x2 c0 = tp[j], c1 = tp[4 + j];
;                             v0[j] = first ? (v0[j] * c0.x - p0[j] * c0.y) : (p0[j] * c0.y + v0[j] * c0.x);
;                             v1[j] = first ? (v1[j] * c1.x - p1[j] * c1.y) : (p1[j] * c1.y + v1[j] * c1.x); } }
;                     *(u32x4*)(Q + (size_t)row * 3072 + gcol * 32 + 8 * fq) = pack8(v0, v1); } }
;     }
.LBB0_961:
	v_cvt_pk_bf16_f32 v108, v108, v109
	v_cvt_pk_bf16_f32 v109, v110, v111
	v_cvt_pk_bf16_f32 v110, v104, v105
	v_mov_b64_e32 v[104:105], s[16:17]
	v_mad_i64_i32 v[104:105], s[6:7], v112, s71, v[104:105]
	v_cvt_pk_bf16_f32 v111, v106, v107
	v_lshl_add_u64 v[106:107], s[44:45], 1, v[104:105]
	v_lshl_add_u64 v[106:107], v[106:107], 0, v[136:137]
	global_store_dwordx4 v[106:107], v[108:111], off nt
	v_mov_b32_e32 v106, v114
	v_mov_b32_e32 v107, v114
	v_mov_b32_e32 v115, v114
	v_pk_mul_f32 v[102:103], v[102:103], v[106:107]
	v_pk_mul_f32 v[98:99], v[98:99], v[106:107]
	v_cndmask_b32_e64 v106, 0, 1, s[30:31]
	v_pk_mul_f32 v[100:101], v[100:101], v[114:115]
	v_cmp_ne_u32_e64 s[6:7], 1, v106
	s_andn2_b64 vcc, exec, s[30:31]
	v_pk_mul_f32 v[96:97], v[96:97], v[114:115]
	s_cbranch_vccnz .LBB0_963
	s_cmp_eq_u32 s35, 4
	v_mov_b32_e32 v106, s37
	s_cselect_b64 vcc, -1, 0
	v_cndmask_b32_e32 v106, v163, v106, vcc
	v_lshlrev_b32_e32 v106, 7, v106
	v_mov_b32_e32 v107, v137
	v_lshl_add_u64 v[118:119], v[138:139], 0, v[106:107]
	global_load_dwordx4 v[106:109], v[118:119], off
	global_load_dwordx4 v[110:113], v[118:119], off offset:32
	global_load_dwordx4 v[114:117], v[118:119], off offset:16
	s_nop 0
	global_load_dwordx4 v[118:121], v[118:119], off offset:48
	v_and_b32_e32 v123, 64, v170
	v_xor_b32_e32 v122, 32, v170
	v_add_u32_e32 v123, 64, v123
	v_cmp_lt_i32_e32 vcc, v122, v123
	s_waitcnt vmcnt(3)
	v_mov_b32_e32 v173, v108
	v_cndmask_b32_e32 v122, v170, v122, vcc
	v_lshlrev_b32_e32 v149, 2, v122
	ds_bpermute_b32 v122, v149, v100
	ds_bpermute_b32 v124, v149, v96
	ds_bpermute_b32 v123, v149, v101
	ds_bpermute_b32 v125, v149, v97
	ds_bpermute_b32 v126, v149, v102
	ds_bpermute_b32 v152, v149, v98
	ds_bpermute_b32 v127, v149, v103
	ds_bpermute_b32 v153, v149, v99
	v_mov_b32_e32 v108, v107
	s_waitcnt vmcnt(2)
	v_mov_b32_e32 v107, v112
	v_mov_b32_e32 v112, v111
	s_waitcnt vmcnt(1)
	v_mov_b32_e32 v111, v116
	v_mov_b32_e32 v116, v115
	s_waitcnt vmcnt(0)
	v_mov_b32_e32 v115, v120
	v_mov_b32_e32 v120, v119
	v_mov_b32_e32 v172, v106
	v_mov_b32_e32 v106, v110
	v_mov_b32_e32 v110, v114
	v_mov_b32_e32 v114, v118
	s_waitcnt lgkmcnt(5)
	v_pk_mul_f32 v[108:109], v[108:109], v[122:123]
	s_waitcnt lgkmcnt(4)
	v_pk_mul_f32 v[112:113], v[112:113], v[124:125]
	s_waitcnt lgkmcnt(1)
	v_pk_mul_f32 v[116:117], v[116:117], v[126:127]
	s_waitcnt lgkmcnt(0)
	v_pk_mul_f32 v[118:119], v[120:121], v[152:153]
	v_cndmask_b32_e64 v109, v109, -v109, s[0:1]
	v_cndmask_b32_e64 v108, v108, -v108, s[0:1]
	v_cndmask_b32_e64 v113, v113, -v113, s[0:1]
	v_cndmask_b32_e64 v112, v112, -v112, s[0:1]
	v_cndmask_b32_e64 v117, v117, -v117, s[0:1]
	v_cndmask_b32_e64 v116, v116, -v116, s[0:1]
	v_cndmask_b32_e64 v119, v119, -v119, s[0:1]
	v_cndmask_b32_e64 v118, v118, -v118, s[0:1]
	v_pk_fma_f32 v[100:101], v[100:101], v[172:173], v[108:109]
	v_pk_fma_f32 v[96:97], v[96:97], v[106:107], v[112:113]
	v_pk_fma_f32 v[102:103], v[102:103], v[110:111], v[116:117]
	v_pk_fma_f32 v[98:99], v[98:99], v[114:115], v[118:119]
.LBB0_963:
	v_cvt_pk_bf16_f32 v100, v100, v101
	v_cvt_pk_bf16_f32 v101, v102, v103
	v_cvt_pk_bf16_f32 v102, v96, v97
	v_lshl_add_u64 v[96:97], s[46:47], 1, v[104:105]
	v_lshl_add_u64 v[96:97], v[96:97], 0, v[136:137]
	v_cvt_pk_bf16_f32 v103, v98, v99
	global_store_dwordx4 v[96:97], v[100:103], off nt
	v_or_b32_e32 v96, 32, v148
	v_ashrrev_i32_e32 v97, 31, v96
	v_lshl_add_u64 v[98:99], v[96:97], 2, s[22:23]
	global_load_dword v97, v[98:99], off
	s_and_b64 vcc, exec, s[4:5]
	s_waitcnt vmcnt(0)
	v_fmamk_f32 v97, v97, 0x3b000000, v169
	v_rsq_f32_e32 v97, v97
	s_nop 0
	v_mul_f32_e32 v98, 0x3dd53b94, v97
	v_pk_mul_f32 v[94:95], v[94:95], v[98:99] op_sel_hi:[1,0]
	v_pk_mul_f32 v[92:93], v[92:93], v[98:99] op_sel_hi:[1,0]
	v_pk_mul_f32 v[90:91], v[90:91], v[98:99] op_sel_hi:[1,0]
	v_pk_mul_f32 v[88:89], v[88:89], v[98:99] op_sel_hi:[1,0]
	s_cbranch_vccnz .LBB0_965
	s_cmp_eq_u32 s34, 4
	v_mov_b32_e32 v97, s37
	s_cselect_b64 vcc, -1, 0
	v_cndmask_b32_e32 v97, v164, v97, vcc
	v_lshlrev_b32_e32 v100, 7, v97
	v_mov_b32_e32 v101, v137
	v_lshl_add_u64 v[112:113], v[138:139], 0, v[100:101]
	global_load_dwordx4 v[100:103], v[112:113], off
	global_load_dwordx4 v[104:107], v[112:113], off offset:32
	global_load_dwordx4 v[108:111], v[112:113], off offset:16
	s_nop 0
	global_load_dwordx4 v[112:115], v[112:113], off offset:48
	v_and_b32_e32 v99, 64, v170
	v_xor_b32_e32 v97, 32, v170
	v_add_u32_e32 v99, 64, v99
	v_cmp_lt_i32_e32 vcc, v97, v99
	s_waitcnt vmcnt(3)
	v_mov_b32_e32 v125, v102
	v_cndmask_b32_e32 v97, v170, v97, vcc
	v_lshlrev_b32_e32 v97, 2, v97
	ds_bpermute_b32 v116, v97, v92
	ds_bpermute_b32 v118, v97, v88
	ds_bpermute_b32 v117, v97, v93
	ds_bpermute_b32 v119, v97, v89
	ds_bpermute_b32 v120, v97, v94
	ds_bpermute_b32 v122, v97, v90
	ds_bpermute_b32 v121, v97, v95
	ds_bpermute_b32 v123, v97, v91
	v_mov_b32_e32 v102, v101
	s_waitcnt vmcnt(2)
	v_mov_b32_e32 v101, v106
	v_mov_b32_e32 v106, v105
	s_waitcnt vmcnt(1)
	v_mov_b32_e32 v105, v110
	v_mov_b32_e32 v110, v109
	s_waitcnt vmcnt(0)
	v_mov_b32_e32 v109, v114
	v_mov_b32_e32 v114, v113
	v_mov_b32_e32 v124, v100
	v_mov_b32_e32 v100, v104
	v_mov_b32_e32 v104, v108
	v_mov_b32_e32 v108, v112
	s_waitcnt lgkmcnt(5)
	v_pk_mul_f32 v[102:103], v[102:103], v[116:117]
	s_waitcnt lgkmcnt(4)
	v_pk_mul_f32 v[106:107], v[106:107], v[118:119]
	s_waitcnt lgkmcnt(1)
	v_pk_mul_f32 v[110:111], v[110:111], v[120:121]
	s_waitcnt lgkmcnt(0)
	v_pk_mul_f32 v[112:113], v[114:115], v[122:123]
	v_cndmask_b32_e64 v103, v103, -v103, s[0:1]
	v_cndmask_b32_e64 v102, v102, -v102, s[0:1]
	v_cndmask_b32_e64 v107, v107, -v107, s[0:1]
	v_cndmask_b32_e64 v106, v106, -v106, s[0:1]
	v_cndmask_b32_e64 v111, v111, -v111, s[0:1]
	v_cndmask_b32_e64 v110, v110, -v110, s[0:1]
	v_cndmask_b32_e64 v113, v113, -v113, s[0:1]
	v_cndmask_b32_e64 v112, v112, -v112, s[0:1]
	v_pk_fma_f32 v[92:93], v[92:93], v[124:125], v[102:103]
	v_pk_fma_f32 v[88:89], v[88:89], v[100:101], v[106:107]
	v_pk_fma_f32 v[94:95], v[94:95], v[104:105], v[110:111]
	v_pk_fma_f32 v[90:91], v[90:91], v[108:109], v[112:113]
; __device__ __forceinline__ u32x4 pack8(f32x4 v0, f32x4 v1) { u32x4 w; w.x = cvt_pk_bf16(v0[0], v0[1]); w.y = cvt_pk_bf16(v0[2], v0[3]); w.z = cvt_pk_bf16(v1[0], v1[1]); w.w = cvt_pk_bf16(v1[2], v1[3]); return w; }
;     __device__ __forceinline__ void operator()(const f32x4 (&acc)[2][2][4][2], const Unit& u, int wr, int wc, int fr, int fq) const {
;         const int row0 = u.pm * BM + wr * 64 + fr; const bool first = fq < 2;
; #pragma unroll
;         for (int ai = 0; ai < 2; ++ai)
; #pragma unroll
;             for (int m = 0; m < 4; ++m) { const int row = row0 + ai * HALF + m * 16; const float rs = __builtin_amdgcn_rsqf(ssq[row] * (1.f / 512.f) + EPS) * QSCALE; const int t = row & (SEQ - 1);
; #pragma unroll
;                 for (int bj = 0; bj < 2; ++bj) { const int gcol = u.pn * 8 + bj * 4 + wc, hg = gcol % 6;
;                     f32x4 v0 = acc[ai][bj][m][0] * rs, v1 = acc[ai][bj][m][1] * rs;
;                     if (hg >= 4) { const int pos = hg == 4 ? (t >> 6) : (t & 63); const f32x2* tp = tab + pos * 16 + 8 * (fq & 1);
;                         f32x4 p0, p1;
; #pragma unroll
;                         for (int j = 0; j < 4; ++j) { p0[j] = __shfl_xor(v0[j], 32); p1[j] = __shfl_xor(v1[j], 32); }
; #pragma unroll
;                         for (int j = 0; j < 4; ++j) { const f32x2 c0 = tp[j], c1 = tp[4 + j];
;                             v0[j] = first ? (v0[j] * c0.x - p0[j] * c0.y) : (p0[j] * c0.y + v0[j] * c0.x);
;                             v1[j] = first ? (v1[j] * c1.x - p1[j] * c1.y) : (p1[j] * c1.y + v1[j] * c1.x); } }
;                     *(u32x4*)(Q + (size_t)row * 3072 + gcol * 32 + 8 * fq) = pack8(v0, v1); } }
;     }
.LBB0_965:
	v_cvt_pk_bf16_f32 v92, v92, v93
	v_cvt_pk_bf16_f32 v93, v94, v95
	v_cvt_pk_bf16_f32 v94, v88, v89
	v_mov_b64_e32 v[88:89], s[16:17]
	v_mad_i64_i32 v[88:89], s[30:31], v96, s71, v[88:89]
	v_cvt_pk_bf16_f32 v95, v90, v91
	v_lshl_add_u64 v[90:91], s[44:45], 1, v[88:89]
	v_lshl_add_u64 v[90:91], v[90:91], 0, v[136:137]
	v_mov_b32_e32 v99, v98
	global_store_dwordx4 v[90:91], v[92:95], off nt
	v_mov_b32_e32 v90, v98
	v_mov_b32_e32 v91, v98
	v_pk_mul_f32 v[86:87], v[86:87], v[90:91]
	v_pk_mul_f32 v[84:85], v[84:85], v[98:99]
	v_pk_mul_f32 v[82:83], v[82:83], v[90:91]
	s_and_b64 vcc, exec, s[6:7]
	v_pk_mul_f32 v[80:81], v[80:81], v[98:99]
	s_cbranch_vccnz .LBB0_967
	s_cmp_eq_u32 s35, 4
	v_mov_b32_e32 v90, s37
	s_cselect_b64 vcc, -1, 0
	v_cndmask_b32_e32 v90, v164, v90, vcc
	v_lshlrev_b32_e32 v90, 7, v90
	v_mov_b32_e32 v91, v137
	v_lshl_add_u64 v[102:103], v[138:139], 0, v[90:91]
	global_load_dwordx4 v[90:93], v[102:103], off
	global_load_dwordx4 v[94:97], v[102:103], off offset:32
	global_load_dwordx4 v[98:101], v[102:103], off offset:16
	s_nop 0
	global_load_dwordx4 v[102:105], v[102:103], off offset:48
	v_and_b32_e32 v107, 64, v170
	v_xor_b32_e32 v106, 32, v170
	v_add_u32_e32 v107, 64, v107
	v_cmp_lt_i32_e32 vcc, v106, v107
	s_waitcnt vmcnt(3)
	v_mov_b32_e32 v115, v92
	v_cndmask_b32_e32 v106, v170, v106, vcc
	v_lshlrev_b32_e32 v113, 2, v106
	ds_bpermute_b32 v106, v113, v84
	ds_bpermute_b32 v108, v113, v80
	ds_bpermute_b32 v107, v113, v85
	ds_bpermute_b32 v109, v113, v81
	ds_bpermute_b32 v110, v113, v86
	ds_bpermute_b32 v112, v113, v82
	ds_bpermute_b32 v111, v113, v87
	ds_bpermute_b32 v113, v113, v83
	v_mov_b32_e32 v92, v91
	s_waitcnt vmcnt(2)
	v_mov_b32_e32 v91, v96
	v_mov_b32_e32 v96, v95
	s_waitcnt vmcnt(1)
	v_mov_b32_e32 v95, v100
	v_mov_b32_e32 v100, v99
	s_waitcnt vmcnt(0)
	v_mov_b32_e32 v99, v104
	v_mov_b32_e32 v104, v103
	v_mov_b32_e32 v114, v90
	v_mov_b32_e32 v90, v94
	v_mov_b32_e32 v94, v98
	v_mov_b32_e32 v98, v102
	s_waitcnt lgkmcnt(5)
	v_pk_mul_f32 v[92:93], v[92:93], v[106:107]
	s_waitcnt lgkmcnt(4)
	v_pk_mul_f32 v[96:97], v[96:97], v[108:109]
	s_waitcnt lgkmcnt(1)
	v_pk_mul_f32 v[100:101], v[100:101], v[110:111]
	s_waitcnt lgkmcnt(0)
	v_pk_mul_f32 v[102:103], v[104:105], v[112:113]
	v_cndmask_b32_e64 v93, v93, -v93, s[0:1]
	v_cndmask_b32_e64 v92, v92, -v92, s[0:1]
	v_cndmask_b32_e64 v97, v97, -v97, s[0:1]
	v_cndmask_b32_e64 v96, v96, -v96, s[0:1]
	v_cndmask_b32_e64 v101, v101, -v101, s[0:1]
	v_cndmask_b32_e64 v100, v100, -v100, s[0:1]
	v_cndmask_b32_e64 v103, v103, -v103, s[0:1]
	v_cndmask_b32_e64 v102, v102, -v102, s[0:1]
	v_pk_fma_f32 v[84:85], v[84:85], v[114:115], v[92:93]
	v_pk_fma_f32 v[80:81], v[80:81], v[90:91], v[96:97]
	v_pk_fma_f32 v[86:87], v[86:87], v[94:95], v[100:101]
	v_pk_fma_f32 v[82:83], v[82:83], v[98:99], v[102:103]
.LBB0_967:
	v_cvt_pk_bf16_f32 v84, v84, v85
	v_cvt_pk_bf16_f32 v85, v86, v87
	v_cvt_pk_bf16_f32 v86, v80, v81
	v_lshl_add_u64 v[80:81], s[46:47], 1, v[88:89]
	v_lshl_add_u64 v[80:81], v[80:81], 0, v[136:137]
	v_cvt_pk_bf16_f32 v87, v82, v83
	global_store_dwordx4 v[80:81], v[84:87], off nt
	v_or_b32_e32 v80, 48, v148
	v_ashrrev_i32_e32 v81, 31, v80
	v_lshl_add_u64 v[82:83], v[80:81], 2, s[22:23]
	global_load_dword v81, v[82:83], off
	s_and_b64 vcc, exec, s[4:5]
	s_waitcnt vmcnt(0)
	v_fmamk_f32 v81, v81, 0x3b000000, v169
	v_rsq_f32_e32 v81, v81
	s_nop 0
	v_mul_f32_e32 v82, 0x3dd53b94, v81
	v_pk_mul_f32 v[78:79], v[78:79], v[82:83] op_sel_hi:[1,0]
	v_pk_mul_f32 v[76:77], v[76:77], v[82:83] op_sel_hi:[1,0]
	v_pk_mul_f32 v[74:75], v[74:75], v[82:83] op_sel_hi:[1,0]
	v_pk_mul_f32 v[72:73], v[72:73], v[82:83] op_sel_hi:[1,0]
	s_cbranch_vccnz .LBB0_969
	s_cmp_eq_u32 s34, 4
	v_mov_b32_e32 v81, s37
	s_cselect_b64 vcc, -1, 0
	v_cndmask_b32_e32 v81, v165, v81, vcc
	v_lshlrev_b32_e32 v84, 7, v81
	v_mov_b32_e32 v85, v137
	v_lshl_add_u64 v[96:97], v[138:139], 0, v[84:85]
	global_load_dwordx4 v[84:87], v[96:97], off
	global_load_dwordx4 v[88:91], v[96:97], off offset:32
	global_load_dwordx4 v[92:95], v[96:97], off offset:16
	s_nop 0
	global_load_dwordx4 v[96:99], v[96:97], off offset:48
	v_and_b32_e32 v83, 64, v170
	v_xor_b32_e32 v81, 32, v170
	v_add_u32_e32 v83, 64, v83
	v_cmp_lt_i32_e32 vcc, v81, v83
	s_waitcnt vmcnt(3)
	v_mov_b32_e32 v109, v86
	v_cndmask_b32_e32 v81, v170, v81, vcc
	v_lshlrev_b32_e32 v81, 2, v81
	ds_bpermute_b32 v100, v81, v76
	ds_bpermute_b32 v102, v81, v72
	ds_bpermute_b32 v101, v81, v77
	ds_bpermute_b32 v103, v81, v73
	ds_bpermute_b32 v104, v81, v78
	ds_bpermute_b32 v106, v81, v74
	ds_bpermute_b32 v105, v81, v79
	ds_bpermute_b32 v107, v81, v75
	v_mov_b32_e32 v86, v85
	s_waitcnt vmcnt(2)
	v_mov_b32_e32 v85, v90
	v_mov_b32_e32 v90, v89
	s_waitcnt vmcnt(1)
	v_mov_b32_e32 v89, v94
	v_mov_b32_e32 v94, v93
	s_waitcnt vmcnt(0)
	v_mov_b32_e32 v93, v98
	v_mov_b32_e32 v98, v97
	v_mov_b32_e32 v108, v84
	v_mov_b32_e32 v84, v88
	v_mov_b32_e32 v88, v92
	v_mov_b32_e32 v92, v96
	s_waitcnt lgkmcnt(5)
	v_pk_mul_f32 v[86:87], v[86:87], v[100:101]
	s_waitcnt lgkmcnt(4)
	v_pk_mul_f32 v[90:91], v[90:91], v[102:103]
	s_waitcnt lgkmcnt(1)
	v_pk_mul_f32 v[94:95], v[94:95], v[104:105]
	s_waitcnt lgkmcnt(0)
	v_pk_mul_f32 v[96:97], v[98:99], v[106:107]
	v_cndmask_b32_e64 v87, v87, -v87, s[0:1]
	v_cndmask_b32_e64 v86, v86, -v86, s[0:1]
	v_cndmask_b32_e64 v91, v91, -v91, s[0:1]
	v_cndmask_b32_e64 v90, v90, -v90, s[0:1]
	v_cndmask_b32_e64 v95, v95, -v95, s[0:1]
	v_cndmask_b32_e64 v94, v94, -v94, s[0:1]
	v_cndmask_b32_e64 v97, v97, -v97, s[0:1]
	v_cndmask_b32_e64 v96, v96, -v96, s[0:1]
	v_pk_fma_f32 v[76:77], v[76:77], v[108:109], v[86:87]
	v_pk_fma_f32 v[72:73], v[72:73], v[84:85], v[90:91]
	v_pk_fma_f32 v[78:79], v[78:79], v[88:89], v[94:95]
	v_pk_fma_f32 v[74:75], v[74:75], v[92:93], v[96:97]
; __device__ __forceinline__ u32x4 pack8(f32x4 v0, f32x4 v1) { u32x4 w; w.x = cvt_pk_bf16(v0[0], v0[1]); w.y = cvt_pk_bf16(v0[2], v0[3]); w.z = cvt_pk_bf16(v1[0], v1[1]); w.w = cvt_pk_bf16(v1[2], v1[3]); return w; }
;     __device__ __forceinline__ void operator()(const f32x4 (&acc)[2][2][4][2], const Unit& u, int wr, int wc, int fr, int fq) const {
;         const int row0 = u.pm * BM + wr * 64 + fr; const bool first = fq < 2;
; #pragma unroll
;         for (int ai = 0; ai < 2; ++ai)
; #pragma unroll
;             for (int m = 0; m < 4; ++m) { const int row = row0 + ai * HALF + m * 16; const float rs = __builtin_amdgcn_rsqf(ssq[row] * (1.f / 512.f) + EPS) * QSCALE; const int t = row & (SEQ - 1);
; #pragma unroll
;                 for (int bj = 0; bj < 2; ++bj) { const int gcol = u.pn * 8 + bj * 4 + wc, hg = gcol % 6;
;                     f32x4 v0 = acc[ai][bj][m][0] * rs, v1 = acc[ai][bj][m][1] * rs;
;                     if (hg >= 4) { const int pos = hg == 4 ? (t >> 6) : (t & 63); const f32x2* tp = tab + pos * 16 + 8 * (fq & 1);
;                         f32x4 p0, p1;
; #pragma unroll
;                         for (int j = 0; j < 4; ++j) { p0[j] = __shfl_xor(v0[j], 32); p1[j] = __shfl_xor(v1[j], 32); }
; #pragma unroll
;                         for (int j = 0; j < 4; ++j) { const f32x2 c0 = tp[j], c1 = tp[4 + j];
;                             v0[j] = first ? (v0[j] * c0.x - p0[j] * c0.y) : (p0[j] * c0.y + v0[j] * c0.x);
;                             v1[j] = first ? (v1[j] * c1.x - p1[j] * c1.y) : (p1[j] * c1.y + v1[j] * c1.x); } }
;                     *(u32x4*)(Q + (size_t)row * 3072 + gcol * 32 + 8 * fq) = pack8(v0, v1); } }
;     }
.LBB0_969:
	v_cvt_pk_bf16_f32 v76, v76, v77
	v_cvt_pk_bf16_f32 v77, v78, v79
	v_cvt_pk_bf16_f32 v78, v72, v73
	v_mov_b64_e32 v[72:73], s[16:17]
	v_mad_i64_i32 v[72:73], s[30:31], v80, s71, v[72:73]
	v_cvt_pk_bf16_f32 v79, v74, v75
	v_lshl_add_u64 v[74:75], s[44:45], 1, v[72:73]
	v_lshl_add_u64 v[74:75], v[74:75], 0, v[136:137]
	v_mov_b32_e32 v83, v82
	global_store_dwordx4 v[74:75], v[76:79], off nt
	v_mov_b32_e32 v74, v82
	v_mov_b32_e32 v75, v82
	v_pk_mul_f32 v[70:71], v[70:71], v[74:75]
	v_pk_mul_f32 v[68:69], v[68:69], v[82:83]
	v_pk_mul_f32 v[66:67], v[66:67], v[74:75]
	s_and_b64 vcc, exec, s[6:7]
	v_pk_mul_f32 v[64:65], v[64:65], v[82:83]
	s_cbranch_vccnz .LBB0_971
	s_cmp_eq_u32 s35, 4
	v_mov_b32_e32 v74, s37
	s_cselect_b64 vcc, -1, 0
	v_cndmask_b32_e32 v74, v165, v74, vcc
	v_lshlrev_b32_e32 v74, 7, v74
	v_mov_b32_e32 v75, v137
	v_lshl_add_u64 v[86:87], v[138:139], 0, v[74:75]
	global_load_dwordx4 v[74:77], v[86:87], off
	global_load_dwordx4 v[78:81], v[86:87], off offset:32
	global_load_dwordx4 v[82:85], v[86:87], off offset:16
	s_nop 0
	global_load_dwordx4 v[86:89], v[86:87], off offset:48
	v_and_b32_e32 v91, 64, v170
	v_xor_b32_e32 v90, 32, v170
	v_add_u32_e32 v91, 64, v91
	v_cmp_lt_i32_e32 vcc, v90, v91
	s_waitcnt vmcnt(3)
	v_mov_b32_e32 v99, v76
	v_cndmask_b32_e32 v90, v170, v90, vcc
	v_lshlrev_b32_e32 v97, 2, v90
	ds_bpermute_b32 v90, v97, v68
	ds_bpermute_b32 v92, v97, v64
	ds_bpermute_b32 v91, v97, v69
	ds_bpermute_b32 v93, v97, v65
	ds_bpermute_b32 v94, v97, v70
	ds_bpermute_b32 v96, v97, v66
	ds_bpermute_b32 v95, v97, v71
	ds_bpermute_b32 v97, v97, v67
	v_mov_b32_e32 v76, v75
	s_waitcnt vmcnt(2)
	v_mov_b32_e32 v75, v80
	v_mov_b32_e32 v80, v79
	s_waitcnt vmcnt(1)
	v_mov_b32_e32 v79, v84
	v_mov_b32_e32 v84, v83
	s_waitcnt vmcnt(0)
	v_mov_b32_e32 v83, v88
	v_mov_b32_e32 v88, v87
	v_mov_b32_e32 v98, v74
	v_mov_b32_e32 v74, v78
	v_mov_b32_e32 v78, v82
	v_mov_b32_e32 v82, v86
	s_waitcnt lgkmcnt(5)
	v_pk_mul_f32 v[76:77], v[76:77], v[90:91]
	s_waitcnt lgkmcnt(4)
	v_pk_mul_f32 v[80:81], v[80:81], v[92:93]
	s_waitcnt lgkmcnt(1)
	v_pk_mul_f32 v[84:85], v[84:85], v[94:95]
	s_waitcnt lgkmcnt(0)
	v_pk_mul_f32 v[86:87], v[88:89], v[96:97]
	v_cndmask_b32_e64 v77, v77, -v77, s[0:1]
	v_cndmask_b32_e64 v76, v76, -v76, s[0:1]
	v_cndmask_b32_e64 v81, v81, -v81, s[0:1]
	v_cndmask_b32_e64 v80, v80, -v80, s[0:1]
	v_cndmask_b32_e64 v85, v85, -v85, s[0:1]
	v_cndmask_b32_e64 v84, v84, -v84, s[0:1]
	v_cndmask_b32_e64 v87, v87, -v87, s[0:1]
	v_cndmask_b32_e64 v86, v86, -v86, s[0:1]
	v_pk_fma_f32 v[68:69], v[68:69], v[98:99], v[76:77]
	v_pk_fma_f32 v[64:65], v[64:65], v[74:75], v[80:81]
	v_pk_fma_f32 v[70:71], v[70:71], v[78:79], v[84:85]
	v_pk_fma_f32 v[66:67], v[66:67], v[82:83], v[86:87]
.LBB0_971:
	v_cvt_pk_bf16_f32 v68, v68, v69
	v_cvt_pk_bf16_f32 v69, v70, v71
	v_cvt_pk_bf16_f32 v70, v64, v65
	v_lshl_add_u64 v[64:65], s[46:47], 1, v[72:73]
	v_lshl_add_u64 v[64:65], v[64:65], 0, v[136:137]
	v_cvt_pk_bf16_f32 v71, v66, v67
	global_store_dwordx4 v[64:65], v[68:71], off nt
	global_load_dword v64, v[150:151], off offset:512
	v_add_u32_e32 v67, 0x80, v148
	s_and_b64 vcc, exec, s[4:5]
	v_bfe_u32 v66, v67, 6, 5
	s_waitcnt vmcnt(0)
	v_fmamk_f32 v64, v64, 0x3b000000, v169
	v_rsq_f32_e32 v64, v64
	s_nop 0
	v_mul_f32_e32 v64, 0x3dd53b94, v64
	v_pk_mul_f32 v[62:63], v[62:63], v[64:65] op_sel_hi:[1,0]
	v_pk_mul_f32 v[60:61], v[60:61], v[64:65] op_sel_hi:[1,0]
	v_pk_mul_f32 v[58:59], v[58:59], v[64:65] op_sel_hi:[1,0]
	v_pk_mul_f32 v[56:57], v[56:57], v[64:65] op_sel_hi:[1,0]
	s_cbranch_vccnz .LBB0_973
	s_cmp_eq_u32 s34, 4
	s_cselect_b64 vcc, -1, 0
	v_cndmask_b32_e32 v65, v160, v66, vcc
	v_lshlrev_b32_e32 v68, 7, v65
	v_mov_b32_e32 v69, v137
	v_lshl_add_u64 v[80:81], v[138:139], 0, v[68:69]
	global_load_dwordx4 v[68:71], v[80:81], off
	global_load_dwordx4 v[72:75], v[80:81], off offset:32
	global_load_dwordx4 v[76:79], v[80:81], off offset:16
	s_nop 0
	global_load_dwordx4 v[80:83], v[80:81], off offset:48
	v_and_b32_e32 v84, 64, v170
	v_xor_b32_e32 v65, 32, v170
	v_add_u32_e32 v84, 64, v84
	v_cmp_lt_i32_e32 vcc, v65, v84
	s_waitcnt vmcnt(3)
	v_mov_b32_e32 v93, v70
	v_cndmask_b32_e32 v65, v170, v65, vcc
	v_lshlrev_b32_e32 v65, 2, v65
	ds_bpermute_b32 v84, v65, v60
	ds_bpermute_b32 v86, v65, v56
	ds_bpermute_b32 v85, v65, v61
	ds_bpermute_b32 v87, v65, v57
	ds_bpermute_b32 v88, v65, v62
	ds_bpermute_b32 v90, v65, v58
	ds_bpermute_b32 v89, v65, v63
	ds_bpermute_b32 v91, v65, v59
	v_mov_b32_e32 v70, v69
	s_waitcnt vmcnt(2)
	v_mov_b32_e32 v69, v74
	v_mov_b32_e32 v74, v73
	s_waitcnt vmcnt(1)
	v_mov_b32_e32 v73, v78
	v_mov_b32_e32 v78, v77
	s_waitcnt vmcnt(0)
	v_mov_b32_e32 v77, v82
	v_mov_b32_e32 v82, v81
	v_mov_b32_e32 v92, v68
	v_mov_b32_e32 v68, v72
	v_mov_b32_e32 v72, v76
	v_mov_b32_e32 v76, v80
	s_waitcnt lgkmcnt(5)
	v_pk_mul_f32 v[70:71], v[70:71], v[84:85]
	s_waitcnt lgkmcnt(4)
	v_pk_mul_f32 v[74:75], v[74:75], v[86:87]
	s_waitcnt lgkmcnt(1)
	v_pk_mul_f32 v[78:79], v[78:79], v[88:89]
	s_waitcnt lgkmcnt(0)
	v_pk_mul_f32 v[80:81], v[82:83], v[90:91]
	v_cndmask_b32_e64 v71, v71, -v71, s[0:1]
	v_cndmask_b32_e64 v70, v70, -v70, s[0:1]
	v_cndmask_b32_e64 v75, v75, -v75, s[0:1]
	v_cndmask_b32_e64 v74, v74, -v74, s[0:1]
	v_cndmask_b32_e64 v79, v79, -v79, s[0:1]
	v_cndmask_b32_e64 v78, v78, -v78, s[0:1]
	v_cndmask_b32_e64 v81, v81, -v81, s[0:1]
	v_cndmask_b32_e64 v80, v80, -v80, s[0:1]
	v_pk_fma_f32 v[60:61], v[60:61], v[92:93], v[70:71]
	v_pk_fma_f32 v[56:57], v[56:57], v[68:69], v[74:75]
	v_pk_fma_f32 v[62:63], v[62:63], v[72:73], v[78:79]
	v_pk_fma_f32 v[58:59], v[58:59], v[76:77], v[80:81]
; __device__ __forceinline__ u32x4 pack8(f32x4 v0, f32x4 v1) { u32x4 w; w.x = cvt_pk_bf16(v0[0], v0[1]); w.y = cvt_pk_bf16(v0[2], v0[3]); w.z = cvt_pk_bf16(v1[0], v1[1]); w.w = cvt_pk_bf16(v1[2], v1[3]); return w; }
;     __device__ __forceinline__ void operator()(const f32x4 (&acc)[2][2][4][2], const Unit& u, int wr, int wc, int fr, int fq) const {
;         const int row0 = u.pm * BM + wr * 64 + fr; const bool first = fq < 2;
; #pragma unroll
;         for (int ai = 0; ai < 2; ++ai)
; #pragma unroll
;             for (int m = 0; m < 4; ++m) { const int row = row0 + ai * HALF + m * 16; const float rs = __builtin_amdgcn_rsqf(ssq[row] * (1.f / 512.f) + EPS) * QSCALE; const int t = row & (SEQ - 1);
; #pragma unroll
;                 for (int bj = 0; bj < 2; ++bj) { const int gcol = u.pn * 8 + bj * 4 + wc, hg = gcol % 6;
;                     f32x4 v0 = acc[ai][bj][m][0] * rs, v1 = acc[ai][bj][m][1] * rs;
;                     if (hg >= 4) { const int pos = hg == 4 ? (t >> 6) : (t & 63); const f32x2* tp = tab + pos * 16 + 8 * (fq & 1);
;                         f32x4 p0, p1;
; #pragma unroll
;                         for (int j = 0; j < 4; ++j) { p0[j] = __shfl_xor(v0[j], 32); p1[j] = __shfl_xor(v1[j], 32); }
; #pragma unroll
;                         for (int j = 0; j < 4; ++j) { const f32x2 c0 = tp[j], c1 = tp[4 + j];
;                             v0[j] = first ? (v0[j] * c0.x - p0[j] * c0.y) : (p0[j] * c0.y + v0[j] * c0.x);
;                             v1[j] = first ? (v1[j] * c1.x - p1[j] * c1.y) : (p1[j] * c1.y + v1[j] * c1.x); } }
;                     *(u32x4*)(Q + (size_t)row * 3072 + gcol * 32 + 8 * fq) = pack8(v0, v1); } }
;     }
.LBB0_973:
	v_cvt_pk_bf16_f32 v60, v60, v61
	v_cvt_pk_bf16_f32 v61, v62, v63
	v_cvt_pk_bf16_f32 v62, v56, v57
	v_mov_b64_e32 v[56:57], s[16:17]
	v_mad_i64_i32 v[56:57], s[30:31], v67, s71, v[56:57]
	v_cvt_pk_bf16_f32 v63, v58, v59
	v_lshl_add_u64 v[58:59], s[44:45], 1, v[56:57]
	v_lshl_add_u64 v[58:59], v[58:59], 0, v[136:137]
	v_mov_b32_e32 v65, v64
	global_store_dwordx4 v[58:59], v[60:63], off nt
	v_mov_b32_e32 v58, v64
	v_mov_b32_e32 v59, v64
	v_pk_mul_f32 v[54:55], v[54:55], v[58:59]
	v_pk_mul_f32 v[52:53], v[52:53], v[64:65]
	v_pk_mul_f32 v[50:51], v[50:51], v[58:59]
	s_and_b64 vcc, exec, s[6:7]
	v_pk_mul_f32 v[48:49], v[48:49], v[64:65]
	s_cbranch_vccnz .LBB0_975
	s_cmp_eq_u32 s35, 4
	s_cselect_b64 vcc, -1, 0
	v_cndmask_b32_e32 v58, v160, v66, vcc
	v_lshlrev_b32_e32 v58, 7, v58
	v_mov_b32_e32 v59, v137
	v_lshl_add_u64 v[72:73], v[138:139], 0, v[58:59]
	global_load_dwordx4 v[58:61], v[72:73], off
	global_load_dwordx4 v[62:65], v[72:73], off offset:32
	global_load_dwordx4 v[68:71], v[72:73], off offset:16
	s_nop 0
	global_load_dwordx4 v[72:75], v[72:73], off offset:48
	v_and_b32_e32 v76, 64, v170
	v_xor_b32_e32 v67, 32, v170
	v_add_u32_e32 v76, 64, v76
	v_cmp_lt_i32_e32 vcc, v67, v76
	s_waitcnt vmcnt(3)
	v_mov_b32_e32 v85, v60
	v_cndmask_b32_e32 v67, v170, v67, vcc
	v_lshlrev_b32_e32 v67, 2, v67
	ds_bpermute_b32 v76, v67, v52
	ds_bpermute_b32 v78, v67, v48
	ds_bpermute_b32 v77, v67, v53
	ds_bpermute_b32 v79, v67, v49
	ds_bpermute_b32 v80, v67, v54
	ds_bpermute_b32 v82, v67, v50
	ds_bpermute_b32 v81, v67, v55
	ds_bpermute_b32 v83, v67, v51
	v_mov_b32_e32 v60, v59
	s_waitcnt vmcnt(2)
	v_mov_b32_e32 v59, v64
	v_mov_b32_e32 v64, v63
	s_waitcnt vmcnt(1)
	v_mov_b32_e32 v63, v70
	v_mov_b32_e32 v70, v69
	s_waitcnt vmcnt(0)
	v_mov_b32_e32 v69, v74
	v_mov_b32_e32 v74, v73
	v_mov_b32_e32 v84, v58
	v_mov_b32_e32 v58, v62
	v_mov_b32_e32 v62, v68
	v_mov_b32_e32 v68, v72
	s_waitcnt lgkmcnt(5)
	v_pk_mul_f32 v[60:61], v[60:61], v[76:77]
	s_waitcnt lgkmcnt(4)
	v_pk_mul_f32 v[64:65], v[64:65], v[78:79]
	s_waitcnt lgkmcnt(1)
	v_pk_mul_f32 v[70:71], v[70:71], v[80:81]
	s_waitcnt lgkmcnt(0)
	v_pk_mul_f32 v[72:73], v[74:75], v[82:83]
	v_cndmask_b32_e64 v61, v61, -v61, s[0:1]
	v_cndmask_b32_e64 v60, v60, -v60, s[0:1]
	v_cndmask_b32_e64 v65, v65, -v65, s[0:1]
	v_cndmask_b32_e64 v64, v64, -v64, s[0:1]
	v_cndmask_b32_e64 v71, v71, -v71, s[0:1]
	v_cndmask_b32_e64 v70, v70, -v70, s[0:1]
	v_cndmask_b32_e64 v73, v73, -v73, s[0:1]
	v_cndmask_b32_e64 v72, v72, -v72, s[0:1]
	v_pk_fma_f32 v[52:53], v[52:53], v[84:85], v[60:61]
	v_pk_fma_f32 v[48:49], v[48:49], v[58:59], v[64:65]
	v_pk_fma_f32 v[54:55], v[54:55], v[62:63], v[70:71]
	v_pk_fma_f32 v[50:51], v[50:51], v[68:69], v[72:73]
.LBB0_975:
	v_cvt_pk_bf16_f32 v52, v52, v53
	v_cvt_pk_bf16_f32 v53, v54, v55
	v_cvt_pk_bf16_f32 v54, v48, v49
	v_lshl_add_u64 v[48:49], s[46:47], 1, v[56:57]
	v_lshl_add_u64 v[48:49], v[48:49], 0, v[136:137]
	v_cvt_pk_bf16_f32 v55, v50, v51
	global_store_dwordx4 v[48:49], v[52:55], off nt
	global_load_dword v48, v[150:151], off offset:576
	s_and_b64 vcc, exec, s[4:5]
	s_waitcnt vmcnt(0)
	v_fmamk_f32 v48, v48, 0x3b000000, v169
	v_rsq_f32_e32 v48, v48
	s_nop 0
	v_mul_f32_e32 v48, 0x3dd53b94, v48
	v_pk_mul_f32 v[46:47], v[46:47], v[48:49] op_sel_hi:[1,0]
	v_pk_mul_f32 v[44:45], v[44:45], v[48:49] op_sel_hi:[1,0]
	v_pk_mul_f32 v[42:43], v[42:43], v[48:49] op_sel_hi:[1,0]
	v_pk_mul_f32 v[40:41], v[40:41], v[48:49] op_sel_hi:[1,0]
	s_cbranch_vccnz .LBB0_977
	s_cmp_eq_u32 s34, 4
	s_cselect_b64 vcc, -1, 0
	v_cndmask_b32_e32 v49, v163, v66, vcc
	v_lshlrev_b32_e32 v50, 7, v49
	v_mov_b32_e32 v51, v137
	v_lshl_add_u64 v[62:63], v[138:139], 0, v[50:51]
	global_load_dwordx4 v[50:53], v[62:63], off
	global_load_dwordx4 v[54:57], v[62:63], off offset:32
	global_load_dwordx4 v[58:61], v[62:63], off offset:16
	s_nop 0
	global_load_dwordx4 v[62:65], v[62:63], off offset:48
	v_and_b32_e32 v67, 64, v170
	v_xor_b32_e32 v49, 32, v170
	v_add_u32_e32 v67, 64, v67
	v_cmp_lt_i32_e32 vcc, v49, v67
	s_waitcnt vmcnt(3)
	v_mov_b32_e32 v77, v52
	v_cndmask_b32_e32 v49, v170, v49, vcc
	v_lshlrev_b32_e32 v49, 2, v49
	ds_bpermute_b32 v68, v49, v44
	ds_bpermute_b32 v70, v49, v40
	ds_bpermute_b32 v69, v49, v45
	ds_bpermute_b32 v71, v49, v41
	ds_bpermute_b32 v72, v49, v46
	ds_bpermute_b32 v74, v49, v42
	ds_bpermute_b32 v73, v49, v47
	ds_bpermute_b32 v75, v49, v43
	v_mov_b32_e32 v52, v51
	s_waitcnt vmcnt(2)
	v_mov_b32_e32 v51, v56
	v_mov_b32_e32 v56, v55
	s_waitcnt vmcnt(1)
	v_mov_b32_e32 v55, v60
	v_mov_b32_e32 v60, v59
	s_waitcnt vmcnt(0)
	v_mov_b32_e32 v59, v64
	v_mov_b32_e32 v64, v63
	v_mov_b32_e32 v76, v50
	v_mov_b32_e32 v50, v54
	v_mov_b32_e32 v54, v58
	v_mov_b32_e32 v58, v62
	s_waitcnt lgkmcnt(5)
	v_pk_mul_f32 v[52:53], v[52:53], v[68:69]
	s_waitcnt lgkmcnt(4)
	v_pk_mul_f32 v[56:57], v[56:57], v[70:71]
	s_waitcnt lgkmcnt(1)
	v_pk_mul_f32 v[60:61], v[60:61], v[72:73]
	s_waitcnt lgkmcnt(0)
	v_pk_mul_f32 v[62:63], v[64:65], v[74:75]
	v_cndmask_b32_e64 v53, v53, -v53, s[0:1]
	v_cndmask_b32_e64 v52, v52, -v52, s[0:1]
	v_cndmask_b32_e64 v57, v57, -v57, s[0:1]
	v_cndmask_b32_e64 v56, v56, -v56, s[0:1]
	v_cndmask_b32_e64 v61, v61, -v61, s[0:1]
	v_cndmask_b32_e64 v60, v60, -v60, s[0:1]
	v_cndmask_b32_e64 v63, v63, -v63, s[0:1]
	v_cndmask_b32_e64 v62, v62, -v62, s[0:1]
	v_pk_fma_f32 v[44:45], v[44:45], v[76:77], v[52:53]
	v_pk_fma_f32 v[40:41], v[40:41], v[50:51], v[56:57]
	v_pk_fma_f32 v[46:47], v[46:47], v[54:55], v[60:61]
	v_pk_fma_f32 v[42:43], v[42:43], v[58:59], v[62:63]
; __device__ __forceinline__ u32x4 pack8(f32x4 v0, f32x4 v1) { u32x4 w; w.x = cvt_pk_bf16(v0[0], v0[1]); w.y = cvt_pk_bf16(v0[2], v0[3]); w.z = cvt_pk_bf16(v1[0], v1[1]); w.w = cvt_pk_bf16(v1[2], v1[3]); return w; }
;     __device__ __forceinline__ void operator()(const f32x4 (&acc)[2][2][4][2], const Unit& u, int wr, int wc, int fr, int fq) const {
;         const int row0 = u.pm * BM + wr * 64 + fr; const bool first = fq < 2;
; #pragma unroll
;         for (int ai = 0; ai < 2; ++ai)
; #pragma unroll
;             for (int m = 0; m < 4; ++m) { const int row = row0 + ai * HALF + m * 16; const float rs = __builtin_amdgcn_rsqf(ssq[row] * (1.f / 512.f) + EPS) * QSCALE; const int t = row & (SEQ - 1);
; #pragma unroll
;                 for (int bj = 0; bj < 2; ++bj) { const int gcol = u.pn * 8 + bj * 4 + wc, hg = gcol % 6;
;                     f32x4 v0 = acc[ai][bj][m][0] * rs, v1 = acc[ai][bj][m][1] * rs;
;                     if (hg >= 4) { const int pos = hg == 4 ? (t >> 6) : (t & 63); const f32x2* tp = tab + pos * 16 + 8 * (fq & 1);
;                         f32x4 p0, p1;
; #pragma unroll
;                         for (int j = 0; j < 4; ++j) { p0[j] = __shfl_xor(v0[j], 32); p1[j] = __shfl_xor(v1[j], 32); }
; #pragma unroll
;                         for (int j = 0; j < 4; ++j) { const f32x2 c0 = tp[j], c1 = tp[4 + j];
;                             v0[j] = first ? (v0[j] * c0.x - p0[j] * c0.y) : (p0[j] * c0.y + v0[j] * c0.x);
;                             v1[j] = first ? (v1[j] * c1.x - p1[j] * c1.y) : (p1[j] * c1.y + v1[j] * c1.x); } }
;                     *(u32x4*)(Q + (size_t)row * 3072 + gcol * 32 + 8 * fq) = pack8(v0, v1); } }
;     }
.LBB0_977:
	v_add_u32_e32 v50, 0x90, v148
	v_cvt_pk_bf16_f32 v44, v44, v45
	v_cvt_pk_bf16_f32 v45, v46, v47
	v_cvt_pk_bf16_f32 v46, v40, v41
	v_mov_b64_e32 v[40:41], s[16:17]
	v_mad_i64_i32 v[40:41], s[30:31], v50, s71, v[40:41]
	v_cvt_pk_bf16_f32 v47, v42, v43
	v_lshl_add_u64 v[42:43], s[44:45], 1, v[40:41]
	v_lshl_add_u64 v[42:43], v[42:43], 0, v[136:137]
	v_mov_b32_e32 v49, v48
	global_store_dwordx4 v[42:43], v[44:47], off nt
	v_mov_b32_e32 v42, v48
	v_mov_b32_e32 v43, v48
	v_pk_mul_f32 v[38:39], v[38:39], v[42:43]
	v_pk_mul_f32 v[36:37], v[36:37], v[48:49]
	v_pk_mul_f32 v[34:35], v[34:35], v[42:43]
	s_and_b64 vcc, exec, s[6:7]
	v_pk_mul_f32 v[32:33], v[32:33], v[48:49]
	s_cbranch_vccnz .LBB0_979
	s_cmp_eq_u32 s35, 4
	s_cselect_b64 vcc, -1, 0
	v_cndmask_b32_e32 v42, v163, v66, vcc
	v_lshlrev_b32_e32 v42, 7, v42
	v_mov_b32_e32 v43, v137
	v_lshl_add_u64 v[54:55], v[138:139], 0, v[42:43]
	global_load_dwordx4 v[42:45], v[54:55], off
	global_load_dwordx4 v[46:49], v[54:55], off offset:32
	global_load_dwordx4 v[50:53], v[54:55], off offset:16
	s_nop 0
	global_load_dwordx4 v[54:57], v[54:55], off offset:48
	v_and_b32_e32 v59, 64, v170
	v_xor_b32_e32 v58, 32, v170
	v_add_u32_e32 v59, 64, v59
	v_cmp_lt_i32_e32 vcc, v58, v59
	s_waitcnt vmcnt(3)
	v_mov_b32_e32 v69, v44
	v_cndmask_b32_e32 v58, v170, v58, vcc
	v_lshlrev_b32_e32 v65, 2, v58
	ds_bpermute_b32 v58, v65, v36
	ds_bpermute_b32 v60, v65, v32
	ds_bpermute_b32 v59, v65, v37
	ds_bpermute_b32 v61, v65, v33
	ds_bpermute_b32 v62, v65, v38
	ds_bpermute_b32 v64, v65, v34
	ds_bpermute_b32 v63, v65, v39
	ds_bpermute_b32 v65, v65, v35
	v_mov_b32_e32 v44, v43
	s_waitcnt vmcnt(2)
	v_mov_b32_e32 v43, v48
	v_mov_b32_e32 v48, v47
	s_waitcnt vmcnt(1)
	v_mov_b32_e32 v47, v52
	v_mov_b32_e32 v52, v51
	s_waitcnt vmcnt(0)
	v_mov_b32_e32 v51, v56
	v_mov_b32_e32 v56, v55
	v_mov_b32_e32 v68, v42
	v_mov_b32_e32 v42, v46
	v_mov_b32_e32 v46, v50
	v_mov_b32_e32 v50, v54
	s_waitcnt lgkmcnt(5)
	v_pk_mul_f32 v[44:45], v[44:45], v[58:59]
	s_waitcnt lgkmcnt(4)
	v_pk_mul_f32 v[48:49], v[48:49], v[60:61]
	s_waitcnt lgkmcnt(1)
	v_pk_mul_f32 v[52:53], v[52:53], v[62:63]
	s_waitcnt lgkmcnt(0)
	v_pk_mul_f32 v[54:55], v[56:57], v[64:65]
	v_cndmask_b32_e64 v45, v45, -v45, s[0:1]
	v_cndmask_b32_e64 v44, v44, -v44, s[0:1]
	v_cndmask_b32_e64 v49, v49, -v49, s[0:1]
	v_cndmask_b32_e64 v48, v48, -v48, s[0:1]
	v_cndmask_b32_e64 v53, v53, -v53, s[0:1]
	v_cndmask_b32_e64 v52, v52, -v52, s[0:1]
	v_cndmask_b32_e64 v55, v55, -v55, s[0:1]
	v_cndmask_b32_e64 v54, v54, -v54, s[0:1]
	v_pk_fma_f32 v[36:37], v[36:37], v[68:69], v[44:45]
	v_pk_fma_f32 v[32:33], v[32:33], v[42:43], v[48:49]
	v_pk_fma_f32 v[38:39], v[38:39], v[46:47], v[52:53]
	v_pk_fma_f32 v[34:35], v[34:35], v[50:51], v[54:55]
.LBB0_979:
	v_cvt_pk_bf16_f32 v36, v36, v37
	v_cvt_pk_bf16_f32 v37, v38, v39
	v_cvt_pk_bf16_f32 v38, v32, v33
	v_lshl_add_u64 v[32:33], s[46:47], 1, v[40:41]
	v_lshl_add_u64 v[32:33], v[32:33], 0, v[136:137]
	v_cvt_pk_bf16_f32 v39, v34, v35
	global_store_dwordx4 v[32:33], v[36:39], off nt
	global_load_dword v32, v[150:151], off offset:640
	s_and_b64 vcc, exec, s[4:5]
	s_waitcnt vmcnt(0)
	v_fmamk_f32 v32, v32, 0x3b000000, v169
	v_rsq_f32_e32 v32, v32
	s_nop 0
	v_mul_f32_e32 v32, 0x3dd53b94, v32
	v_pk_mul_f32 v[30:31], v[30:31], v[32:33] op_sel_hi:[1,0]
	v_pk_mul_f32 v[28:29], v[28:29], v[32:33] op_sel_hi:[1,0]
	v_pk_mul_f32 v[26:27], v[26:27], v[32:33] op_sel_hi:[1,0]
	v_pk_mul_f32 v[24:25], v[24:25], v[32:33] op_sel_hi:[1,0]
	s_cbranch_vccnz .LBB0_981
	s_cmp_eq_u32 s34, 4
	s_cselect_b64 vcc, -1, 0
	v_cndmask_b32_e32 v33, v164, v66, vcc
	v_lshlrev_b32_e32 v34, 7, v33
	v_mov_b32_e32 v35, v137
	v_lshl_add_u64 v[46:47], v[138:139], 0, v[34:35]
	global_load_dwordx4 v[34:37], v[46:47], off
	global_load_dwordx4 v[38:41], v[46:47], off offset:32
	global_load_dwordx4 v[42:45], v[46:47], off offset:16
	s_nop 0
	global_load_dwordx4 v[46:49], v[46:47], off offset:48
	v_and_b32_e32 v50, 64, v170
	v_xor_b32_e32 v33, 32, v170
	v_add_u32_e32 v50, 64, v50
	v_cmp_lt_i32_e32 vcc, v33, v50
	s_waitcnt vmcnt(3)
	v_mov_b32_e32 v59, v36
	v_cndmask_b32_e32 v33, v170, v33, vcc
	v_lshlrev_b32_e32 v33, 2, v33
	ds_bpermute_b32 v50, v33, v28
	ds_bpermute_b32 v52, v33, v24
	ds_bpermute_b32 v51, v33, v29
	ds_bpermute_b32 v53, v33, v25
	ds_bpermute_b32 v54, v33, v30
	ds_bpermute_b32 v56, v33, v26
	ds_bpermute_b32 v55, v33, v31
	ds_bpermute_b32 v57, v33, v27
	v_mov_b32_e32 v36, v35
	s_waitcnt vmcnt(2)
	v_mov_b32_e32 v35, v40
	v_mov_b32_e32 v40, v39
	s_waitcnt vmcnt(1)
	v_mov_b32_e32 v39, v44
	v_mov_b32_e32 v44, v43
	s_waitcnt vmcnt(0)
	v_mov_b32_e32 v43, v48
	v_mov_b32_e32 v48, v47
	v_mov_b32_e32 v58, v34
	v_mov_b32_e32 v34, v38
	v_mov_b32_e32 v38, v42
	v_mov_b32_e32 v42, v46
	s_waitcnt lgkmcnt(5)
	v_pk_mul_f32 v[36:37], v[36:37], v[50:51]
	s_waitcnt lgkmcnt(4)
	v_pk_mul_f32 v[40:41], v[40:41], v[52:53]
	s_waitcnt lgkmcnt(1)
	v_pk_mul_f32 v[44:45], v[44:45], v[54:55]
	s_waitcnt lgkmcnt(0)
	v_pk_mul_f32 v[46:47], v[48:49], v[56:57]
	v_cndmask_b32_e64 v37, v37, -v37, s[0:1]
	v_cndmask_b32_e64 v36, v36, -v36, s[0:1]
	v_cndmask_b32_e64 v41, v41, -v41, s[0:1]
	v_cndmask_b32_e64 v40, v40, -v40, s[0:1]
	v_cndmask_b32_e64 v45, v45, -v45, s[0:1]
	v_cndmask_b32_e64 v44, v44, -v44, s[0:1]
	v_cndmask_b32_e64 v47, v47, -v47, s[0:1]
	v_cndmask_b32_e64 v46, v46, -v46, s[0:1]
	v_pk_fma_f32 v[28:29], v[28:29], v[58:59], v[36:37]
	v_pk_fma_f32 v[24:25], v[24:25], v[34:35], v[40:41]
	v_pk_fma_f32 v[30:31], v[30:31], v[38:39], v[44:45]
	v_pk_fma_f32 v[26:27], v[26:27], v[42:43], v[46:47]
; __device__ __forceinline__ u32x4 pack8(f32x4 v0, f32x4 v1) { u32x4 w; w.x = cvt_pk_bf16(v0[0], v0[1]); w.y = cvt_pk_bf16(v0[2], v0[3]); w.z = cvt_pk_bf16(v1[0], v1[1]); w.w = cvt_pk_bf16(v1[2], v1[3]); return w; }
;     __device__ __forceinline__ void operator()(const f32x4 (&acc)[2][2][4][2], const Unit& u, int wr, int wc, int fr, int fq) const {
;         const int row0 = u.pm * BM + wr * 64 + fr; const bool first = fq < 2;
; #pragma unroll
;         for (int ai = 0; ai < 2; ++ai)
; #pragma unroll
;             for (int m = 0; m < 4; ++m) { const int row = row0 + ai * HALF + m * 16; const float rs = __builtin_amdgcn_rsqf(ssq[row] * (1.f / 512.f) + EPS) * QSCALE; const int t = row & (SEQ - 1);
; #pragma unroll
;                 for (int bj = 0; bj < 2; ++bj) { const int gcol = u.pn * 8 + bj * 4 + wc, hg = gcol % 6;
;                     f32x4 v0 = acc[ai][bj][m][0] * rs, v1 = acc[ai][bj][m][1] * rs;
;                     if (hg >= 4) { const int pos = hg == 4 ? (t >> 6) : (t & 63); const f32x2* tp = tab + pos * 16 + 8 * (fq & 1);
;                         f32x4 p0, p1;
; #pragma unroll
;                         for (int j = 0; j < 4; ++j) { p0[j] = __shfl_xor(v0[j], 32); p1[j] = __shfl_xor(v1[j], 32); }
; #pragma unroll
;                         for (int j = 0; j < 4; ++j) { const f32x2 c0 = tp[j], c1 = tp[4 + j];
;                             v0[j] = first ? (v0[j] * c0.x - p0[j] * c0.y) : (p0[j] * c0.y + v0[j] * c0.x);
;                             v1[j] = first ? (v1[j] * c1.x - p1[j] * c1.y) : (p1[j] * c1.y + v1[j] * c1.x); } }
;                     *(u32x4*)(Q + (size_t)row * 3072 + gcol * 32 + 8 * fq) = pack8(v0, v1); } }
;     }
.LBB0_981:
	v_add_u32_e32 v34, 0xa0, v148
	v_cvt_pk_bf16_f32 v28, v28, v29
	v_cvt_pk_bf16_f32 v29, v30, v31
	v_cvt_pk_bf16_f32 v30, v24, v25
	v_mov_b64_e32 v[24:25], s[16:17]
	v_mad_i64_i32 v[24:25], s[30:31], v34, s71, v[24:25]
	v_cvt_pk_bf16_f32 v31, v26, v27
	v_lshl_add_u64 v[26:27], s[44:45], 1, v[24:25]
	v_lshl_add_u64 v[26:27], v[26:27], 0, v[136:137]
	v_mov_b32_e32 v33, v32
	global_store_dwordx4 v[26:27], v[28:31], off nt
	v_mov_b32_e32 v26, v32
	v_mov_b32_e32 v27, v32
	v_pk_mul_f32 v[22:23], v[22:23], v[26:27]
	v_pk_mul_f32 v[20:21], v[20:21], v[32:33]
	v_pk_mul_f32 v[18:19], v[18:19], v[26:27]
	s_and_b64 vcc, exec, s[6:7]
	v_pk_mul_f32 v[16:17], v[16:17], v[32:33]
	s_cbranch_vccnz .LBB0_983
	s_cmp_eq_u32 s35, 4
	s_cselect_b64 vcc, -1, 0
	v_cndmask_b32_e32 v26, v164, v66, vcc
	v_lshlrev_b32_e32 v26, 7, v26
	v_mov_b32_e32 v27, v137
	v_lshl_add_u64 v[38:39], v[138:139], 0, v[26:27]
	global_load_dwordx4 v[26:29], v[38:39], off
	global_load_dwordx4 v[30:33], v[38:39], off offset:32
	global_load_dwordx4 v[34:37], v[38:39], off offset:16
	s_nop 0
	global_load_dwordx4 v[38:41], v[38:39], off offset:48
	v_and_b32_e32 v43, 64, v170
	v_xor_b32_e32 v42, 32, v170
	v_add_u32_e32 v43, 64, v43
	v_cmp_lt_i32_e32 vcc, v42, v43
	s_waitcnt vmcnt(3)
	v_mov_b32_e32 v51, v28
	v_cndmask_b32_e32 v42, v170, v42, vcc
	v_lshlrev_b32_e32 v49, 2, v42
	ds_bpermute_b32 v42, v49, v20
	ds_bpermute_b32 v44, v49, v16
	ds_bpermute_b32 v43, v49, v21
	ds_bpermute_b32 v45, v49, v17
	ds_bpermute_b32 v46, v49, v22
	ds_bpermute_b32 v48, v49, v18
	ds_bpermute_b32 v47, v49, v23
	ds_bpermute_b32 v49, v49, v19
	v_mov_b32_e32 v28, v27
	s_waitcnt vmcnt(2)
	v_mov_b32_e32 v27, v32
	v_mov_b32_e32 v32, v31
	s_waitcnt vmcnt(1)
	v_mov_b32_e32 v31, v36
	v_mov_b32_e32 v36, v35
	s_waitcnt vmcnt(0)
	v_mov_b32_e32 v35, v40
	v_mov_b32_e32 v40, v39
	v_mov_b32_e32 v50, v26
	v_mov_b32_e32 v26, v30
	v_mov_b32_e32 v30, v34
	v_mov_b32_e32 v34, v38
	s_waitcnt lgkmcnt(5)
	v_pk_mul_f32 v[28:29], v[28:29], v[42:43]
	s_waitcnt lgkmcnt(4)
	v_pk_mul_f32 v[32:33], v[32:33], v[44:45]
	s_waitcnt lgkmcnt(1)
	v_pk_mul_f32 v[36:37], v[36:37], v[46:47]
	s_waitcnt lgkmcnt(0)
	v_pk_mul_f32 v[38:39], v[40:41], v[48:49]
	v_cndmask_b32_e64 v29, v29, -v29, s[0:1]
	v_cndmask_b32_e64 v28, v28, -v28, s[0:1]
	v_cndmask_b32_e64 v33, v33, -v33, s[0:1]
	v_cndmask_b32_e64 v32, v32, -v32, s[0:1]
	v_cndmask_b32_e64 v37, v37, -v37, s[0:1]
	v_cndmask_b32_e64 v36, v36, -v36, s[0:1]
	v_cndmask_b32_e64 v39, v39, -v39, s[0:1]
	v_cndmask_b32_e64 v38, v38, -v38, s[0:1]
	v_pk_fma_f32 v[20:21], v[20:21], v[50:51], v[28:29]
	v_pk_fma_f32 v[16:17], v[16:17], v[26:27], v[32:33]
	v_pk_fma_f32 v[22:23], v[22:23], v[30:31], v[36:37]
	v_pk_fma_f32 v[18:19], v[18:19], v[34:35], v[38:39]
.LBB0_983:
	v_cvt_pk_bf16_f32 v20, v20, v21
	v_cvt_pk_bf16_f32 v21, v22, v23
	v_cvt_pk_bf16_f32 v22, v16, v17
	v_lshl_add_u64 v[16:17], s[46:47], 1, v[24:25]
	v_lshl_add_u64 v[16:17], v[16:17], 0, v[136:137]
	v_cvt_pk_bf16_f32 v23, v18, v19
	global_store_dwordx4 v[16:17], v[20:23], off nt
	global_load_dword v16, v[150:151], off offset:704
	s_and_b64 vcc, exec, s[4:5]
	s_waitcnt vmcnt(0)
	v_fmamk_f32 v16, v16, 0x3b000000, v169
	v_rsq_f32_e32 v16, v16
	s_nop 0
	v_mul_f32_e32 v16, 0x3dd53b94, v16
	v_pk_mul_f32 v[14:15], v[14:15], v[16:17] op_sel_hi:[1,0]
	v_pk_mul_f32 v[12:13], v[12:13], v[16:17] op_sel_hi:[1,0]
	v_pk_mul_f32 v[10:11], v[10:11], v[16:17] op_sel_hi:[1,0]
	v_pk_mul_f32 v[8:9], v[8:9], v[16:17] op_sel_hi:[1,0]
	s_cbranch_vccnz .LBB0_985
	s_cmp_eq_u32 s34, 4
	s_cselect_b64 vcc, -1, 0
	v_cndmask_b32_e32 v17, v165, v66, vcc
	v_lshlrev_b32_e32 v18, 7, v17
	v_mov_b32_e32 v19, v137
	v_lshl_add_u64 v[30:31], v[138:139], 0, v[18:19]
	global_load_dwordx4 v[18:21], v[30:31], off
	global_load_dwordx4 v[22:25], v[30:31], off offset:32
	global_load_dwordx4 v[26:29], v[30:31], off offset:16
	s_nop 0
	global_load_dwordx4 v[30:33], v[30:31], off offset:48
	v_and_b32_e32 v34, 64, v170
	v_xor_b32_e32 v17, 32, v170
	v_add_u32_e32 v34, 64, v34
	v_cmp_lt_i32_e32 vcc, v17, v34
	s_waitcnt vmcnt(3)
	v_mov_b32_e32 v43, v20
	v_cndmask_b32_e32 v17, v170, v17, vcc
	v_lshlrev_b32_e32 v17, 2, v17
	ds_bpermute_b32 v34, v17, v12
	ds_bpermute_b32 v36, v17, v8
	ds_bpermute_b32 v35, v17, v13
	ds_bpermute_b32 v37, v17, v9
	ds_bpermute_b32 v38, v17, v14
	ds_bpermute_b32 v40, v17, v10
	ds_bpermute_b32 v39, v17, v15
	ds_bpermute_b32 v41, v17, v11
	v_mov_b32_e32 v20, v19
	s_waitcnt vmcnt(2)
	v_mov_b32_e32 v19, v24
	v_mov_b32_e32 v24, v23
	s_waitcnt vmcnt(1)
	v_mov_b32_e32 v23, v28
	v_mov_b32_e32 v28, v27
	s_waitcnt vmcnt(0)
	v_mov_b32_e32 v27, v32
	v_mov_b32_e32 v32, v31
	v_mov_b32_e32 v42, v18
	v_mov_b32_e32 v18, v22
	v_mov_b32_e32 v22, v26
	v_mov_b32_e32 v26, v30
	s_waitcnt lgkmcnt(5)
	v_pk_mul_f32 v[20:21], v[20:21], v[34:35]
	s_waitcnt lgkmcnt(4)
	v_pk_mul_f32 v[24:25], v[24:25], v[36:37]
	s_waitcnt lgkmcnt(1)
	v_pk_mul_f32 v[28:29], v[28:29], v[38:39]
	s_waitcnt lgkmcnt(0)
	v_pk_mul_f32 v[30:31], v[32:33], v[40:41]
	v_cndmask_b32_e64 v21, v21, -v21, s[0:1]
	v_cndmask_b32_e64 v20, v20, -v20, s[0:1]
	v_cndmask_b32_e64 v25, v25, -v25, s[0:1]
	v_cndmask_b32_e64 v24, v24, -v24, s[0:1]
	v_cndmask_b32_e64 v29, v29, -v29, s[0:1]
	v_cndmask_b32_e64 v28, v28, -v28, s[0:1]
	v_cndmask_b32_e64 v31, v31, -v31, s[0:1]
	v_cndmask_b32_e64 v30, v30, -v30, s[0:1]
	v_pk_fma_f32 v[12:13], v[12:13], v[42:43], v[20:21]
	v_pk_fma_f32 v[8:9], v[8:9], v[18:19], v[24:25]
	v_pk_fma_f32 v[14:15], v[14:15], v[22:23], v[28:29]
	v_pk_fma_f32 v[10:11], v[10:11], v[26:27], v[30:31]
; __device__ __forceinline__ u32x4 pack8(f32x4 v0, f32x4 v1) { u32x4 w; w.x = cvt_pk_bf16(v0[0], v0[1]); w.y = cvt_pk_bf16(v0[2], v0[3]); w.z = cvt_pk_bf16(v1[0], v1[1]); w.w = cvt_pk_bf16(v1[2], v1[3]); return w; }
;     __device__ __forceinline__ void operator()(const f32x4 (&acc)[2][2][4][2], const Unit& u, int wr, int wc, int fr, int fq) const {
;         const int row0 = u.pm * BM + wr * 64 + fr; const bool first = fq < 2;
; #pragma unroll
;         for (int ai = 0; ai < 2; ++ai)
; #pragma unroll
;             for (int m = 0; m < 4; ++m) { const int row = row0 + ai * HALF + m * 16; const float rs = __builtin_amdgcn_rsqf(ssq[row] * (1.f / 512.f) + EPS) * QSCALE; const int t = row & (SEQ - 1);
; #pragma unroll
;                 for (int bj = 0; bj < 2; ++bj) { const int gcol = u.pn * 8 + bj * 4 + wc, hg = gcol % 6;
;                     f32x4 v0 = acc[ai][bj][m][0] * rs, v1 = acc[ai][bj][m][1] * rs;
;                     if (hg >= 4) { const int pos = hg == 4 ? (t >> 6) : (t & 63); const f32x2* tp = tab + pos * 16 + 8 * (fq & 1);
;                         f32x4 p0, p1;
; #pragma unroll
;                         for (int j = 0; j < 4; ++j) { p0[j] = __shfl_xor(v0[j], 32); p1[j] = __shfl_xor(v1[j], 32); }
; #pragma unroll
;                         for (int j = 0; j < 4; ++j) { const f32x2 c0 = tp[j], c1 = tp[4 + j];
;                             v0[j] = first ? (v0[j] * c0.x - p0[j] * c0.y) : (p0[j] * c0.y + v0[j] * c0.x);
;                             v1[j] = first ? (v1[j] * c1.x - p1[j] * c1.y) : (p1[j] * c1.y + v1[j] * c1.x); } }
;                     *(u32x4*)(Q + (size_t)row * 3072 + gcol * 32 + 8 * fq) = pack8(v0, v1); } }
;     }
.LBB0_985:
	v_add_u32_e32 v18, 0xb0, v148
	v_cvt_pk_bf16_f32 v12, v12, v13
	v_cvt_pk_bf16_f32 v13, v14, v15
	v_cvt_pk_bf16_f32 v14, v8, v9
	v_mov_b64_e32 v[8:9], s[16:17]
	v_mad_i64_i32 v[8:9], s[4:5], v18, s71, v[8:9]
	v_cvt_pk_bf16_f32 v15, v10, v11
	v_lshl_add_u64 v[10:11], s[44:45], 1, v[8:9]
	v_lshl_add_u64 v[10:11], v[10:11], 0, v[136:137]
	v_mov_b32_e32 v17, v16
	global_store_dwordx4 v[10:11], v[12:15], off nt
	v_mov_b32_e32 v10, v16
	v_mov_b32_e32 v11, v16
	v_pk_mul_f32 v[6:7], v[6:7], v[10:11]
	v_pk_mul_f32 v[4:5], v[4:5], v[16:17]
	v_pk_mul_f32 v[2:3], v[2:3], v[10:11]
	s_and_b64 vcc, exec, s[6:7]
	v_pk_mul_f32 v[0:1], v[0:1], v[16:17]
	s_cbranch_vccnz .LBB0_987
	s_cmp_eq_u32 s35, 4
	s_cselect_b64 vcc, -1, 0
	v_cndmask_b32_e32 v10, v165, v66, vcc
	v_lshlrev_b32_e32 v10, 7, v10
	v_mov_b32_e32 v11, v137
	v_lshl_add_u64 v[22:23], v[138:139], 0, v[10:11]
	global_load_dwordx4 v[10:13], v[22:23], off
	global_load_dwordx4 v[14:17], v[22:23], off offset:32
	global_load_dwordx4 v[18:21], v[22:23], off offset:16
	s_nop 0
	global_load_dwordx4 v[22:25], v[22:23], off offset:48
	v_and_b32_e32 v27, 64, v170
	v_xor_b32_e32 v26, 32, v170
	v_add_u32_e32 v27, 64, v27
	v_cmp_lt_i32_e32 vcc, v26, v27
	s_waitcnt vmcnt(3)
	v_mov_b32_e32 v35, v12
	v_cndmask_b32_e32 v26, v170, v26, vcc
	v_lshlrev_b32_e32 v33, 2, v26
	ds_bpermute_b32 v26, v33, v4
	ds_bpermute_b32 v28, v33, v0
	ds_bpermute_b32 v27, v33, v5
	ds_bpermute_b32 v29, v33, v1
	ds_bpermute_b32 v30, v33, v6
	ds_bpermute_b32 v32, v33, v2
	ds_bpermute_b32 v31, v33, v7
	ds_bpermute_b32 v33, v33, v3
	v_mov_b32_e32 v12, v11
	s_waitcnt vmcnt(2)
	v_mov_b32_e32 v11, v16
	v_mov_b32_e32 v16, v15
	s_waitcnt vmcnt(1)
	v_mov_b32_e32 v15, v20
	v_mov_b32_e32 v20, v19
	s_waitcnt vmcnt(0)
	v_mov_b32_e32 v19, v24
	v_mov_b32_e32 v24, v23
	v_mov_b32_e32 v34, v10
	v_mov_b32_e32 v10, v14
	v_mov_b32_e32 v14, v18
	v_mov_b32_e32 v18, v22
	s_waitcnt lgkmcnt(5)
	v_pk_mul_f32 v[12:13], v[12:13], v[26:27]
	s_waitcnt lgkmcnt(4)
	v_pk_mul_f32 v[16:17], v[16:17], v[28:29]
	s_waitcnt lgkmcnt(1)
	v_pk_mul_f32 v[20:21], v[20:21], v[30:31]
	s_waitcnt lgkmcnt(0)
	v_pk_mul_f32 v[22:23], v[24:25], v[32:33]
	v_cndmask_b32_e64 v13, v13, -v13, s[0:1]
	v_cndmask_b32_e64 v12, v12, -v12, s[0:1]
	v_cndmask_b32_e64 v17, v17, -v17, s[0:1]
	v_cndmask_b32_e64 v16, v16, -v16, s[0:1]
	v_cndmask_b32_e64 v21, v21, -v21, s[0:1]
	v_cndmask_b32_e64 v20, v20, -v20, s[0:1]
	v_cndmask_b32_e64 v23, v23, -v23, s[0:1]
	v_cndmask_b32_e64 v22, v22, -v22, s[0:1]
	v_pk_fma_f32 v[4:5], v[4:5], v[34:35], v[12:13]
	v_pk_fma_f32 v[0:1], v[0:1], v[10:11], v[16:17]
	v_pk_fma_f32 v[6:7], v[6:7], v[14:15], v[20:21]
	v_pk_fma_f32 v[2:3], v[2:3], v[18:19], v[22:23]
.LBB0_987:
	v_cvt_pk_bf16_f32 v4, v4, v5
	v_cvt_pk_bf16_f32 v5, v6, v7
	v_cvt_pk_bf16_f32 v6, v0, v1
	v_lshl_add_u64 v[0:1], s[46:47], 1, v[8:9]
	v_lshl_add_u64 v[0:1], v[0:1], 0, v[136:137]
	s_andn2_b64 vcc, exec, s[8:9]
	s_mov_b64 s[4:5], -1
	v_cvt_pk_bf16_f32 v7, v2, v3
	global_store_dwordx4 v[0:1], v[4:7], off nt
	s_cbranch_vccnz .LBB0_948
	s_andn2_b64 vcc, exec, s[24:25]
	s_cbranch_vccnz .LBB0_947
	s_barrier
	s_branch .LBB0_947

; __device__ __forceinline__ u32x4 pack8(f32x4 v0, f32x4 v1) { u32x4 w; w.x = cvt_pk_bf16(v0[0], v0[1]); w.y = cvt_pk_bf16(v0[2], v0[3]); w.z = cvt_pk_bf16(v1[0], v1[1]); w.w = cvt_pk_bf16(v1[2], v1[3]); return w; }
;     __device__ __forceinline__ void operator()(const f32x4 (&acc)[2][2][4][2], const Unit& u, int wr, int wc, int fr, int fq) const {
;         const int row0 = u.pm * BM + wr * 64 + fr, col0 = u.pn * 128 + wc * 32 + 8 * fq;
; #pragma unroll
;         for (int ai = 0; ai < 2; ++ai)
; #pragma unroll
;             for (int m = 0; m < 4; ++m) { const int row = row0 + ai * HALF + m * 16; const float rs = __builtin_amdgcn_rsqf(ssq[row] * (1.f / 512.f) + EPS);
;                 *(u32x4*)(KN + (size_t)row * DM + col0) = pack8(acc[ai][0][m][0] * rs, acc[ai][0][m][1] * rs);
;                 *(u32x4*)(V + (size_t)row * DM + col0) = pack8(acc[ai][1][m][0] * rs, acc[ai][1][m][1] * rs); }
;     }
.LBB0_1003:
	v_lshl_add_u32 v158, s30, 8, v150
	v_ashrrev_i32_e32 v159, 31, v158
	v_lshl_add_u64 v[146:147], v[158:159], 2, s[6:7]
	global_load_dword v157, v[146:147], off
	v_lshl_or_b32 v144, s68, 7, v152
	v_ashrrev_i32_e32 v145, 31, v144
	v_lshlrev_b64 v[148:149], 12, v[158:159]
	v_or_b32_e32 v160, 16, v158
	v_lshlrev_b64 v[144:145], 1, v[144:145]
	v_lshl_add_u64 v[162:163], s[12:13], 0, v[148:149]
	v_lshl_add_u64 v[164:165], s[20:21], 0, v[148:149]
	v_ashrrev_i32_e32 v161, 31, v160
	v_lshl_add_u64 v[162:163], v[162:163], 0, v[144:145]
	v_lshl_add_u64 v[164:165], v[164:165], 0, v[144:145]
	v_lshl_add_u64 v[168:169], v[160:161], 2, s[6:7]
	s_andn2_b64 vcc, exec, s[0:1]
	s_mov_b64 s[0:1], -1
	s_waitcnt vmcnt(0)
	v_fmamk_f32 v157, v157, 0x3b000000, v156
	v_rsq_f32_e32 v166, v157
	s_nop 0
	v_pk_mul_f32 v[126:127], v[126:127], v[166:167] op_sel_hi:[1,0]
	v_pk_mul_f32 v[124:125], v[124:125], v[166:167] op_sel_hi:[1,0]
	v_pk_mul_f32 v[122:123], v[122:123], v[166:167] op_sel_hi:[1,0]
	v_pk_mul_f32 v[120:121], v[120:121], v[166:167] op_sel_hi:[1,0]
	v_pk_mul_f32 v[118:119], v[118:119], v[166:167] op_sel_hi:[1,0]
	v_pk_mul_f32 v[116:117], v[116:117], v[166:167] op_sel_hi:[1,0]
	v_pk_mul_f32 v[170:171], v[114:115], v[166:167] op_sel_hi:[1,0]
	v_pk_mul_f32 v[166:167], v[112:113], v[166:167] op_sel_hi:[1,0]
	v_cvt_pk_bf16_f32 v112, v124, v125
	v_cvt_pk_bf16_f32 v113, v126, v127
	v_cvt_pk_bf16_f32 v114, v120, v121
	v_cvt_pk_bf16_f32 v115, v122, v123
	global_store_dwordx4 v[162:163], v[112:115], off nt
	s_nop 1
	v_cvt_pk_bf16_f32 v112, v116, v117
	v_cvt_pk_bf16_f32 v113, v118, v119
	v_cvt_pk_bf16_f32 v114, v166, v167
	v_cvt_pk_bf16_f32 v115, v170, v171
	global_store_dwordx4 v[164:165], v[112:115], off nt
	global_load_dword v120, v[168:169], off
	s_waitcnt vmcnt(0)
	v_fmamk_f32 v120, v120, 0x3b000000, v156
	v_rsq_f32_e32 v120, v120
	v_lshlrev_b64 v[114:115], 12, v[160:161]
	v_or_b32_e32 v112, 32, v158
	v_lshl_add_u64 v[118:119], s[12:13], 0, v[114:115]
	v_lshl_add_u64 v[114:115], s[20:21], 0, v[114:115]
	v_ashrrev_i32_e32 v113, 31, v112
	v_lshl_add_u64 v[118:119], v[118:119], 0, v[144:145]
	v_lshl_add_u64 v[114:115], v[114:115], 0, v[144:145]
	v_pk_mul_f32 v[110:111], v[110:111], v[120:121] op_sel_hi:[1,0]
	v_pk_mul_f32 v[108:109], v[108:109], v[120:121] op_sel_hi:[1,0]
	v_pk_mul_f32 v[106:107], v[106:107], v[120:121] op_sel_hi:[1,0]
	v_pk_mul_f32 v[104:105], v[104:105], v[120:121] op_sel_hi:[1,0]
	v_pk_mul_f32 v[102:103], v[102:103], v[120:121] op_sel_hi:[1,0]
	v_pk_mul_f32 v[100:101], v[100:101], v[120:121] op_sel_hi:[1,0]
	v_pk_mul_f32 v[122:123], v[98:99], v[120:121] op_sel_hi:[1,0]
	v_pk_mul_f32 v[120:121], v[96:97], v[120:121] op_sel_hi:[1,0]
	v_cvt_pk_bf16_f32 v96, v108, v109
	v_cvt_pk_bf16_f32 v97, v110, v111
	v_cvt_pk_bf16_f32 v98, v104, v105
	v_cvt_pk_bf16_f32 v99, v106, v107
	v_lshl_add_u64 v[116:117], v[112:113], 2, s[6:7]
	global_store_dwordx4 v[118:119], v[96:99], off nt
	s_nop 1
	v_cvt_pk_bf16_f32 v96, v100, v101
	v_cvt_pk_bf16_f32 v97, v102, v103
	v_cvt_pk_bf16_f32 v98, v120, v121
	v_cvt_pk_bf16_f32 v99, v122, v123
	global_store_dwordx4 v[114:115], v[96:99], off nt
	global_load_dword v104, v[116:117], off
	s_waitcnt vmcnt(0)
	v_fmamk_f32 v104, v104, 0x3b000000, v156
	v_rsq_f32_e32 v104, v104
	v_lshlrev_b64 v[98:99], 12, v[112:113]
	v_or_b32_e32 v96, 48, v158
	v_lshl_add_u64 v[102:103], s[12:13], 0, v[98:99]
	v_lshl_add_u64 v[98:99], s[20:21], 0, v[98:99]
	v_ashrrev_i32_e32 v97, 31, v96
	v_lshl_add_u64 v[102:103], v[102:103], 0, v[144:145]
	v_lshl_add_u64 v[98:99], v[98:99], 0, v[144:145]
	v_pk_mul_f32 v[94:95], v[94:95], v[104:105] op_sel_hi:[1,0]
	v_pk_mul_f32 v[92:93], v[92:93], v[104:105] op_sel_hi:[1,0]
	v_pk_mul_f32 v[90:91], v[90:91], v[104:105] op_sel_hi:[1,0]
	v_pk_mul_f32 v[88:89], v[88:89], v[104:105] op_sel_hi:[1,0]
	v_pk_mul_f32 v[86:87], v[86:87], v[104:105] op_sel_hi:[1,0]
	v_pk_mul_f32 v[84:85], v[84:85], v[104:105] op_sel_hi:[1,0]
	v_pk_mul_f32 v[106:107], v[82:83], v[104:105] op_sel_hi:[1,0]
	v_pk_mul_f32 v[104:105], v[80:81], v[104:105] op_sel_hi:[1,0]
	v_cvt_pk_bf16_f32 v80, v92, v93
	v_cvt_pk_bf16_f32 v81, v94, v95
	v_cvt_pk_bf16_f32 v82, v88, v89
	v_cvt_pk_bf16_f32 v83, v90, v91
	v_lshl_add_u64 v[100:101], v[96:97], 2, s[6:7]
	global_store_dwordx4 v[102:103], v[80:83], off nt
	s_nop 1
	v_cvt_pk_bf16_f32 v80, v84, v85
	v_cvt_pk_bf16_f32 v81, v86, v87
	v_cvt_pk_bf16_f32 v82, v104, v105
	v_cvt_pk_bf16_f32 v83, v106, v107
	global_store_dwordx4 v[98:99], v[80:83], off nt
	global_load_dword v84, v[100:101], off
	s_waitcnt vmcnt(0)
	v_fmamk_f32 v84, v84, 0x3b000000, v156
	v_rsq_f32_e32 v84, v84
	v_lshlrev_b64 v[80:81], 12, v[96:97]
	v_lshl_add_u64 v[82:83], s[12:13], 0, v[80:81]
	v_lshl_add_u64 v[80:81], s[20:21], 0, v[80:81]
	v_lshl_add_u64 v[82:83], v[82:83], 0, v[144:145]
	v_lshl_add_u64 v[80:81], v[80:81], 0, v[144:145]
	v_pk_mul_f32 v[78:79], v[78:79], v[84:85] op_sel_hi:[1,0]
	v_pk_mul_f32 v[76:77], v[76:77], v[84:85] op_sel_hi:[1,0]
	v_pk_mul_f32 v[74:75], v[74:75], v[84:85] op_sel_hi:[1,0]
	v_pk_mul_f32 v[72:73], v[72:73], v[84:85] op_sel_hi:[1,0]
	v_pk_mul_f32 v[70:71], v[70:71], v[84:85] op_sel_hi:[1,0]
	v_pk_mul_f32 v[68:69], v[68:69], v[84:85] op_sel_hi:[1,0]
	v_pk_mul_f32 v[86:87], v[66:67], v[84:85] op_sel_hi:[1,0]
	v_pk_mul_f32 v[84:85], v[64:65], v[84:85] op_sel_hi:[1,0]
	v_cvt_pk_bf16_f32 v64, v76, v77
	v_cvt_pk_bf16_f32 v65, v78, v79
	v_cvt_pk_bf16_f32 v66, v72, v73
	v_cvt_pk_bf16_f32 v67, v74, v75
	global_store_dwordx4 v[82:83], v[64:67], off nt
	s_nop 1
	v_cvt_pk_bf16_f32 v64, v68, v69
	v_cvt_pk_bf16_f32 v65, v70, v71
	v_cvt_pk_bf16_f32 v66, v84, v85
	v_cvt_pk_bf16_f32 v67, v86, v87
	global_store_dwordx4 v[80:81], v[64:67], off nt
	global_load_dword v68, v[146:147], off offset:512
	s_waitcnt vmcnt(0)
; __device__ __forceinline__ u32x4 pack8(f32x4 v0, f32x4 v1) { u32x4 w; w.x = cvt_pk_bf16(v0[0], v0[1]); w.y = cvt_pk_bf16(v0[2], v0[3]); w.z = cvt_pk_bf16(v1[0], v1[1]); w.w = cvt_pk_bf16(v1[2], v1[3]); return w; }
;     __device__ __forceinline__ void operator()(const f32x4 (&acc)[2][2][4][2], const Unit& u, int wr, int wc, int fr, int fq) const {
;         const int row0 = u.pm * BM + wr * 64 + fr, col0 = u.pn * 128 + wc * 32 + 8 * fq;
; #pragma unroll
;         for (int ai = 0; ai < 2; ++ai)
; #pragma unroll
;             for (int m = 0; m < 4; ++m) { const int row = row0 + ai * HALF + m * 16; const float rs = __builtin_amdgcn_rsqf(ssq[row] * (1.f / 512.f) + EPS);
;                 *(u32x4*)(KN + (size_t)row * DM + col0) = pack8(acc[ai][0][m][0] * rs, acc[ai][0][m][1] * rs);
;                 *(u32x4*)(V + (size_t)row * DM + col0) = pack8(acc[ai][1][m][0] * rs, acc[ai][1][m][1] * rs); }
;     }
	v_fmamk_f32 v68, v68, 0x3b000000, v156
	v_rsq_f32_e32 v68, v68
	v_lshl_add_u64 v[64:65], v[148:149], 0, s[24:25]
	v_lshl_add_u64 v[66:67], s[12:13], 0, v[64:65]
	v_lshl_add_u64 v[64:65], s[20:21], 0, v[64:65]
	v_lshl_add_u64 v[66:67], v[66:67], 0, v[144:145]
	v_lshl_add_u64 v[64:65], v[64:65], 0, v[144:145]
	v_pk_mul_f32 v[62:63], v[62:63], v[68:69] op_sel_hi:[1,0]
	v_pk_mul_f32 v[60:61], v[60:61], v[68:69] op_sel_hi:[1,0]
	v_pk_mul_f32 v[58:59], v[58:59], v[68:69] op_sel_hi:[1,0]
	v_pk_mul_f32 v[56:57], v[56:57], v[68:69] op_sel_hi:[1,0]
	v_pk_mul_f32 v[54:55], v[54:55], v[68:69] op_sel_hi:[1,0]
	v_pk_mul_f32 v[52:53], v[52:53], v[68:69] op_sel_hi:[1,0]
	v_pk_mul_f32 v[70:71], v[50:51], v[68:69] op_sel_hi:[1,0]
	v_pk_mul_f32 v[68:69], v[48:49], v[68:69] op_sel_hi:[1,0]
	v_cvt_pk_bf16_f32 v48, v60, v61
	v_cvt_pk_bf16_f32 v49, v62, v63
	v_cvt_pk_bf16_f32 v50, v56, v57
	v_cvt_pk_bf16_f32 v51, v58, v59
	global_store_dwordx4 v[66:67], v[48:51], off nt
	s_nop 1
	v_cvt_pk_bf16_f32 v48, v52, v53
	v_cvt_pk_bf16_f32 v49, v54, v55
	v_cvt_pk_bf16_f32 v50, v68, v69
	v_cvt_pk_bf16_f32 v51, v70, v71
	global_store_dwordx4 v[64:65], v[48:51], off nt
	global_load_dword v52, v[146:147], off offset:576
	s_waitcnt vmcnt(0)
	v_fmamk_f32 v52, v52, 0x3b000000, v156
	v_rsq_f32_e32 v52, v52
	v_lshl_add_u64 v[48:49], v[148:149], 0, s[26:27]
	v_lshl_add_u64 v[50:51], s[12:13], 0, v[48:49]
	v_lshl_add_u64 v[48:49], s[20:21], 0, v[48:49]
	v_lshl_add_u64 v[50:51], v[50:51], 0, v[144:145]
	v_lshl_add_u64 v[48:49], v[48:49], 0, v[144:145]
	v_pk_mul_f32 v[46:47], v[46:47], v[52:53] op_sel_hi:[1,0]
	v_pk_mul_f32 v[44:45], v[44:45], v[52:53] op_sel_hi:[1,0]
	v_pk_mul_f32 v[42:43], v[42:43], v[52:53] op_sel_hi:[1,0]
	v_pk_mul_f32 v[40:41], v[40:41], v[52:53] op_sel_hi:[1,0]
	v_pk_mul_f32 v[38:39], v[38:39], v[52:53] op_sel_hi:[1,0]
	v_pk_mul_f32 v[36:37], v[36:37], v[52:53] op_sel_hi:[1,0]
	v_pk_mul_f32 v[54:55], v[34:35], v[52:53] op_sel_hi:[1,0]
	v_pk_mul_f32 v[52:53], v[32:33], v[52:53] op_sel_hi:[1,0]
	v_cvt_pk_bf16_f32 v32, v44, v45
	v_cvt_pk_bf16_f32 v33, v46, v47
	v_cvt_pk_bf16_f32 v34, v40, v41
	v_cvt_pk_bf16_f32 v35, v42, v43
	global_store_dwordx4 v[50:51], v[32:35], off nt
	s_nop 1
	v_cvt_pk_bf16_f32 v32, v36, v37
	v_cvt_pk_bf16_f32 v33, v38, v39
	v_cvt_pk_bf16_f32 v34, v52, v53
	v_cvt_pk_bf16_f32 v35, v54, v55
	global_store_dwordx4 v[48:49], v[32:35], off nt
	global_load_dword v36, v[146:147], off offset:640
	s_waitcnt vmcnt(0)
	v_fmamk_f32 v36, v36, 0x3b000000, v156
	v_rsq_f32_e32 v36, v36
	v_lshl_add_u64 v[32:33], v[148:149], 0, s[28:29]
	v_lshl_add_u64 v[34:35], s[12:13], 0, v[32:33]
	v_lshl_add_u64 v[32:33], s[20:21], 0, v[32:33]
	v_lshl_add_u64 v[34:35], v[34:35], 0, v[144:145]
	v_lshl_add_u64 v[32:33], v[32:33], 0, v[144:145]
	v_pk_mul_f32 v[30:31], v[30:31], v[36:37] op_sel_hi:[1,0]
	v_pk_mul_f32 v[28:29], v[28:29], v[36:37] op_sel_hi:[1,0]
	v_pk_mul_f32 v[26:27], v[26:27], v[36:37] op_sel_hi:[1,0]
	v_pk_mul_f32 v[24:25], v[24:25], v[36:37] op_sel_hi:[1,0]
	v_pk_mul_f32 v[22:23], v[22:23], v[36:37] op_sel_hi:[1,0]
	v_pk_mul_f32 v[20:21], v[20:21], v[36:37] op_sel_hi:[1,0]
	v_pk_mul_f32 v[38:39], v[18:19], v[36:37] op_sel_hi:[1,0]
	v_pk_mul_f32 v[36:37], v[16:17], v[36:37] op_sel_hi:[1,0]
	v_cvt_pk_bf16_f32 v16, v28, v29
	v_cvt_pk_bf16_f32 v17, v30, v31
	v_cvt_pk_bf16_f32 v18, v24, v25
	v_cvt_pk_bf16_f32 v19, v26, v27
	global_store_dwordx4 v[34:35], v[16:19], off nt
	s_nop 1
	v_cvt_pk_bf16_f32 v16, v20, v21
	v_cvt_pk_bf16_f32 v17, v22, v23
	v_cvt_pk_bf16_f32 v18, v36, v37
	v_cvt_pk_bf16_f32 v19, v38, v39
	global_store_dwordx4 v[32:33], v[16:19], off nt
	global_load_dword v20, v[146:147], off offset:704
	s_waitcnt vmcnt(0)
	v_fmamk_f32 v20, v20, 0x3b000000, v156
	v_rsq_f32_e32 v20, v20
	v_lshl_add_u64 v[16:17], v[148:149], 0, s[36:37]
	v_lshl_add_u64 v[18:19], s[12:13], 0, v[16:17]
	v_lshl_add_u64 v[16:17], s[20:21], 0, v[16:17]
	v_lshl_add_u64 v[18:19], v[18:19], 0, v[144:145]
	v_lshl_add_u64 v[16:17], v[16:17], 0, v[144:145]
	v_pk_mul_f32 v[14:15], v[14:15], v[20:21] op_sel_hi:[1,0]
	v_pk_mul_f32 v[12:13], v[12:13], v[20:21] op_sel_hi:[1,0]
	v_pk_mul_f32 v[10:11], v[10:11], v[20:21] op_sel_hi:[1,0]
	v_pk_mul_f32 v[8:9], v[8:9], v[20:21] op_sel_hi:[1,0]
	v_pk_mul_f32 v[6:7], v[6:7], v[20:21] op_sel_hi:[1,0]
	v_pk_mul_f32 v[4:5], v[4:5], v[20:21] op_sel_hi:[1,0]
	v_pk_mul_f32 v[22:23], v[2:3], v[20:21] op_sel_hi:[1,0]
	v_pk_mul_f32 v[20:21], v[0:1], v[20:21] op_sel_hi:[1,0]
	v_cvt_pk_bf16_f32 v0, v12, v13
	v_cvt_pk_bf16_f32 v1, v14, v15
	v_cvt_pk_bf16_f32 v2, v8, v9
	v_cvt_pk_bf16_f32 v3, v10, v11
	global_store_dwordx4 v[18:19], v[0:3], off nt
	s_nop 1
	v_cvt_pk_bf16_f32 v0, v4, v5
	v_cvt_pk_bf16_f32 v1, v6, v7
	v_cvt_pk_bf16_f32 v2, v20, v21
	v_cvt_pk_bf16_f32 v3, v22, v23
	global_store_dwordx4 v[16:17], v[0:3], off nt
	s_cbranch_vccnz .LBB0_996
	s_andn2_b64 vcc, exec, s[4:5]
	s_cbranch_vccnz .LBB0_995
	s_barrier
	s_branch .LBB0_995

; #define SBAR() __builtin_amdgcn_sched_barrier(0)
; __device__ __forceinline__ void pv_d0(f32x16* o, int vb, bf16x8 pa0, bf16x8 pa1, bf16x8 pa2, bf16x8 pa3) {
;   VFrag fa, fb;
;   v_read8<0>(fa, vb); v_read8<1>(fb, vb);
;   asm volatile("s_waitcnt lgkmcnt(8)" ::: "memory"); SBAR(); pv_mma(o[0], fa, pa0, pa1, pa2, pa3); SBAR();
;   v_read8<2>(fa, vb);
;   asm volatile("s_waitcnt lgkmcnt(8)" ::: "memory"); SBAR(); pv_mma(o[1], fb, pa0, pa1, pa2, pa3); SBAR();
;   v_read8<3>(fb, vb);
;   asm volatile("s_waitcnt lgkmcnt(8)" ::: "memory"); SBAR(); pv_mma(o[2], fa, pa0, pa1, pa2, pa3); SBAR();
;   asm volatile("s_waitcnt lgkmcnt(0)" ::: "memory"); SBAR(); pv_mma(o[3], fb, pa0, pa1, pa2, pa3); SBAR();
; }
.LBB0_1090:
	s_cmp_eq_u32 s70, 0
	s_cbranch_scc1 .LBB0_1094
	s_add_i32 s4, s70, -1
	s_mul_i32 s4, s4, s63
	s_add_i32 s4, s4, s46
	s_lshl_b32 s5, s4, 4
	s_lshl_b32 s4, s4, 8
	s_and_b32 s6, s5, 0xfffff800
	s_and_b32 s4, s4, 0x700
	s_or_b32 s4, s6, s4
	v_add_u32_e32 v34, s4, v210
	v_ashrrev_i32_e32 v35, 31, v34
	v_lshlrev_b64 v[46:47], 11, v[34:35]
	s_and_b32 s4, s5, 0x780
	v_or_b32_e32 v33, s4, v46
	v_or_b32_e32 v46, v33, v184
	v_lshl_add_u64 v[34:35], v[46:47], 1, s[14:15]
	v_add_co_u32_e32 v36, vcc, s62, v34
	v_lshl_add_u32 v33, s72, 14, v209
	s_nop 0
	v_addc_co_u32_e32 v37, vcc, 0, v35, vcc
	v_add_co_u32_e32 v38, vcc, s64, v34
	s_nop 1
	v_addc_co_u32_e32 v39, vcc, 0, v35, vcc
	v_add_co_u32_e32 v214, vcc, s66, v34
	s_nop 1
	v_addc_co_u32_e32 v215, vcc, 0, v35, vcc
	global_load_dwordx4 v[160:163], v[34:35], off nt
	global_load_dwordx4 v[80:83], v[34:35], off offset:128 nt
	global_load_dwordx4 v[108:111], v[36:37], off nt
	global_load_dwordx4 v[42:45], v[36:37], off offset:128 nt
	global_load_dwordx4 v[104:107], v[38:39], off nt
	s_nop 0
	global_load_dwordx4 v[38:41], v[38:39], off offset:128 nt
	s_nop 0
	global_load_dwordx4 v[100:103], v[214:215], off nt
	global_load_dwordx4 v[34:37], v[214:215], off offset:128 nt
	ds_read_b64_tr_b16 v[214:215], v33 offset:0
	ds_read_b64_tr_b16 v[216:217], v33 offset:0x800
	ds_read_b64_tr_b16 v[218:219], v33 offset:0x1000
	ds_read_b64_tr_b16 v[220:221], v33 offset:0x1800
	ds_read_b64_tr_b16 v[222:223], v33 offset:0x2000
	ds_read_b64_tr_b16 v[224:225], v33 offset:0x2800
	ds_read_b64_tr_b16 v[226:227], v33 offset:0x3000
	ds_read_b64_tr_b16 v[228:229], v33 offset:0x3800
	ds_read_b64_tr_b16 v[230:231], v33 offset:0x200
	ds_read_b64_tr_b16 v[232:233], v33 offset:0xa00
	ds_read_b64_tr_b16 v[234:235], v33 offset:0x1200
	ds_read_b64_tr_b16 v[236:237], v33 offset:0x1a00
	ds_read_b64_tr_b16 v[238:239], v33 offset:0x2200
	ds_read_b64_tr_b16 v[240:241], v33 offset:0x2a00
	ds_read_b64_tr_b16 v[242:243], v33 offset:0x3200
	ds_read_b64_tr_b16 v[244:245], v33 offset:0x3a00
	s_waitcnt lgkmcnt(8)
	s_nop 0
	v_mfma_f32_32x32x16_bf16 v[64:79], v[96:99], v[214:217], v[64:79]
	v_mfma_f32_32x32x16_bf16 v[64:79], v[92:95], v[218:221], v[64:79]
	v_mfma_f32_32x32x16_bf16 v[64:79], v[88:91], v[222:225], v[64:79]
	v_mfma_f32_32x32x16_bf16 v[64:79], v[84:87], v[226:229], v[64:79]
	ds_read_b64_tr_b16 v[214:215], v33 offset:0x400
	ds_read_b64_tr_b16 v[216:217], v33 offset:0xc00
	ds_read_b64_tr_b16 v[218:219], v33 offset:0x1400
	ds_read_b64_tr_b16 v[220:221], v33 offset:0x1c00
	ds_read_b64_tr_b16 v[222:223], v33 offset:0x2400
	ds_read_b64_tr_b16 v[224:225], v33 offset:0x2c00
	ds_read_b64_tr_b16 v[226:227], v33 offset:0x3400
	ds_read_b64_tr_b16 v[228:229], v33 offset:0x3c00
	s_waitcnt lgkmcnt(8)
	v_mfma_f32_32x32x16_bf16 v[48:63], v[96:99], v[230:233], v[48:63]
	v_mfma_f32_32x32x16_bf16 v[48:63], v[92:95], v[234:237], v[48:63]
	v_mfma_f32_32x32x16_bf16 v[48:63], v[88:91], v[238:241], v[48:63]
	v_mfma_f32_32x32x16_bf16 v[48:63], v[84:87], v[242:245], v[48:63]
	ds_read_b64_tr_b16 v[230:231], v33 offset:0x600
	ds_read_b64_tr_b16 v[232:233], v33 offset:0xe00
	ds_read_b64_tr_b16 v[234:235], v33 offset:0x1600
	ds_read_b64_tr_b16 v[236:237], v33 offset:0x1e00
	ds_read_b64_tr_b16 v[238:239], v33 offset:0x2600
	ds_read_b64_tr_b16 v[240:241], v33 offset:0x2e00
	ds_read_b64_tr_b16 v[242:243], v33 offset:0x3600
	ds_read_b64_tr_b16 v[244:245], v33 offset:0x3e00
	s_waitcnt lgkmcnt(8)
	v_mfma_f32_32x32x16_bf16 v[16:31], v[96:99], v[214:217], v[16:31]
	v_mfma_f32_32x32x16_bf16 v[16:31], v[92:95], v[218:221], v[16:31]
	v_mfma_f32_32x32x16_bf16 v[16:31], v[88:91], v[222:225], v[16:31]
	v_mfma_f32_32x32x16_bf16 v[16:31], v[84:87], v[226:229], v[16:31]
	s_waitcnt lgkmcnt(0)
	v_mfma_f32_32x32x16_bf16 v[0:15], v[96:99], v[230:233], v[0:15]
	v_mfma_f32_32x32x16_bf16 v[0:15], v[92:95], v[234:237], v[0:15]
	v_mfma_f32_32x32x16_bf16 v[0:15], v[88:91], v[238:241], v[0:15]
	v_mfma_f32_32x32x16_bf16 v[0:15], v[84:87], v[242:245], v[0:15]
	s_and_saveexec_b64 s[4:5], s[0:1]
	ds_write_b32 v208, v187
	s_or_b64 exec, exec, s[4:5]
	s_waitcnt lgkmcnt(0)
	ds_read_b32 v230, v185
	ds_read_b32 v231, v185 offset:4
	ds_read_b32 v232, v185 offset:8
	ds_read_b32 v233, v185 offset:12
	ds_read_b32 v234, v185 offset:32
	ds_read_b32 v235, v185 offset:36
	ds_read_b32 v236, v185 offset:40
	ds_read_b32 v237, v185 offset:44
	ds_read_b32 v238, v185 offset:64
	ds_read_b32 v239, v185 offset:68
	ds_read_b32 v240, v185 offset:72
	ds_read_b32 v241, v185 offset:76
	ds_read_b32 v242, v185 offset:96
	ds_read_b32 v243, v185 offset:100
	ds_read_b32 v244, v185 offset:104
	ds_read_b32 v245, v185 offset:108
	s_waitcnt lgkmcnt(0)
	v_rcp_f32_e32 v230, v230
	v_rcp_f32_e32 v231, v231
	v_rcp_f32_e32 v232, v232
	v_rcp_f32_e32 v233, v233
	v_rcp_f32_e32 v234, v234
	v_rcp_f32_e32 v235, v235
	v_rcp_f32_e32 v236, v236
	v_rcp_f32_e32 v237, v237
	v_rcp_f32_e32 v238, v238
	v_rcp_f32_e32 v239, v239
	v_rcp_f32_e32 v240, v240
	v_rcp_f32_e32 v241, v241
	v_rcp_f32_e32 v242, v242
	v_rcp_f32_e32 v243, v243
	v_rcp_f32_e32 v244, v244
	v_rcp_f32_e32 v245, v245
	s_nop 0
	v_add_u32_e32 v84, v190, v207
	v_lshl_add_u64 v[46:47], v[46:47], 1, s[18:19]
	v_mov_b32_e32 v187, 0
	s_nop 0
	v_mul_f32_e32 v64, v64, v230
	v_mul_f32_e32 v33, v48, v230
	v_cvt_pk_bf16_f32 v48, v64, v32
	ds_write_b16 v84, v48
	v_cvt_pk_bf16_f32 v33, v33, v32
	ds_write_b16 v84, v33 offset:64
	v_add_u32_e32 v64, v190, v206
	s_nop 0
	v_mul_f32_e32 v33, v65, v231
	v_mul_f32_e32 v48, v49, v231
	v_cvt_pk_bf16_f32 v33, v33, v32
	ds_write_b16 v64, v33
	v_cvt_pk_bf16_f32 v33, v48, v32
	ds_write_b16 v64, v33 offset:64
	v_add_u32_e32 v65, v190, v205
	s_nop 0
	v_mul_f32_e32 v33, v66, v232
	v_mul_f32_e32 v48, v50, v232
	v_cvt_pk_bf16_f32 v33, v33, v32
	ds_write_b16 v65, v33
	v_cvt_pk_bf16_f32 v33, v48, v32
	ds_write_b16 v65, v33 offset:64
	v_add_u32_e32 v66, v190, v204
	s_nop 0
	v_mul_f32_e32 v33, v67, v233
	v_mul_f32_e32 v48, v51, v233
	v_cvt_pk_bf16_f32 v33, v33, v32
	ds_write_b16 v66, v33
	v_cvt_pk_bf16_f32 v33, v48, v32
	ds_write_b16 v66, v33 offset:64
	v_add_u32_e32 v67, v190, v203
	s_nop 0
	v_mul_f32_e32 v33, v68, v234
	v_mul_f32_e32 v48, v52, v234
	v_cvt_pk_bf16_f32 v33, v33, v32
	ds_write_b16 v67, v33
	v_cvt_pk_bf16_f32 v33, v48, v32
	ds_write_b16 v67, v33 offset:64
	v_add_u32_e32 v68, v190, v202
	s_waitcnt vmcnt(0)
	v_lshlrev_b32_e32 v52, 16, v160
	s_nop 0
	v_mul_f32_e32 v33, v69, v235
	v_mul_f32_e32 v48, v53, v235
	v_cvt_pk_bf16_f32 v33, v33, v32
	ds_write_b16 v68, v33
	v_cvt_pk_bf16_f32 v33, v48, v32
	ds_write_b16 v68, v33 offset:64
	v_add_u32_e32 v69, v190, v201
	v_and_b32_e32 v53, 0xffff0000, v160
	v_mov_b32_e32 v160, 0xf149f2ca
	s_nop 0
	v_mul_f32_e32 v33, v70, v236
	v_mul_f32_e32 v48, v54, v236
	v_cvt_pk_bf16_f32 v33, v33, v32
	ds_write_b16 v69, v33
	v_cvt_pk_bf16_f32 v33, v48, v32
	ds_write_b16 v69, v33 offset:64
	v_add_u32_e32 v70, v190, v200
	v_lshlrev_b32_e32 v54, 16, v161
	s_nop 0
	v_mul_f32_e32 v33, v71, v237
	v_mul_f32_e32 v48, v55, v237
	v_cvt_pk_bf16_f32 v33, v33, v32
	ds_write_b16 v70, v33
	v_cvt_pk_bf16_f32 v33, v48, v32
	ds_write_b16 v70, v33 offset:64
	v_add_u32_e32 v71, v190, v199
	v_and_b32_e32 v55, 0xffff0000, v161
	s_nop 0
	v_mul_f32_e32 v33, v72, v238
	v_mul_f32_e32 v48, v56, v238
	v_cvt_pk_bf16_f32 v33, v33, v32
	ds_write_b16 v71, v33
	v_cvt_pk_bf16_f32 v33, v48, v32
	ds_write_b16 v71, v33 offset:64
	v_add_u32_e32 v72, v190, v197
	v_lshlrev_b32_e32 v56, 16, v162
	s_nop 0
	v_mul_f32_e32 v33, v73, v239
	v_mul_f32_e32 v48, v57, v239
	v_cvt_pk_bf16_f32 v33, v33, v32
	ds_write_b16 v72, v33
	v_cvt_pk_bf16_f32 v33, v48, v32
	ds_write_b16 v72, v33 offset:64
	v_add_u32_e32 v73, v190, v196
	v_and_b32_e32 v57, 0xffff0000, v162
	s_nop 0
	v_mul_f32_e32 v33, v74, v240
	v_mul_f32_e32 v48, v58, v240
	v_cvt_pk_bf16_f32 v33, v33, v32
	ds_write_b16 v73, v33
	v_cvt_pk_bf16_f32 v33, v48, v32
	ds_write_b16 v73, v33 offset:64
	v_add_u32_e32 v74, v190, v195
	v_and_b32_e32 v58, 0xffff0000, v163
	s_nop 0
	v_mul_f32_e32 v33, v75, v241
	v_mul_f32_e32 v48, v59, v241
	v_cvt_pk_bf16_f32 v33, v33, v32
	ds_write_b16 v74, v33
	v_cvt_pk_bf16_f32 v33, v48, v32
	ds_write_b16 v74, v33 offset:64
	v_add_u32_e32 v75, v190, v194
	s_waitcnt vmcnt(5)
	v_lshlrev_b32_e32 v59, 16, v108
	s_nop 0
	v_mul_f32_e32 v33, v76, v242
	v_mul_f32_e32 v48, v60, v242
	v_cvt_pk_bf16_f32 v33, v33, v32
	ds_write_b16 v75, v33
	v_cvt_pk_bf16_f32 v33, v48, v32
	ds_write_b16 v75, v33 offset:64
	v_add_u32_e32 v60, v190, v193
	v_add_u32_e32 v76, v190, v191
	s_nop 0
	v_mul_f32_e32 v33, v77, v243
	v_mul_f32_e32 v48, v61, v243
	v_cvt_pk_bf16_f32 v33, v33, v32
	ds_write_b16 v60, v33
	v_cvt_pk_bf16_f32 v33, v48, v32
	ds_write_b16 v60, v33 offset:64
	v_add_u32_e32 v61, v190, v192
	v_add_u32_e32 v77, v188, v189
	s_nop 0
	v_mul_f32_e32 v33, v78, v244
	v_mul_f32_e32 v48, v62, v244
	v_cvt_pk_bf16_f32 v33, v33, v32
	ds_write_b16 v61, v33
	v_cvt_pk_bf16_f32 v33, v48, v32
	ds_write_b16 v61, v33 offset:64
	v_and_b32_e32 v62, 0xffff0000, v108
	s_nop 0
	v_mul_f32_e32 v33, v79, v245
	v_cvt_pk_bf16_f32 v33, v33, v32
	v_mul_f32_e32 v48, v63, v245
	ds_write_b16 v76, v33
	v_cvt_pk_bf16_f32 v33, v48, v32
	ds_write_b16 v76, v33 offset:64
	s_waitcnt lgkmcnt(0)
	ds_read_b128 v[214:217], v77
	ds_read_b128 v[218:221], v77 offset:1024
	ds_read_b128 v[222:225], v77 offset:2048
	ds_read_b128 v[226:229], v77 offset:3072
	v_lshlrev_b32_e32 v33, 16, v163
	s_waitcnt lgkmcnt(0)
	v_lshlrev_b32_e32 v63, 16, v214
	v_and_b32_e32 v48, 0xffff0000, v214
	v_lshlrev_b32_e32 v78, 16, v215
	v_and_b32_e32 v49, 0xffff0000, v215
	v_lshlrev_b32_e32 v79, 16, v216
	v_and_b32_e32 v50, 0xffff0000, v216
	v_lshlrev_b32_e32 v85, 16, v217
	v_and_b32_e32 v51, 0xffff0000, v217
	v_mul_f32_e32 v52, v63, v52
	v_mul_f32_e32 v48, v48, v53
	v_mul_f32_e32 v53, v78, v54
	v_mul_f32_e32 v49, v49, v55
	v_mul_f32_e32 v54, v79, v56
	v_mul_f32_e32 v50, v50, v57
	v_mul_f32_e32 v51, v51, v58
	v_mul_f32_e32 v33, v85, v33
	v_cvt_pk_bf16_f32 v48, v52, v48
	v_cvt_pk_bf16_f32 v49, v53, v49
	v_cvt_pk_bf16_f32 v50, v54, v50
	v_cvt_pk_bf16_f32 v51, v33, v51
	global_store_dwordx4 v[46:47], v[48:51], off nt
	v_lshlrev_b32_e32 v33, 16, v109
	v_and_b32_e32 v56, 0xffff0000, v109
	v_lshlrev_b32_e32 v57, 16, v110
	s_waitcnt lgkmcnt(0)
	v_lshlrev_b32_e32 v48, 16, v218
	v_and_b32_e32 v49, 0xffff0000, v218
	v_lshlrev_b32_e32 v50, 16, v219
	v_and_b32_e32 v51, 0xffff0000, v219
	v_mul_f32_e32 v48, v48, v59
	v_mul_f32_e32 v49, v49, v62
	v_lshlrev_b32_e32 v52, 16, v220
	v_mul_f32_e32 v33, v50, v33
	v_mul_f32_e32 v51, v51, v56
	v_cvt_pk_bf16_f32 v50, v48, v49
	v_and_b32_e32 v48, 0xffff0000, v220
	v_and_b32_e32 v49, 0xffff0000, v110
	v_cvt_pk_bf16_f32 v51, v33, v51
	v_mul_f32_e32 v33, v52, v57
	v_mul_f32_e32 v48, v48, v49
	v_cvt_pk_bf16_f32 v52, v33, v48
	v_lshlrev_b32_e32 v33, 16, v111
	v_lshlrev_b32_e32 v48, 16, v221
	v_mul_f32_e32 v33, v48, v33
	v_and_b32_e32 v48, 0xffff0000, v221
	v_and_b32_e32 v49, 0xffff0000, v111
	v_mul_f32_e32 v48, v48, v49
	v_cvt_pk_bf16_f32 v53, v33, v48
	v_add_co_u32_e32 v48, vcc, s62, v46
	s_waitcnt vmcnt(4)
	v_lshlrev_b32_e32 v33, 16, v104
	v_addc_co_u32_e32 v49, vcc, 0, v47, vcc
	global_store_dwordx4 v[48:49], v[50:53], off nt
	s_waitcnt lgkmcnt(0)
	s_nop 0
	v_lshlrev_b32_e32 v50, 16, v222
	v_mul_f32_e32 v33, v50, v33
	v_and_b32_e32 v50, 0xffff0000, v222
	v_and_b32_e32 v51, 0xffff0000, v104
	v_mul_f32_e32 v50, v50, v51
	v_cvt_pk_bf16_f32 v52, v33, v50
	v_lshlrev_b32_e32 v33, 16, v105
	v_lshlrev_b32_e32 v50, 16, v223
	v_mul_f32_e32 v33, v50, v33
	v_and_b32_e32 v50, 0xffff0000, v223
	v_and_b32_e32 v51, 0xffff0000, v105
	v_mul_f32_e32 v50, v50, v51
	v_cvt_pk_bf16_f32 v53, v33, v50
	v_lshlrev_b32_e32 v33, 16, v106
	v_lshlrev_b32_e32 v50, 16, v224
	v_mul_f32_e32 v33, v50, v33
	v_and_b32_e32 v50, 0xffff0000, v224
	v_and_b32_e32 v51, 0xffff0000, v106
	v_mul_f32_e32 v50, v50, v51
	v_cvt_pk_bf16_f32 v54, v33, v50
	v_lshlrev_b32_e32 v33, 16, v107
	v_lshlrev_b32_e32 v50, 16, v225
	v_mul_f32_e32 v33, v50, v33
	v_and_b32_e32 v50, 0xffff0000, v225
	v_and_b32_e32 v51, 0xffff0000, v107
	v_mul_f32_e32 v50, v50, v51
	v_cvt_pk_bf16_f32 v55, v33, v50
	v_add_co_u32_e32 v50, vcc, s64, v46
	s_waitcnt vmcnt(3)
	v_lshlrev_b32_e32 v33, 16, v100
	v_addc_co_u32_e32 v51, vcc, 0, v47, vcc
	global_store_dwordx4 v[50:51], v[52:55], off nt
	s_waitcnt lgkmcnt(0)
	s_nop 0
	v_lshlrev_b32_e32 v52, 16, v226
	v_mul_f32_e32 v33, v52, v33
	v_and_b32_e32 v52, 0xffff0000, v226
	v_and_b32_e32 v53, 0xffff0000, v100
	v_mul_f32_e32 v52, v52, v53
	v_cvt_pk_bf16_f32 v54, v33, v52
	v_lshlrev_b32_e32 v33, 16, v101
	v_lshlrev_b32_e32 v52, 16, v227
	v_mul_f32_e32 v33, v52, v33
	v_and_b32_e32 v52, 0xffff0000, v227
	v_and_b32_e32 v53, 0xffff0000, v101
	v_mul_f32_e32 v52, v52, v53
	v_cvt_pk_bf16_f32 v55, v33, v52
	v_lshlrev_b32_e32 v33, 16, v102
	v_lshlrev_b32_e32 v52, 16, v228
	v_mul_f32_e32 v33, v52, v33
	v_and_b32_e32 v52, 0xffff0000, v228
	v_and_b32_e32 v53, 0xffff0000, v102
	v_mul_f32_e32 v52, v52, v53
	v_cvt_pk_bf16_f32 v56, v33, v52
	v_lshlrev_b32_e32 v33, 16, v103
	v_lshlrev_b32_e32 v52, 16, v229
	v_mul_f32_e32 v33, v52, v33
	v_and_b32_e32 v52, 0xffff0000, v229
	v_and_b32_e32 v53, 0xffff0000, v103
	v_mul_f32_e32 v52, v52, v53
	v_cvt_pk_bf16_f32 v57, v33, v52
	v_add_co_u32_e32 v52, vcc, s66, v46
	s_nop 1
	v_addc_co_u32_e32 v53, vcc, 0, v47, vcc
	global_store_dwordx4 v[52:53], v[54:57], off nt
	s_waitcnt lgkmcnt(0)
	s_nop 0
	v_mul_f32_e32 v16, v16, v230
	v_cvt_pk_bf16_f32 v16, v16, v32
	v_mul_f32_e32 v0, v0, v230
	ds_write_b16 v84, v16
	v_cvt_pk_bf16_f32 v0, v0, v32
	ds_write_b16 v84, v0 offset:64
	v_mov_b32_e32 v33, v32
	s_nop 0
	v_mul_f32_e32 v0, v17, v231
	v_cvt_pk_bf16_f32 v0, v0, v32
	ds_write_b16 v64, v0
	v_mul_f32_e32 v0, v1, v231
	v_cvt_pk_bf16_f32 v0, v0, v32
	ds_write_b16 v64, v0 offset:64
	s_nop 0
	v_mul_f32_e32 v0, v18, v232
	v_cvt_pk_bf16_f32 v0, v0, v32
	ds_write_b16 v65, v0
	v_mul_f32_e32 v0, v2, v232
	v_cvt_pk_bf16_f32 v0, v0, v32
	ds_write_b16 v65, v0 offset:64
	s_nop 0
	v_mul_f32_e32 v0, v19, v233
	v_cvt_pk_bf16_f32 v0, v0, v32
	ds_write_b16 v66, v0
	v_mul_f32_e32 v0, v3, v233
	v_cvt_pk_bf16_f32 v0, v0, v32
	ds_write_b16 v66, v0 offset:64
	s_nop 0
	v_mul_f32_e32 v0, v20, v234
	v_cvt_pk_bf16_f32 v0, v0, v32
	ds_write_b16 v67, v0
	v_mul_f32_e32 v0, v4, v234
	v_cvt_pk_bf16_f32 v0, v0, v32
	ds_write_b16 v67, v0 offset:64
	v_lshlrev_b32_e32 v4, 16, v80
	s_nop 0
	v_mul_f32_e32 v0, v21, v235
	v_cvt_pk_bf16_f32 v0, v0, v32
	ds_write_b16 v68, v0
	v_mul_f32_e32 v0, v5, v235
	v_cvt_pk_bf16_f32 v0, v0, v32
	ds_write_b16 v68, v0 offset:64
	s_nop 0
	v_mul_f32_e32 v0, v22, v236
	v_cvt_pk_bf16_f32 v0, v0, v32
	ds_write_b16 v69, v0
	v_mul_f32_e32 v0, v6, v236
	v_cvt_pk_bf16_f32 v0, v0, v32
	ds_write_b16 v69, v0 offset:64
	s_nop 0
	v_mul_f32_e32 v0, v23, v237
	v_cvt_pk_bf16_f32 v0, v0, v32
	ds_write_b16 v70, v0
	v_mul_f32_e32 v0, v7, v237
	v_cvt_pk_bf16_f32 v0, v0, v32
	ds_write_b16 v70, v0 offset:64
	s_nop 0
	v_mul_f32_e32 v0, v24, v238
	v_cvt_pk_bf16_f32 v0, v0, v32
	ds_write_b16 v71, v0
	v_mul_f32_e32 v0, v8, v238
	v_cvt_pk_bf16_f32 v0, v0, v32
	ds_write_b16 v71, v0 offset:64
	s_nop 0
	v_mul_f32_e32 v0, v25, v239
	v_cvt_pk_bf16_f32 v0, v0, v32
	ds_write_b16 v72, v0
	v_mul_f32_e32 v0, v9, v239
	v_cvt_pk_bf16_f32 v0, v0, v32
	ds_write_b16 v72, v0 offset:64
	s_nop 0
	v_mul_f32_e32 v0, v26, v240
	v_cvt_pk_bf16_f32 v0, v0, v32
	ds_write_b16 v73, v0
	v_mul_f32_e32 v0, v10, v240
	v_cvt_pk_bf16_f32 v0, v0, v32
	ds_write_b16 v73, v0 offset:64
	s_nop 0
	v_mul_f32_e32 v0, v27, v241
	v_cvt_pk_bf16_f32 v0, v0, v32
	ds_write_b16 v74, v0
	v_mul_f32_e32 v0, v11, v241
	v_cvt_pk_bf16_f32 v0, v0, v32
	ds_write_b16 v74, v0 offset:64
	s_nop 0
	v_mul_f32_e32 v0, v28, v242
	v_cvt_pk_bf16_f32 v0, v0, v32
	ds_write_b16 v75, v0
	v_mul_f32_e32 v0, v12, v242
	v_cvt_pk_bf16_f32 v0, v0, v32
	ds_write_b16 v75, v0 offset:64
	s_nop 0
	v_mul_f32_e32 v0, v29, v243
	v_cvt_pk_bf16_f32 v0, v0, v32
	ds_write_b16 v60, v0
	v_mul_f32_e32 v0, v13, v243
	v_cvt_pk_bf16_f32 v0, v0, v32
	ds_write_b16 v60, v0 offset:64
	s_nop 0
	v_mul_f32_e32 v0, v30, v244
	v_cvt_pk_bf16_f32 v0, v0, v32
	ds_write_b16 v61, v0
	v_mul_f32_e32 v0, v14, v244
	v_cvt_pk_bf16_f32 v0, v0, v32
	ds_write_b16 v61, v0 offset:64
	s_nop 0
	v_mul_f32_e32 v0, v31, v245
	v_cvt_pk_bf16_f32 v0, v0, v32
	ds_write_b16 v76, v0
	v_mul_f32_e32 v0, v15, v245
	v_cvt_pk_bf16_f32 v0, v0, v32
	ds_write_b16 v76, v0 offset:64
	s_waitcnt lgkmcnt(0)
	ds_read_b128 v[214:217], v77
	ds_read_b128 v[218:221], v77 offset:1024
	ds_read_b128 v[222:225], v77 offset:2048
	ds_read_b128 v[226:229], v77 offset:3072
	s_waitcnt lgkmcnt(0)
; __device__ __forceinline__ void attn_phase(const bf16_t* __restrict__ Q, const bf16_t* __restrict__ KN, const bf16_t* __restrict__ KR, const bf16_t* __restrict__ V, ...
;     ...
;         m_reg = -1e30f; l_reg = 0;
; #pragma unroll
;         for (int d = 0; d < 4; ++d) o[d] = f32x16{};
	v_lshlrev_b32_e32 v5, 16, v214
	v_mul_f32_e32 v4, v5, v4
	v_and_b32_e32 v0, 0xffff0000, v214
	v_and_b32_e32 v5, 0xffff0000, v80
	v_mul_f32_e32 v0, v0, v5
	v_cvt_pk_bf16_f32 v0, v4, v0
	v_lshlrev_b32_e32 v4, 16, v81
	v_lshlrev_b32_e32 v5, 16, v215
	v_mul_f32_e32 v4, v5, v4
	v_and_b32_e32 v1, 0xffff0000, v215
	v_and_b32_e32 v5, 0xffff0000, v81
	v_mul_f32_e32 v1, v1, v5
	v_cvt_pk_bf16_f32 v1, v4, v1
	v_lshlrev_b32_e32 v4, 16, v82
	v_lshlrev_b32_e32 v5, 16, v216
	v_mul_f32_e32 v4, v5, v4
	v_and_b32_e32 v2, 0xffff0000, v216
	v_and_b32_e32 v5, 0xffff0000, v82
	v_mul_f32_e32 v2, v2, v5
	v_cvt_pk_bf16_f32 v2, v4, v2
	v_lshlrev_b32_e32 v4, 16, v83
	v_lshlrev_b32_e32 v5, 16, v217
	v_mul_f32_e32 v4, v5, v4
	v_and_b32_e32 v3, 0xffff0000, v217
	v_and_b32_e32 v5, 0xffff0000, v83
	v_mul_f32_e32 v3, v3, v5
	v_cvt_pk_bf16_f32 v3, v4, v3
	global_store_dwordx4 v[46:47], v[0:3], off offset:128 nt
	v_mov_b32_e32 v46, v32
	v_mov_b32_e32 v47, v32
	v_lshlrev_b32_e32 v0, 16, v42
	s_waitcnt lgkmcnt(0)
	v_lshlrev_b32_e32 v1, 16, v218
	v_mul_f32_e32 v0, v1, v0
	v_and_b32_e32 v1, 0xffff0000, v218
	v_and_b32_e32 v2, 0xffff0000, v42
	v_mul_f32_e32 v1, v1, v2
	v_cvt_pk_bf16_f32 v0, v0, v1
	v_lshlrev_b32_e32 v1, 16, v43
	v_lshlrev_b32_e32 v2, 16, v219
	v_mul_f32_e32 v1, v2, v1
	v_and_b32_e32 v2, 0xffff0000, v219
	v_and_b32_e32 v3, 0xffff0000, v43
	v_mul_f32_e32 v2, v2, v3
	v_cvt_pk_bf16_f32 v1, v1, v2
	v_lshlrev_b32_e32 v2, 16, v44
	v_lshlrev_b32_e32 v3, 16, v220
	v_mul_f32_e32 v2, v3, v2
	v_and_b32_e32 v3, 0xffff0000, v220
	v_and_b32_e32 v4, 0xffff0000, v44
	v_mul_f32_e32 v3, v3, v4
	v_cvt_pk_bf16_f32 v2, v2, v3
	v_lshlrev_b32_e32 v3, 16, v45
	v_lshlrev_b32_e32 v4, 16, v221
	v_mul_f32_e32 v3, v4, v3
	v_and_b32_e32 v4, 0xffff0000, v221
	v_and_b32_e32 v5, 0xffff0000, v45
	v_mul_f32_e32 v4, v4, v5
	v_cvt_pk_bf16_f32 v3, v3, v4
	global_store_dwordx4 v[48:49], v[0:3], off offset:128 nt
	v_mov_b32_e32 v42, v32
	v_mov_b32_e32 v43, v32
	v_lshlrev_b32_e32 v0, 16, v38
	s_waitcnt lgkmcnt(0)
	v_lshlrev_b32_e32 v1, 16, v222
	v_mul_f32_e32 v0, v1, v0
	v_and_b32_e32 v1, 0xffff0000, v222
	v_and_b32_e32 v2, 0xffff0000, v38
	v_mul_f32_e32 v1, v1, v2
	v_cvt_pk_bf16_f32 v0, v0, v1
	v_lshlrev_b32_e32 v1, 16, v39
	v_lshlrev_b32_e32 v2, 16, v223
	v_mul_f32_e32 v1, v2, v1
	v_and_b32_e32 v2, 0xffff0000, v223
	v_and_b32_e32 v3, 0xffff0000, v39
	v_mul_f32_e32 v2, v2, v3
	v_cvt_pk_bf16_f32 v1, v1, v2
	v_lshlrev_b32_e32 v2, 16, v40
	v_lshlrev_b32_e32 v3, 16, v224
	v_mul_f32_e32 v2, v3, v2
	v_and_b32_e32 v3, 0xffff0000, v224
	v_and_b32_e32 v4, 0xffff0000, v40
	v_mul_f32_e32 v3, v3, v4
	v_cvt_pk_bf16_f32 v2, v2, v3
	v_lshlrev_b32_e32 v3, 16, v41
	v_lshlrev_b32_e32 v4, 16, v225
	v_mul_f32_e32 v3, v4, v3
	v_and_b32_e32 v4, 0xffff0000, v225
	v_and_b32_e32 v5, 0xffff0000, v41
	v_mul_f32_e32 v4, v4, v5
	v_cvt_pk_bf16_f32 v3, v3, v4
	global_store_dwordx4 v[50:51], v[0:3], off offset:128 nt
	v_mov_b32_e32 v38, v32
	v_mov_b32_e32 v39, v32
	s_waitcnt vmcnt(7)
	v_lshlrev_b32_e32 v0, 16, v34
	s_waitcnt lgkmcnt(0)
	v_lshlrev_b32_e32 v1, 16, v226
	v_mul_f32_e32 v0, v1, v0
	v_and_b32_e32 v1, 0xffff0000, v226
	v_and_b32_e32 v2, 0xffff0000, v34
	v_mul_f32_e32 v1, v1, v2
	v_cvt_pk_bf16_f32 v0, v0, v1
	v_lshlrev_b32_e32 v1, 16, v35
	v_lshlrev_b32_e32 v2, 16, v227
	v_mul_f32_e32 v1, v2, v1
	v_and_b32_e32 v2, 0xffff0000, v227
	v_and_b32_e32 v3, 0xffff0000, v35
	v_mul_f32_e32 v2, v2, v3
	v_cvt_pk_bf16_f32 v1, v1, v2
	v_lshlrev_b32_e32 v2, 16, v36
	v_lshlrev_b32_e32 v3, 16, v228
	v_mul_f32_e32 v2, v3, v2
	v_and_b32_e32 v3, 0xffff0000, v228
	v_and_b32_e32 v4, 0xffff0000, v36
	v_mul_f32_e32 v3, v3, v4
	v_cvt_pk_bf16_f32 v2, v2, v3
	v_lshlrev_b32_e32 v3, 16, v37
	v_lshlrev_b32_e32 v4, 16, v229
	v_mul_f32_e32 v3, v4, v3
	v_and_b32_e32 v4, 0xffff0000, v229
	v_and_b32_e32 v5, 0xffff0000, v37
	v_mul_f32_e32 v4, v4, v5
	v_cvt_pk_bf16_f32 v3, v3, v4
	global_store_dwordx4 v[52:53], v[0:3], off offset:128 nt
	s_waitcnt lgkmcnt(0)
	v_mov_b32_e32 v34, v32
	v_mov_b32_e32 v35, v32
	v_mov_b32_e32 v36, v32
	v_mov_b32_e32 v37, v32
	v_mov_b32_e32 v40, v32
	v_mov_b32_e32 v41, v32
	v_mov_b32_e32 v44, v32
	v_mov_b32_e32 v45, v32
	v_mov_b64_e32 v[78:79], v[46:47]
	v_mov_b64_e32 v[62:63], v[46:47]
	v_mov_b64_e32 v[16:17], v[32:33]
	v_mov_b64_e32 v[0:1], v[32:33]
	v_mov_b64_e32 v[76:77], v[44:45]
	v_mov_b64_e32 v[74:75], v[42:43]
	v_mov_b64_e32 v[72:73], v[40:41]
	v_mov_b64_e32 v[70:71], v[38:39]
	v_mov_b64_e32 v[68:69], v[36:37]
	v_mov_b64_e32 v[66:67], v[34:35]
	v_mov_b64_e32 v[64:65], v[32:33]
	v_mov_b64_e32 v[60:61], v[44:45]
	v_mov_b64_e32 v[58:59], v[42:43]
	v_mov_b64_e32 v[56:57], v[40:41]
	v_mov_b64_e32 v[54:55], v[38:39]
	v_mov_b64_e32 v[52:53], v[36:37]
	v_mov_b64_e32 v[50:51], v[34:35]
	v_mov_b64_e32 v[48:49], v[32:33]
	v_mov_b64_e32 v[18:19], v[34:35]
	v_mov_b64_e32 v[20:21], v[36:37]
	v_mov_b64_e32 v[22:23], v[38:39]
	v_mov_b64_e32 v[24:25], v[40:41]
	v_mov_b64_e32 v[26:27], v[42:43]
	v_mov_b64_e32 v[28:29], v[44:45]
	v_mov_b64_e32 v[30:31], v[46:47]
	v_mov_b64_e32 v[2:3], v[34:35]
	v_mov_b64_e32 v[4:5], v[36:37]
	v_mov_b64_e32 v[6:7], v[38:39]
	v_mov_b64_e32 v[8:9], v[40:41]
	v_mov_b64_e32 v[10:11], v[42:43]
	v_mov_b64_e32 v[12:13], v[44:45]
	v_mov_b64_e32 v[14:15], v[46:47]

; #define SBAR() __builtin_amdgcn_sched_barrier(0)
; __device__ __forceinline__ void pv_d0(f32x16* o, int vb, bf16x8 pa0, bf16x8 pa1, bf16x8 pa2, bf16x8 pa3) {
;   VFrag fa, fb;
;   v_read8<0>(fa, vb); v_read8<1>(fb, vb);
;   asm volatile("s_waitcnt lgkmcnt(8)" ::: "memory"); SBAR(); pv_mma(o[0], fa, pa0, pa1, pa2, pa3); SBAR();
;   v_read8<2>(fa, vb);
;   asm volatile("s_waitcnt lgkmcnt(8)" ::: "memory"); SBAR(); pv_mma(o[1], fb, pa0, pa1, pa2, pa3); SBAR();
;   v_read8<3>(fb, vb);
;   asm volatile("s_waitcnt lgkmcnt(8)" ::: "memory"); SBAR(); pv_mma(o[2], fa, pa0, pa1, pa2, pa3); SBAR();
;   asm volatile("s_waitcnt lgkmcnt(0)" ::: "memory"); SBAR(); pv_mma(o[3], fb, pa0, pa1, pa2, pa3); SBAR();
; }
; __device__ __forceinline__ void attn_phase(const bf16_t* __restrict__ Q, const bf16_t* __restrict__ KN, const bf16_t* __restrict__ KR, const bf16_t* __restrict__ V, ...
;     ...
;     EPI_PREFETCH(vcu + (nun_wg - 1) * G);
;     pv_d0(o, vb0 + pslot * SLOT_V, pa0, pa1, pa2, pa3);
.LBB0_1158:
	s_add_i32 s3, s47, -1
	s_mul_i32 s3, s3, s63
	s_add_i32 s3, s3, s46
	s_lshl_b32 s6, s3, 4
	s_lshl_b32 s3, s3, 8
	s_and_b32 s7, s6, 0xfffff800
	s_and_b32 s3, s3, 0x700
	s_or_b32 s3, s7, s3
	v_add_u32_e32 v32, s3, v210
	v_ashrrev_i32_e32 v33, 31, v32
	s_waitcnt vmcnt(0)
	v_lshlrev_b64 v[112:113], 11, v[32:33]
	s_and_b32 s3, s6, 0x780
	v_or_b32_e32 v32, s3, v112
	v_or_b32_e32 v112, v32, v184
	v_lshl_add_u64 v[32:33], v[112:113], 1, s[14:15]
	s_mov_b32 s9, 0x8000
	v_add_co_u32_e32 v34, vcc, s9, v32
	s_mov_b32 s8, 0x10000
	s_nop 0
	v_addc_co_u32_e32 v35, vcc, 0, v33, vcc
	v_add_co_u32_e32 v36, vcc, s8, v32
	s_mov_b32 s3, 0x18000
	s_nop 0
	v_addc_co_u32_e32 v37, vcc, 0, v33, vcc
	v_add_co_u32_e32 v114, vcc, s3, v32
	v_lshl_add_u32 v146, s72, 14, v209
	s_nop 0
	v_addc_co_u32_e32 v115, vcc, 0, v33, vcc
	global_load_dwordx4 v[108:111], v[32:33], off nt
	global_load_dwordx4 v[44:47], v[32:33], off offset:128 nt
	global_load_dwordx4 v[104:107], v[34:35], off nt
	global_load_dwordx4 v[40:43], v[34:35], off offset:128 nt
	global_load_dwordx4 v[100:103], v[36:37], off nt
	s_nop 0
	global_load_dwordx4 v[36:39], v[36:37], off offset:128 nt
	s_nop 0
	global_load_dwordx4 v[80:83], v[114:115], off nt
	global_load_dwordx4 v[32:35], v[114:115], off offset:128 nt
	ds_read_b64_tr_b16 v[114:115], v146 offset:0
	ds_read_b64_tr_b16 v[116:117], v146 offset:0x800
	ds_read_b64_tr_b16 v[118:119], v146 offset:0x1000
	ds_read_b64_tr_b16 v[120:121], v146 offset:0x1800
	ds_read_b64_tr_b16 v[122:123], v146 offset:0x2000
	ds_read_b64_tr_b16 v[124:125], v146 offset:0x2800
	ds_read_b64_tr_b16 v[126:127], v146 offset:0x3000
	ds_read_b64_tr_b16 v[128:129], v146 offset:0x3800
	ds_read_b64_tr_b16 v[130:131], v146 offset:0x200
	ds_read_b64_tr_b16 v[132:133], v146 offset:0xa00
	ds_read_b64_tr_b16 v[134:135], v146 offset:0x1200
	ds_read_b64_tr_b16 v[136:137], v146 offset:0x1a00
	ds_read_b64_tr_b16 v[138:139], v146 offset:0x2200
	ds_read_b64_tr_b16 v[140:141], v146 offset:0x2a00
	ds_read_b64_tr_b16 v[142:143], v146 offset:0x3200
	ds_read_b64_tr_b16 v[144:145], v146 offset:0x3a00
	s_waitcnt lgkmcnt(8)
	s_nop 0
	v_mfma_f32_32x32x16_bf16 v[64:79], v[96:99], v[114:117], v[64:79]
	v_mfma_f32_32x32x16_bf16 v[64:79], v[92:95], v[118:121], v[64:79]
	v_mfma_f32_32x32x16_bf16 v[64:79], v[88:91], v[122:125], v[64:79]
	v_mfma_f32_32x32x16_bf16 v[64:79], v[84:87], v[126:129], v[64:79]
	ds_read_b64_tr_b16 v[114:115], v146 offset:0x400
	ds_read_b64_tr_b16 v[116:117], v146 offset:0xc00
	ds_read_b64_tr_b16 v[118:119], v146 offset:0x1400
	ds_read_b64_tr_b16 v[120:121], v146 offset:0x1c00
	ds_read_b64_tr_b16 v[122:123], v146 offset:0x2400
	ds_read_b64_tr_b16 v[124:125], v146 offset:0x2c00
	ds_read_b64_tr_b16 v[126:127], v146 offset:0x3400
	ds_read_b64_tr_b16 v[128:129], v146 offset:0x3c00
	s_waitcnt lgkmcnt(8)
	v_mfma_f32_32x32x16_bf16 v[48:63], v[96:99], v[130:133], v[48:63]
	v_mfma_f32_32x32x16_bf16 v[48:63], v[92:95], v[134:137], v[48:63]
	v_mfma_f32_32x32x16_bf16 v[48:63], v[88:91], v[138:141], v[48:63]
	v_mfma_f32_32x32x16_bf16 v[48:63], v[84:87], v[142:145], v[48:63]
	ds_read_b64_tr_b16 v[130:131], v146 offset:0x600
	ds_read_b64_tr_b16 v[132:133], v146 offset:0xe00
	ds_read_b64_tr_b16 v[134:135], v146 offset:0x1600
	ds_read_b64_tr_b16 v[136:137], v146 offset:0x1e00
	ds_read_b64_tr_b16 v[138:139], v146 offset:0x2600
	ds_read_b64_tr_b16 v[140:141], v146 offset:0x2e00
	ds_read_b64_tr_b16 v[142:143], v146 offset:0x3600
	ds_read_b64_tr_b16 v[144:145], v146 offset:0x3e00
	s_waitcnt lgkmcnt(8)
	v_mfma_f32_32x32x16_bf16 v[16:31], v[96:99], v[114:117], v[16:31]
	v_mfma_f32_32x32x16_bf16 v[16:31], v[92:95], v[118:121], v[16:31]
	v_mfma_f32_32x32x16_bf16 v[16:31], v[88:91], v[122:125], v[16:31]
	v_mfma_f32_32x32x16_bf16 v[16:31], v[84:87], v[126:129], v[16:31]
	s_waitcnt lgkmcnt(0)
	v_mfma_f32_32x32x16_bf16 v[0:15], v[96:99], v[130:133], v[0:15]
	v_mfma_f32_32x32x16_bf16 v[0:15], v[92:95], v[134:137], v[0:15]
	v_mfma_f32_32x32x16_bf16 v[0:15], v[88:91], v[138:141], v[0:15]
	v_mfma_f32_32x32x16_bf16 v[0:15], v[84:87], v[142:145], v[0:15]
	s_and_saveexec_b64 s[6:7], s[0:1]
	ds_write_b32 v208, v187
	s_or_b64 exec, exec, s[6:7]
	s_waitcnt lgkmcnt(0)
	ds_read_b32 v230, v185
	ds_read_b32 v231, v185 offset:4
	ds_read_b32 v232, v185 offset:8
	ds_read_b32 v233, v185 offset:12
	ds_read_b32 v234, v185 offset:32
	ds_read_b32 v235, v185 offset:36
	ds_read_b32 v236, v185 offset:40
	ds_read_b32 v237, v185 offset:44
	ds_read_b32 v238, v185 offset:64
	ds_read_b32 v239, v185 offset:68
	ds_read_b32 v240, v185 offset:72
	ds_read_b32 v241, v185 offset:76
	ds_read_b32 v242, v185 offset:96
	ds_read_b32 v243, v185 offset:100
	ds_read_b32 v244, v185 offset:104
	ds_read_b32 v245, v185 offset:108
	s_waitcnt lgkmcnt(0)
	v_rcp_f32_e32 v230, v230
	v_rcp_f32_e32 v231, v231
	v_rcp_f32_e32 v232, v232
	v_rcp_f32_e32 v233, v233
	v_rcp_f32_e32 v234, v234
	v_rcp_f32_e32 v235, v235
	v_rcp_f32_e32 v236, v236
	v_rcp_f32_e32 v237, v237
	v_rcp_f32_e32 v238, v238
	v_rcp_f32_e32 v239, v239
	v_rcp_f32_e32 v240, v240
	v_rcp_f32_e32 v241, v241
	v_rcp_f32_e32 v242, v242
	v_rcp_f32_e32 v243, v243
	v_rcp_f32_e32 v244, v244
	v_rcp_f32_e32 v245, v245
	s_nop 0
	v_add_u32_e32 v86, v190, v207
	v_add_u32_e32 v87, v188, v189
	v_readlane_b32 s68, v247, 34
	v_readlane_b32 s82, v247, 48
	v_mov_b32_e32 v84, 0
	v_readlane_b32 s83, v247, 49
	v_readlane_b32 s69, v247, 35
	v_mul_f32_e32 v64, v64, v230
	v_mul_f32_e32 v48, v48, v230
	v_cvt_pk_bf16_f32 v64, v64, v84
	ds_write_b16 v86, v64
	v_cvt_pk_bf16_f32 v48, v48, v84
	ds_write_b16 v86, v48 offset:64
	v_add_u32_e32 v85, v190, v206
	v_readlane_b32 s70, v247, 36
	v_readlane_b32 s71, v247, 37
	v_readlane_b32 s72, v247, 38
	v_readlane_b32 s73, v247, 39
	v_readlane_b32 s74, v247, 40
	v_mul_f32_e32 v48, v65, v231
	v_mul_f32_e32 v49, v49, v231
	v_cvt_pk_bf16_f32 v48, v48, v84
	ds_write_b16 v85, v48
	v_cvt_pk_bf16_f32 v48, v49, v84
	ds_write_b16 v85, v48 offset:64
	v_add_u32_e32 v64, v190, v205
	v_add_u32_e32 v65, v190, v204
	v_readlane_b32 s75, v247, 41
	v_readlane_b32 s76, v247, 42
	v_readlane_b32 s77, v247, 43
	v_readlane_b32 s78, v247, 44
	v_mul_f32_e32 v48, v66, v232
	v_mul_f32_e32 v49, v50, v232
	v_cvt_pk_bf16_f32 v48, v48, v84
	ds_write_b16 v64, v48
	v_cvt_pk_bf16_f32 v48, v49, v84
	ds_write_b16 v64, v48 offset:64
	v_add_u32_e32 v66, v190, v203
	v_readlane_b32 s79, v247, 45
	v_readlane_b32 s80, v247, 46
	v_readlane_b32 s81, v247, 47
	v_mul_f32_e32 v48, v67, v233
	v_mul_f32_e32 v49, v51, v233
	v_cvt_pk_bf16_f32 v48, v48, v84
	ds_write_b16 v65, v48
	v_cvt_pk_bf16_f32 v48, v49, v84
	ds_write_b16 v65, v48 offset:64
	v_add_u32_e32 v67, v190, v202
	s_nop 0
	v_mul_f32_e32 v48, v68, v234
	v_mul_f32_e32 v49, v52, v234
	v_cvt_pk_bf16_f32 v48, v48, v84
	ds_write_b16 v66, v48
	v_cvt_pk_bf16_f32 v48, v49, v84
	ds_write_b16 v66, v48 offset:64
	v_add_u32_e32 v68, v190, v201
	s_nop 0
	v_mul_f32_e32 v48, v69, v235
	v_mul_f32_e32 v49, v53, v235
	v_cvt_pk_bf16_f32 v48, v48, v84
	ds_write_b16 v67, v48
	v_cvt_pk_bf16_f32 v48, v49, v84
	ds_write_b16 v67, v48 offset:64
	v_add_u32_e32 v69, v190, v200
	s_nop 0
	v_mul_f32_e32 v48, v70, v236
	v_mul_f32_e32 v49, v54, v236
	v_cvt_pk_bf16_f32 v48, v48, v84
	ds_write_b16 v68, v48
	v_cvt_pk_bf16_f32 v48, v49, v84
	ds_write_b16 v68, v48 offset:64
	v_add_u32_e32 v70, v190, v199
	s_waitcnt vmcnt(7)
	v_lshlrev_b32_e32 v54, 16, v108
	s_nop 0
	v_mul_f32_e32 v48, v71, v237
	v_mul_f32_e32 v49, v55, v237
	v_cvt_pk_bf16_f32 v48, v48, v84
	ds_write_b16 v69, v48
	v_cvt_pk_bf16_f32 v48, v49, v84
	ds_write_b16 v69, v48 offset:64
	v_add_u32_e32 v71, v190, v197
	v_and_b32_e32 v55, 0xffff0000, v108
	s_nop 0
	v_mul_f32_e32 v48, v72, v238
	v_mul_f32_e32 v49, v56, v238
	v_cvt_pk_bf16_f32 v48, v48, v84
	ds_write_b16 v70, v48
	v_cvt_pk_bf16_f32 v48, v49, v84
	ds_write_b16 v70, v48 offset:64
	v_add_u32_e32 v72, v190, v196
	v_lshlrev_b32_e32 v56, 16, v109
	s_nop 0
	v_mul_f32_e32 v48, v73, v239
	v_mul_f32_e32 v49, v57, v239
	v_cvt_pk_bf16_f32 v48, v48, v84
	ds_write_b16 v71, v48
	v_cvt_pk_bf16_f32 v48, v49, v84
	ds_write_b16 v71, v48 offset:64
	v_add_u32_e32 v73, v190, v195
	v_and_b32_e32 v57, 0xffff0000, v109
	s_nop 0
	v_mul_f32_e32 v48, v74, v240
	v_mul_f32_e32 v49, v58, v240
	v_cvt_pk_bf16_f32 v48, v48, v84
	ds_write_b16 v72, v48
	v_cvt_pk_bf16_f32 v48, v49, v84
	ds_write_b16 v72, v48 offset:64
	v_add_u32_e32 v74, v190, v194
	v_lshlrev_b32_e32 v58, 16, v110
	s_nop 0
	v_mul_f32_e32 v48, v75, v241
	v_mul_f32_e32 v49, v59, v241
	v_cvt_pk_bf16_f32 v48, v48, v84
	ds_write_b16 v73, v48
	v_cvt_pk_bf16_f32 v48, v49, v84
	ds_write_b16 v73, v48 offset:64
	v_add_u32_e32 v75, v190, v193
	v_and_b32_e32 v59, 0xffff0000, v110
	s_nop 0
	v_mul_f32_e32 v48, v76, v242
	v_mul_f32_e32 v49, v60, v242
	v_cvt_pk_bf16_f32 v48, v48, v84
	ds_write_b16 v74, v48
	v_cvt_pk_bf16_f32 v48, v49, v84
	ds_write_b16 v74, v48 offset:64
	v_add_u32_e32 v76, v190, v192
	v_lshlrev_b32_e32 v60, 16, v111
	s_nop 0
	v_mul_f32_e32 v48, v77, v243
	v_mul_f32_e32 v49, v61, v243
	v_cvt_pk_bf16_f32 v48, v48, v84
	ds_write_b16 v75, v48
	v_cvt_pk_bf16_f32 v50, v49, v84
	ds_write_b16 v75, v50 offset:64
	v_add_u32_e32 v77, v190, v191
	v_and_b32_e32 v61, 0xffff0000, v111
	v_lshl_add_u64 v[48:49], v[112:113], 1, s[18:19]
	s_nop 0
	v_mul_f32_e32 v50, v78, v244
	v_mul_f32_e32 v51, v62, v244
	v_cvt_pk_bf16_f32 v50, v50, v84
	ds_write_b16 v76, v50
	v_cvt_pk_bf16_f32 v50, v51, v84
	ds_write_b16 v76, v50 offset:64
	s_waitcnt vmcnt(5)
	v_lshlrev_b32_e32 v62, 16, v104
	s_nop 0
	v_mul_f32_e32 v50, v79, v245
	v_cvt_pk_bf16_f32 v50, v50, v84
	v_mul_f32_e32 v51, v63, v245
	ds_write_b16 v77, v50
	v_cvt_pk_bf16_f32 v50, v51, v84
	ds_write_b16 v77, v50 offset:64
	s_waitcnt lgkmcnt(0)
	ds_read_b128 v[214:217], v87
	ds_read_b128 v[218:221], v87 offset:1024
	ds_read_b128 v[222:225], v87 offset:2048
	ds_read_b128 v[226:229], v87 offset:3072
	v_and_b32_e32 v63, 0xffff0000, v104
	s_waitcnt lgkmcnt(0)
	v_lshlrev_b32_e32 v78, 16, v214
	v_and_b32_e32 v50, 0xffff0000, v214
	v_lshlrev_b32_e32 v79, 16, v215
	v_and_b32_e32 v51, 0xffff0000, v215
	v_lshlrev_b32_e32 v88, 16, v216
	v_and_b32_e32 v52, 0xffff0000, v216
	v_lshlrev_b32_e32 v89, 16, v217
	v_and_b32_e32 v53, 0xffff0000, v217
	v_mul_f32_e32 v54, v78, v54
	v_mul_f32_e32 v50, v50, v55
	v_mul_f32_e32 v55, v79, v56
	v_mul_f32_e32 v51, v51, v57
	v_mul_f32_e32 v56, v88, v58
	v_mul_f32_e32 v52, v52, v59
	v_mul_f32_e32 v57, v89, v60
	v_mul_f32_e32 v53, v53, v61
	v_cvt_pk_bf16_f32 v50, v54, v50
	v_cvt_pk_bf16_f32 v51, v55, v51
	v_cvt_pk_bf16_f32 v52, v56, v52
	v_cvt_pk_bf16_f32 v53, v57, v53
	v_lshlrev_b32_e32 v58, 16, v105
	v_and_b32_e32 v59, 0xffff0000, v105
	global_store_dwordx4 v[48:49], v[50:53], off nt
	v_lshlrev_b32_e32 v60, 16, v106
	s_waitcnt lgkmcnt(0)
	v_lshlrev_b32_e32 v50, 16, v218
	v_and_b32_e32 v51, 0xffff0000, v218
	v_lshlrev_b32_e32 v52, 16, v219
	v_and_b32_e32 v53, 0xffff0000, v219
	v_mul_f32_e32 v50, v50, v62
	v_mul_f32_e32 v51, v51, v63
	v_mul_f32_e32 v54, v52, v58
	v_mul_f32_e32 v53, v53, v59
	v_cvt_pk_bf16_f32 v52, v50, v51
	v_cvt_pk_bf16_f32 v53, v54, v53
	v_lshlrev_b32_e32 v50, 16, v220
	v_and_b32_e32 v51, 0xffff0000, v220
	v_and_b32_e32 v54, 0xffff0000, v106
	v_mul_f32_e32 v50, v50, v60
	v_mul_f32_e32 v51, v51, v54
	v_cvt_pk_bf16_f32 v54, v50, v51
	v_lshlrev_b32_e32 v50, 16, v107
	v_lshlrev_b32_e32 v51, 16, v221
	v_mul_f32_e32 v50, v51, v50
	v_and_b32_e32 v51, 0xffff0000, v221
	v_and_b32_e32 v55, 0xffff0000, v107
	v_mul_f32_e32 v51, v51, v55
	v_cvt_pk_bf16_f32 v55, v50, v51
	v_add_co_u32_e32 v50, vcc, s9, v48
	s_nop 1
	v_addc_co_u32_e32 v51, vcc, 0, v49, vcc
	global_store_dwordx4 v[50:51], v[52:55], off nt
	s_waitcnt vmcnt(5)
	s_nop 0
	v_lshlrev_b32_e32 v52, 16, v100
	s_waitcnt lgkmcnt(0)
	v_lshlrev_b32_e32 v53, 16, v222
	v_mul_f32_e32 v52, v53, v52
	v_and_b32_e32 v53, 0xffff0000, v222
	v_and_b32_e32 v54, 0xffff0000, v100
	v_mul_f32_e32 v53, v53, v54
	v_cvt_pk_bf16_f32 v54, v52, v53
	v_lshlrev_b32_e32 v52, 16, v101
	v_lshlrev_b32_e32 v53, 16, v223
	v_mul_f32_e32 v52, v53, v52
	v_and_b32_e32 v53, 0xffff0000, v223
	v_and_b32_e32 v55, 0xffff0000, v101
	v_mul_f32_e32 v53, v53, v55
	v_cvt_pk_bf16_f32 v55, v52, v53
	v_lshlrev_b32_e32 v52, 16, v102
	v_lshlrev_b32_e32 v53, 16, v224
	v_mul_f32_e32 v52, v53, v52
	v_and_b32_e32 v53, 0xffff0000, v224
	v_and_b32_e32 v56, 0xffff0000, v102
	v_mul_f32_e32 v53, v53, v56
	v_cvt_pk_bf16_f32 v56, v52, v53
	v_lshlrev_b32_e32 v52, 16, v103
	v_lshlrev_b32_e32 v53, 16, v225
	v_mul_f32_e32 v52, v53, v52
	v_and_b32_e32 v53, 0xffff0000, v225
	v_and_b32_e32 v57, 0xffff0000, v103
	v_mul_f32_e32 v53, v53, v57
	v_cvt_pk_bf16_f32 v57, v52, v53
	v_add_co_u32_e32 v52, vcc, s8, v48
	s_nop 1
	v_addc_co_u32_e32 v53, vcc, 0, v49, vcc
	global_store_dwordx4 v[52:53], v[54:57], off nt
	s_waitcnt vmcnt(4)
	s_nop 0
	v_lshlrev_b32_e32 v54, 16, v80
	s_waitcnt lgkmcnt(0)
	v_lshlrev_b32_e32 v55, 16, v226
	v_mul_f32_e32 v54, v55, v54
	v_and_b32_e32 v55, 0xffff0000, v226
	v_and_b32_e32 v56, 0xffff0000, v80
	v_mul_f32_e32 v55, v55, v56
	v_cvt_pk_bf16_f32 v56, v54, v55
	v_lshlrev_b32_e32 v54, 16, v81
	v_lshlrev_b32_e32 v55, 16, v227
	v_mul_f32_e32 v54, v55, v54
	v_and_b32_e32 v55, 0xffff0000, v227
	v_and_b32_e32 v57, 0xffff0000, v81
	v_mul_f32_e32 v55, v55, v57
	v_cvt_pk_bf16_f32 v57, v54, v55
	v_lshlrev_b32_e32 v54, 16, v82
	v_lshlrev_b32_e32 v55, 16, v228
	v_mul_f32_e32 v54, v55, v54
	v_and_b32_e32 v55, 0xffff0000, v228
	v_and_b32_e32 v58, 0xffff0000, v82
	v_mul_f32_e32 v55, v55, v58
	v_cvt_pk_bf16_f32 v58, v54, v55
	v_lshlrev_b32_e32 v54, 16, v83
	v_lshlrev_b32_e32 v55, 16, v229
	v_mul_f32_e32 v54, v55, v54
	v_and_b32_e32 v55, 0xffff0000, v229
	v_and_b32_e32 v59, 0xffff0000, v83
	v_mul_f32_e32 v55, v55, v59
	v_cvt_pk_bf16_f32 v59, v54, v55
	v_add_co_u32_e32 v54, vcc, s3, v48
	s_nop 1
	v_addc_co_u32_e32 v55, vcc, 0, v49, vcc
	global_store_dwordx4 v[54:55], v[56:59], off nt
	s_waitcnt lgkmcnt(0)
	s_and_b64 vcc, exec, s[4:5]
	s_nop 0
	v_mul_f32_e32 v16, v16, v230
	v_cvt_pk_bf16_f32 v16, v16, v84
	v_mul_f32_e32 v0, v0, v230
	ds_write_b16 v86, v16
	v_cvt_pk_bf16_f32 v0, v0, v84
	ds_write_b16 v86, v0 offset:64
	s_nop 0
	v_mul_f32_e32 v0, v17, v231
	v_cvt_pk_bf16_f32 v0, v0, v84
	ds_write_b16 v85, v0
	v_mul_f32_e32 v0, v1, v231
	v_cvt_pk_bf16_f32 v0, v0, v84
	ds_write_b16 v85, v0 offset:64
	s_nop 0
	v_mul_f32_e32 v0, v18, v232
	v_cvt_pk_bf16_f32 v0, v0, v84
	ds_write_b16 v64, v0
	v_mul_f32_e32 v0, v2, v232
	v_cvt_pk_bf16_f32 v0, v0, v84
	ds_write_b16 v64, v0 offset:64
	s_nop 0
	v_mul_f32_e32 v0, v19, v233
	v_cvt_pk_bf16_f32 v0, v0, v84
	ds_write_b16 v65, v0
	v_mul_f32_e32 v0, v3, v233
	v_cvt_pk_bf16_f32 v0, v0, v84
	ds_write_b16 v65, v0 offset:64
	s_nop 0
	v_mul_f32_e32 v0, v20, v234
	v_cvt_pk_bf16_f32 v0, v0, v84
	ds_write_b16 v66, v0
	v_mul_f32_e32 v0, v4, v234
	v_cvt_pk_bf16_f32 v0, v0, v84
	ds_write_b16 v66, v0 offset:64
	v_lshlrev_b32_e32 v4, 16, v44
	s_nop 0
	v_mul_f32_e32 v0, v21, v235
	v_cvt_pk_bf16_f32 v0, v0, v84
	ds_write_b16 v67, v0
	v_mul_f32_e32 v0, v5, v235
	v_cvt_pk_bf16_f32 v0, v0, v84
	ds_write_b16 v67, v0 offset:64
	s_nop 0
	v_mul_f32_e32 v0, v22, v236
	v_cvt_pk_bf16_f32 v0, v0, v84
	ds_write_b16 v68, v0
	v_mul_f32_e32 v0, v6, v236
	v_cvt_pk_bf16_f32 v0, v0, v84
	ds_write_b16 v68, v0 offset:64
	s_nop 0
	v_mul_f32_e32 v0, v23, v237
	v_cvt_pk_bf16_f32 v0, v0, v84
	ds_write_b16 v69, v0
	v_mul_f32_e32 v0, v7, v237
	v_cvt_pk_bf16_f32 v0, v0, v84
	ds_write_b16 v69, v0 offset:64
	s_nop 0
	v_mul_f32_e32 v0, v24, v238
	v_cvt_pk_bf16_f32 v0, v0, v84
	ds_write_b16 v70, v0
	v_mul_f32_e32 v0, v8, v238
	v_cvt_pk_bf16_f32 v0, v0, v84
	ds_write_b16 v70, v0 offset:64
	s_nop 0
	v_mul_f32_e32 v0, v25, v239
	v_cvt_pk_bf16_f32 v0, v0, v84
	ds_write_b16 v71, v0
	v_mul_f32_e32 v0, v9, v239
	v_cvt_pk_bf16_f32 v0, v0, v84
	ds_write_b16 v71, v0 offset:64
	s_nop 0
	v_mul_f32_e32 v0, v26, v240
	v_cvt_pk_bf16_f32 v0, v0, v84
	ds_write_b16 v72, v0
	v_mul_f32_e32 v0, v10, v240
	v_cvt_pk_bf16_f32 v0, v0, v84
	ds_write_b16 v72, v0 offset:64
	s_nop 0
	v_mul_f32_e32 v0, v27, v241
	v_cvt_pk_bf16_f32 v0, v0, v84
	ds_write_b16 v73, v0
	v_mul_f32_e32 v0, v11, v241
	v_cvt_pk_bf16_f32 v0, v0, v84
	ds_write_b16 v73, v0 offset:64
	s_nop 0
	v_mul_f32_e32 v0, v28, v242
	v_cvt_pk_bf16_f32 v0, v0, v84
	ds_write_b16 v74, v0
	v_mul_f32_e32 v0, v12, v242
	v_cvt_pk_bf16_f32 v0, v0, v84
	ds_write_b16 v74, v0 offset:64
	s_nop 0
	v_mul_f32_e32 v0, v29, v243
	v_cvt_pk_bf16_f32 v0, v0, v84
	ds_write_b16 v75, v0
	v_mul_f32_e32 v0, v13, v243
	v_cvt_pk_bf16_f32 v0, v0, v84
	ds_write_b16 v75, v0 offset:64
	s_nop 0
	v_mul_f32_e32 v0, v30, v244
	v_cvt_pk_bf16_f32 v0, v0, v84
	ds_write_b16 v76, v0
	v_mul_f32_e32 v0, v14, v244
	v_cvt_pk_bf16_f32 v0, v0, v84
	ds_write_b16 v76, v0 offset:64
	s_nop 0
	v_mul_f32_e32 v0, v31, v245
	v_cvt_pk_bf16_f32 v0, v0, v84
	ds_write_b16 v77, v0
	v_mul_f32_e32 v0, v15, v245
	v_cvt_pk_bf16_f32 v0, v0, v84
	ds_write_b16 v77, v0 offset:64
	s_waitcnt lgkmcnt(0)
; #define ABAR() do { asm volatile("s_waitcnt lgkmcnt(0)" ::: "memory"); __builtin_amdgcn_s_barrier(); asm volatile("" ::: "memory"); } while (0)
; __device__ __forceinline__ void attn_phase(const bf16_t* __restrict__ Q, const bf16_t* __restrict__ KN, const bf16_t* __restrict__ KR, const bf16_t* __restrict__ V, ...
;     ...
;     if (half == 0) ABAR();
	ds_read_b128 v[214:217], v87
	ds_read_b128 v[218:221], v87 offset:1024
	ds_read_b128 v[222:225], v87 offset:2048
	ds_read_b128 v[226:229], v87 offset:3072
	s_waitcnt lgkmcnt(0)
	v_lshlrev_b32_e32 v5, 16, v214
	v_mul_f32_e32 v4, v5, v4
	v_and_b32_e32 v0, 0xffff0000, v214
	v_and_b32_e32 v5, 0xffff0000, v44
	v_mul_f32_e32 v0, v0, v5
	v_cvt_pk_bf16_f32 v0, v4, v0
	v_lshlrev_b32_e32 v4, 16, v45
	v_lshlrev_b32_e32 v5, 16, v215
	v_mul_f32_e32 v4, v5, v4
	v_and_b32_e32 v1, 0xffff0000, v215
	v_and_b32_e32 v5, 0xffff0000, v45
	v_mul_f32_e32 v1, v1, v5
	v_cvt_pk_bf16_f32 v1, v4, v1
	v_lshlrev_b32_e32 v4, 16, v46
	v_lshlrev_b32_e32 v5, 16, v216
	v_mul_f32_e32 v4, v5, v4
	v_and_b32_e32 v2, 0xffff0000, v216
	v_and_b32_e32 v5, 0xffff0000, v46
	v_mul_f32_e32 v2, v2, v5
	v_cvt_pk_bf16_f32 v2, v4, v2
	v_lshlrev_b32_e32 v4, 16, v47
	v_lshlrev_b32_e32 v5, 16, v217
	v_mul_f32_e32 v4, v5, v4
	v_and_b32_e32 v3, 0xffff0000, v217
	v_and_b32_e32 v5, 0xffff0000, v47
	v_mul_f32_e32 v3, v3, v5
	v_cvt_pk_bf16_f32 v3, v4, v3
	global_store_dwordx4 v[48:49], v[0:3], off offset:128 nt
	s_nop 1
	v_lshlrev_b32_e32 v0, 16, v40
	s_waitcnt lgkmcnt(0)
	v_lshlrev_b32_e32 v1, 16, v218
	v_mul_f32_e32 v0, v1, v0
	v_and_b32_e32 v1, 0xffff0000, v218
	v_and_b32_e32 v2, 0xffff0000, v40
	v_mul_f32_e32 v1, v1, v2
	v_cvt_pk_bf16_f32 v0, v0, v1
	v_lshlrev_b32_e32 v1, 16, v41
	v_lshlrev_b32_e32 v2, 16, v219
	v_mul_f32_e32 v1, v2, v1
	v_and_b32_e32 v2, 0xffff0000, v219
	v_and_b32_e32 v3, 0xffff0000, v41
	v_mul_f32_e32 v2, v2, v3
	v_cvt_pk_bf16_f32 v1, v1, v2
	v_lshlrev_b32_e32 v2, 16, v42
	v_lshlrev_b32_e32 v3, 16, v220
	v_mul_f32_e32 v2, v3, v2
	v_and_b32_e32 v3, 0xffff0000, v220
	v_and_b32_e32 v4, 0xffff0000, v42
	v_mul_f32_e32 v3, v3, v4
	v_cvt_pk_bf16_f32 v2, v2, v3
	v_lshlrev_b32_e32 v3, 16, v43
	v_lshlrev_b32_e32 v4, 16, v221
	v_mul_f32_e32 v3, v4, v3
	v_and_b32_e32 v4, 0xffff0000, v221
	v_and_b32_e32 v5, 0xffff0000, v43
	v_mul_f32_e32 v4, v4, v5
	v_cvt_pk_bf16_f32 v3, v3, v4
	global_store_dwordx4 v[50:51], v[0:3], off offset:128 nt
	s_nop 1
	v_lshlrev_b32_e32 v0, 16, v36
	s_waitcnt lgkmcnt(0)
	v_lshlrev_b32_e32 v1, 16, v222
	v_mul_f32_e32 v0, v1, v0
	v_and_b32_e32 v1, 0xffff0000, v222
	v_and_b32_e32 v2, 0xffff0000, v36
	v_mul_f32_e32 v1, v1, v2
	v_cvt_pk_bf16_f32 v0, v0, v1
	v_lshlrev_b32_e32 v1, 16, v37
	v_lshlrev_b32_e32 v2, 16, v223
	v_mul_f32_e32 v1, v2, v1
	v_and_b32_e32 v2, 0xffff0000, v223
	v_and_b32_e32 v3, 0xffff0000, v37
	v_mul_f32_e32 v2, v2, v3
	v_cvt_pk_bf16_f32 v1, v1, v2
	v_lshlrev_b32_e32 v2, 16, v38
	v_lshlrev_b32_e32 v3, 16, v224
	v_mul_f32_e32 v2, v3, v2
	v_and_b32_e32 v3, 0xffff0000, v224
	v_and_b32_e32 v4, 0xffff0000, v38
	v_mul_f32_e32 v3, v3, v4
	v_cvt_pk_bf16_f32 v2, v2, v3
	v_lshlrev_b32_e32 v3, 16, v39
	v_lshlrev_b32_e32 v4, 16, v225
	v_mul_f32_e32 v3, v4, v3
	v_and_b32_e32 v4, 0xffff0000, v225
	v_and_b32_e32 v5, 0xffff0000, v39
	v_mul_f32_e32 v4, v4, v5
	v_cvt_pk_bf16_f32 v3, v3, v4
	global_store_dwordx4 v[52:53], v[0:3], off offset:128 nt
	s_waitcnt vmcnt(7)
	s_nop 0
	v_lshlrev_b32_e32 v0, 16, v32
	s_waitcnt lgkmcnt(0)
	v_lshlrev_b32_e32 v1, 16, v226
	v_mul_f32_e32 v0, v1, v0
	v_and_b32_e32 v1, 0xffff0000, v226
	v_and_b32_e32 v2, 0xffff0000, v32
	v_mul_f32_e32 v1, v1, v2
	v_cvt_pk_bf16_f32 v0, v0, v1
	v_lshlrev_b32_e32 v1, 16, v33
	v_lshlrev_b32_e32 v2, 16, v227
	v_mul_f32_e32 v1, v2, v1
	v_and_b32_e32 v2, 0xffff0000, v227
	v_and_b32_e32 v3, 0xffff0000, v33
	v_mul_f32_e32 v2, v2, v3
	v_cvt_pk_bf16_f32 v1, v1, v2
	v_lshlrev_b32_e32 v2, 16, v34
	v_lshlrev_b32_e32 v3, 16, v228
	v_mul_f32_e32 v2, v3, v2
	v_and_b32_e32 v3, 0xffff0000, v228
	v_and_b32_e32 v4, 0xffff0000, v34
	v_mul_f32_e32 v3, v3, v4
	v_cvt_pk_bf16_f32 v2, v2, v3
	v_lshlrev_b32_e32 v3, 16, v35
	v_lshlrev_b32_e32 v4, 16, v229
	v_mul_f32_e32 v3, v4, v3
	v_and_b32_e32 v4, 0xffff0000, v229
	v_and_b32_e32 v5, 0xffff0000, v35
	v_mul_f32_e32 v4, v4, v5
	v_cvt_pk_bf16_f32 v3, v3, v4
	global_store_dwordx4 v[54:55], v[0:3], off offset:128 nt
	s_waitcnt lgkmcnt(0)
	s_cbranch_vccnz .LBB0_1162
	s_waitcnt lgkmcnt(0)
	s_barrier
